# weight conversion: all 32 loads of an item in flight before one wait (instead of 8), rest as stack
# speedup vs baseline: 1.0042x; 1.0042x over previous
.LBB0_14:
	v_mov_b32_e32 v200, 0
	v_mov_b32_e32 v201, 0
	v_mov_b32_e32 v202, 0
	v_mov_b32_e32 v203, 0
	v_mov_b32_e32 v204, 0
	v_mov_b32_e32 v205, 0
	v_mov_b32_e32 v206, 0
	v_mov_b32_e32 v207, 0
	v_mov_b32_e32 v208, 0
	v_mov_b32_e32 v209, 0
	v_mov_b32_e32 v210, 0
	v_mov_b32_e32 v211, 0
	v_mov_b32_e32 v212, 0
	v_mov_b32_e32 v213, 0
	v_mov_b32_e32 v214, 0
	v_mov_b32_e32 v215, 0
	v_mov_b32_e32 v216, 0
	v_mov_b32_e32 v217, 0
	v_mov_b32_e32 v218, 0
	v_mov_b32_e32 v219, 0
	v_mov_b32_e32 v220, 0
	v_mov_b32_e32 v221, 0
	v_mov_b32_e32 v222, 0
	v_mov_b32_e32 v223, 0
	v_mov_b32_e32 v224, 0
	v_mov_b32_e32 v225, 0
	v_mov_b32_e32 v226, 0
	v_mov_b32_e32 v227, 0
	v_mov_b32_e32 v228, 0
	v_mov_b32_e32 v229, 0
	v_mov_b32_e32 v230, 0
	v_mov_b32_e32 v231, 0
	s_and_saveexec_b64 s[16:17], vcc
	s_cbranch_execz .Lcv0_0_16
	v_add_u32_e32 v12, s15, v2
	v_mad_i64_i32 v[12:13], s[22:23], v12, s19, v[6:7]
	global_load_dword v200, v[12:13], off nt

.Lcv0_0_end:
	s_or_b64 exec, exec, s[16:17]
	s_add_i32 s15, s15, 16
	s_and_saveexec_b64 s[16:17], vcc
	s_cbranch_execz .Lcv0_1_16
	v_add_u32_e32 v12, s15, v2
	v_mad_i64_i32 v[12:13], s[22:23], v12, s19, v[6:7]
	global_load_dword v208, v[12:13], off nt
.Lcv0_1_16:
	s_or_b64 exec, exec, s[16:17]
	s_and_saveexec_b64 s[16:17], vcc
	s_cbranch_execz .Lcv0_1_18
	v_add3_u32 v11, v2, s15, 2
	v_mad_i64_i32 v[12:13], s[22:23], v11, s19, v[6:7]
	global_load_dword v209, v[12:13], off nt
.Lcv0_1_18:
	s_or_b64 exec, exec, s[16:17]
	s_and_saveexec_b64 s[16:17], vcc
	s_cbranch_execz .Lcv0_1_20
	v_add3_u32 v12, v2, s15, 4
	v_mad_i64_i32 v[12:13], s[22:23], v12, s19, v[6:7]
	global_load_dword v210, v[12:13], off nt
.Lcv0_1_20:
	s_or_b64 exec, exec, s[16:17]
	s_and_saveexec_b64 s[16:17], vcc
	s_cbranch_execz .Lcv0_1_22
	v_add3_u32 v11, v2, s15, 6
	v_mad_i64_i32 v[12:13], s[22:23], v11, s19, v[6:7]
	global_load_dword v211, v[12:13], off nt
.Lcv0_1_22:
	s_or_b64 exec, exec, s[16:17]
	s_and_saveexec_b64 s[16:17], vcc
	s_cbranch_execz .Lcv0_1_24
	v_add3_u32 v12, v2, s15, 8
	v_mad_i64_i32 v[12:13], s[22:23], v12, s19, v[6:7]
	global_load_dword v212, v[12:13], off nt
.Lcv0_1_24:
	s_or_b64 exec, exec, s[16:17]
	s_and_saveexec_b64 s[16:17], vcc
	s_cbranch_execz .Lcv0_1_26
	v_add3_u32 v11, v2, s15, 10
	v_mad_i64_i32 v[12:13], s[22:23], v11, s19, v[6:7]
	global_load_dword v213, v[12:13], off nt
.Lcv0_1_26:
	s_or_b64 exec, exec, s[16:17]
	s_and_saveexec_b64 s[16:17], vcc
	s_cbranch_execz .Lcv0_1_28
	v_add3_u32 v12, v2, s15, 12
	v_mad_i64_i32 v[12:13], s[22:23], v12, s19, v[6:7]
	global_load_dword v214, v[12:13], off nt
.Lcv0_1_28:
	s_or_b64 exec, exec, s[16:17]
	s_and_saveexec_b64 s[16:17], vcc
	s_cbranch_execz .Lcv0_1_end
	v_add3_u32 v11, v2, s15, 14
	v_mad_i64_i32 v[12:13], s[22:23], v11, s19, v[6:7]
	global_load_dword v215, v[12:13], off nt
.Lcv0_1_end:
	s_or_b64 exec, exec, s[16:17]
	s_add_i32 s15, s15, 16
	s_and_saveexec_b64 s[16:17], vcc
	s_cbranch_execz .Lcv0_2_16
	v_add_u32_e32 v12, s15, v2
	v_mad_i64_i32 v[12:13], s[22:23], v12, s19, v[6:7]
	global_load_dword v216, v[12:13], off nt
.Lcv0_2_16:
	s_or_b64 exec, exec, s[16:17]
	s_and_saveexec_b64 s[16:17], vcc
	s_cbranch_execz .Lcv0_2_18
	v_add3_u32 v11, v2, s15, 2
	v_mad_i64_i32 v[12:13], s[22:23], v11, s19, v[6:7]
	global_load_dword v217, v[12:13], off nt
.Lcv0_2_18:
	s_or_b64 exec, exec, s[16:17]
	s_and_saveexec_b64 s[16:17], vcc
	s_cbranch_execz .Lcv0_2_20
	v_add3_u32 v12, v2, s15, 4
	v_mad_i64_i32 v[12:13], s[22:23], v12, s19, v[6:7]
	global_load_dword v218, v[12:13], off nt
.Lcv0_2_20:
	s_or_b64 exec, exec, s[16:17]
	s_and_saveexec_b64 s[16:17], vcc
	s_cbranch_execz .Lcv0_2_22
	v_add3_u32 v11, v2, s15, 6
	v_mad_i64_i32 v[12:13], s[22:23], v11, s19, v[6:7]
	global_load_dword v219, v[12:13], off nt
.Lcv0_2_22:
	s_or_b64 exec, exec, s[16:17]
	s_and_saveexec_b64 s[16:17], vcc
	s_cbranch_execz .Lcv0_2_24
	v_add3_u32 v12, v2, s15, 8
	v_mad_i64_i32 v[12:13], s[22:23], v12, s19, v[6:7]
	global_load_dword v220, v[12:13], off nt
.Lcv0_2_24:
	s_or_b64 exec, exec, s[16:17]
	s_and_saveexec_b64 s[16:17], vcc
	s_cbranch_execz .Lcv0_2_26
	v_add3_u32 v11, v2, s15, 10
	v_mad_i64_i32 v[12:13], s[22:23], v11, s19, v[6:7]
	global_load_dword v221, v[12:13], off nt
.Lcv0_2_26:
	s_or_b64 exec, exec, s[16:17]
	s_and_saveexec_b64 s[16:17], vcc
	s_cbranch_execz .Lcv0_2_28
	v_add3_u32 v12, v2, s15, 12
	v_mad_i64_i32 v[12:13], s[22:23], v12, s19, v[6:7]
	global_load_dword v222, v[12:13], off nt
.Lcv0_2_28:
	s_or_b64 exec, exec, s[16:17]
	s_and_saveexec_b64 s[16:17], vcc
	s_cbranch_execz .Lcv0_2_end
	v_add3_u32 v11, v2, s15, 14
	v_mad_i64_i32 v[12:13], s[22:23], v11, s19, v[6:7]
	global_load_dword v223, v[12:13], off nt
.Lcv0_2_end:
	s_or_b64 exec, exec, s[16:17]
	s_add_i32 s15, s15, 16
	s_and_saveexec_b64 s[16:17], vcc
	s_cbranch_execz .Lcv0_3_16
	v_add_u32_e32 v12, s15, v2
	v_mad_i64_i32 v[12:13], s[22:23], v12, s19, v[6:7]
	global_load_dword v224, v[12:13], off nt
.Lcv0_3_16:
	s_or_b64 exec, exec, s[16:17]
	s_and_saveexec_b64 s[16:17], vcc
	s_cbranch_execz .Lcv0_3_18
	v_add3_u32 v11, v2, s15, 2
	v_mad_i64_i32 v[12:13], s[22:23], v11, s19, v[6:7]
	global_load_dword v225, v[12:13], off nt
.Lcv0_3_18:
	s_or_b64 exec, exec, s[16:17]
	s_and_saveexec_b64 s[16:17], vcc
	s_cbranch_execz .Lcv0_3_20
	v_add3_u32 v12, v2, s15, 4
	v_mad_i64_i32 v[12:13], s[22:23], v12, s19, v[6:7]
	global_load_dword v226, v[12:13], off nt
.Lcv0_3_20:
	s_or_b64 exec, exec, s[16:17]
	s_and_saveexec_b64 s[16:17], vcc
	s_cbranch_execz .Lcv0_3_22
	v_add3_u32 v11, v2, s15, 6
	v_mad_i64_i32 v[12:13], s[22:23], v11, s19, v[6:7]
	global_load_dword v227, v[12:13], off nt
.Lcv0_3_22:
	s_or_b64 exec, exec, s[16:17]
	s_and_saveexec_b64 s[16:17], vcc
	s_cbranch_execz .Lcv0_3_24
	v_add3_u32 v12, v2, s15, 8
	v_mad_i64_i32 v[12:13], s[22:23], v12, s19, v[6:7]
	global_load_dword v228, v[12:13], off nt
.Lcv0_3_24:
	s_or_b64 exec, exec, s[16:17]
	s_and_saveexec_b64 s[16:17], vcc
	s_cbranch_execz .Lcv0_3_26
	v_add3_u32 v11, v2, s15, 10
	v_mad_i64_i32 v[12:13], s[22:23], v11, s19, v[6:7]
	global_load_dword v229, v[12:13], off nt
.Lcv0_3_26:
	s_or_b64 exec, exec, s[16:17]
	s_and_saveexec_b64 s[16:17], vcc
	s_cbranch_execz .Lcv0_3_28
	v_add3_u32 v12, v2, s15, 12
	v_mad_i64_i32 v[12:13], s[22:23], v12, s19, v[6:7]
	global_load_dword v230, v[12:13], off nt
.Lcv0_3_28:
	s_or_b64 exec, exec, s[16:17]
	s_and_saveexec_b64 s[16:17], vcc
	s_cbranch_execz .Lcv0_3_end
	v_add3_u32 v11, v2, s15, 14
	v_mad_i64_i32 v[12:13], s[22:23], v11, s19, v[6:7]
	global_load_dword v231, v[12:13], off nt
.Lcv0_3_end:
	s_or_b64 exec, exec, s[16:17]
	s_add_i32 s15, s15, 16
	s_waitcnt vmcnt(0)
	ds_write_b32 v10, v200
	ds_write_b32 v10, v201 offset:264
	ds_write_b32 v10, v202 offset:528
	ds_write_b32 v10, v203 offset:792
	ds_write_b32 v10, v204 offset:1056
	ds_write_b32 v10, v205 offset:1320
	ds_write_b32 v10, v206 offset:1584
	ds_write_b32 v10, v207 offset:1848
	ds_write_b32 v10, v208 offset:2112
	ds_write_b32 v10, v209 offset:2376
	ds_write_b32 v10, v210 offset:2640
	ds_write_b32 v10, v211 offset:2904
	ds_write_b32 v10, v212 offset:3168
	ds_write_b32 v10, v213 offset:3432
	ds_write_b32 v10, v214 offset:3696
	ds_write_b32 v10, v215 offset:3960
	ds_write_b32 v10, v216 offset:4224
	ds_write_b32 v10, v217 offset:4488
	ds_write_b32 v10, v218 offset:4752
	ds_write_b32 v10, v219 offset:5016
	ds_write_b32 v10, v220 offset:5280
	ds_write_b32 v10, v221 offset:5544
	ds_write_b32 v10, v222 offset:5808
	ds_write_b32 v10, v223 offset:6072
	ds_write_b32 v10, v224 offset:6336
	ds_write_b32 v10, v225 offset:6600
	ds_write_b32 v10, v226 offset:6864
	ds_write_b32 v10, v227 offset:7128
	ds_write_b32 v10, v228 offset:7392
	ds_write_b32 v10, v229 offset:7656
	ds_write_b32 v10, v230 offset:7920
	ds_write_b32 v10, v231 offset:8184
	s_branch .LBB0_5

.LBB0_35:
	v_mov_b32_e32 v200, 0
	v_mov_b32_e32 v201, 0
	v_mov_b32_e32 v202, 0
	v_mov_b32_e32 v203, 0
	v_mov_b32_e32 v204, 0
	v_mov_b32_e32 v205, 0
	v_mov_b32_e32 v206, 0
	v_mov_b32_e32 v207, 0
	v_mov_b32_e32 v208, 0
	v_mov_b32_e32 v209, 0
	v_mov_b32_e32 v210, 0
	v_mov_b32_e32 v211, 0
	v_mov_b32_e32 v212, 0
	v_mov_b32_e32 v213, 0
	v_mov_b32_e32 v214, 0
	v_mov_b32_e32 v215, 0
	v_mov_b32_e32 v216, 0
	v_mov_b32_e32 v217, 0
	v_mov_b32_e32 v218, 0
	v_mov_b32_e32 v219, 0
	v_mov_b32_e32 v220, 0
	v_mov_b32_e32 v221, 0
	v_mov_b32_e32 v222, 0
	v_mov_b32_e32 v223, 0
	v_mov_b32_e32 v224, 0
	v_mov_b32_e32 v225, 0
	v_mov_b32_e32 v226, 0
	v_mov_b32_e32 v227, 0
	v_mov_b32_e32 v228, 0
	v_mov_b32_e32 v229, 0
	v_mov_b32_e32 v230, 0
	v_mov_b32_e32 v231, 0
	s_and_saveexec_b64 s[16:17], vcc
	s_cbranch_execz .Lcv1_0_37
	v_add_u32_e32 v12, s15, v2
	v_ashrrev_i32_e32 v13, 31, v12
	v_lshlrev_b64 v[12:13], 12, v[12:13]
	v_lshl_add_u64 v[12:13], v[6:7], 0, v[12:13]
	global_load_dword v200, v[12:13], off nt

.Lcv1_0_end:
	s_or_b64 exec, exec, s[16:17]
	s_add_i32 s15, s15, 16
	s_and_saveexec_b64 s[16:17], vcc
	s_cbranch_execz .Lcv1_1_37
	v_add_u32_e32 v12, s15, v2
	v_ashrrev_i32_e32 v13, 31, v12
	v_lshlrev_b64 v[12:13], 12, v[12:13]
	v_lshl_add_u64 v[12:13], v[6:7], 0, v[12:13]
	global_load_dword v208, v[12:13], off nt
.Lcv1_1_37:
	s_or_b64 exec, exec, s[16:17]
	s_and_saveexec_b64 s[16:17], vcc
	s_cbranch_execz .Lcv1_1_39
	v_add3_u32 v12, v2, s15, 2
	v_ashrrev_i32_e32 v13, 31, v12
	v_lshlrev_b64 v[12:13], 12, v[12:13]
	v_lshl_add_u64 v[12:13], v[6:7], 0, v[12:13]
	global_load_dword v209, v[12:13], off nt
.Lcv1_1_39:
	s_or_b64 exec, exec, s[16:17]
	s_and_saveexec_b64 s[16:17], vcc
	s_cbranch_execz .Lcv1_1_41
	v_add3_u32 v12, v2, s15, 4
	v_ashrrev_i32_e32 v13, 31, v12
	v_lshlrev_b64 v[12:13], 12, v[12:13]
	v_lshl_add_u64 v[12:13], v[6:7], 0, v[12:13]
	global_load_dword v210, v[12:13], off nt
.Lcv1_1_41:
	s_or_b64 exec, exec, s[16:17]
	s_and_saveexec_b64 s[16:17], vcc
	s_cbranch_execz .Lcv1_1_43
	v_add3_u32 v12, v2, s15, 6
	v_ashrrev_i32_e32 v13, 31, v12
	v_lshlrev_b64 v[12:13], 12, v[12:13]
	v_lshl_add_u64 v[12:13], v[6:7], 0, v[12:13]
	global_load_dword v211, v[12:13], off nt
.Lcv1_1_43:
	s_or_b64 exec, exec, s[16:17]
	s_and_saveexec_b64 s[16:17], vcc
	s_cbranch_execz .Lcv1_1_45
	v_add3_u32 v12, v2, s15, 8
	v_ashrrev_i32_e32 v13, 31, v12
	v_lshlrev_b64 v[12:13], 12, v[12:13]
	v_lshl_add_u64 v[12:13], v[6:7], 0, v[12:13]
	global_load_dword v212, v[12:13], off nt
.Lcv1_1_45:
	s_or_b64 exec, exec, s[16:17]
	s_and_saveexec_b64 s[16:17], vcc
	s_cbranch_execz .Lcv1_1_47
	v_add3_u32 v12, v2, s15, 10
	v_ashrrev_i32_e32 v13, 31, v12
	v_lshlrev_b64 v[12:13], 12, v[12:13]
	v_lshl_add_u64 v[12:13], v[6:7], 0, v[12:13]
	global_load_dword v213, v[12:13], off nt
.Lcv1_1_47:
	s_or_b64 exec, exec, s[16:17]
	s_and_saveexec_b64 s[16:17], vcc
	s_cbranch_execz .Lcv1_1_49
	v_add3_u32 v12, v2, s15, 12
	v_ashrrev_i32_e32 v13, 31, v12
	v_lshlrev_b64 v[12:13], 12, v[12:13]
	v_lshl_add_u64 v[12:13], v[6:7], 0, v[12:13]
	global_load_dword v214, v[12:13], off nt
.Lcv1_1_49:
	s_or_b64 exec, exec, s[16:17]
	s_and_saveexec_b64 s[16:17], vcc
	s_cbranch_execz .Lcv1_1_end
	v_add3_u32 v12, v2, s15, 14
	v_ashrrev_i32_e32 v13, 31, v12
	v_lshlrev_b64 v[12:13], 12, v[12:13]
	v_lshl_add_u64 v[12:13], v[6:7], 0, v[12:13]
	global_load_dword v215, v[12:13], off nt
.Lcv1_1_end:
	s_or_b64 exec, exec, s[16:17]
	s_add_i32 s15, s15, 16
	s_and_saveexec_b64 s[16:17], vcc
	s_cbranch_execz .Lcv1_2_37
	v_add_u32_e32 v12, s15, v2
	v_ashrrev_i32_e32 v13, 31, v12
	v_lshlrev_b64 v[12:13], 12, v[12:13]
	v_lshl_add_u64 v[12:13], v[6:7], 0, v[12:13]
	global_load_dword v216, v[12:13], off nt
.Lcv1_2_37:
	s_or_b64 exec, exec, s[16:17]
	s_and_saveexec_b64 s[16:17], vcc
	s_cbranch_execz .Lcv1_2_39
	v_add3_u32 v12, v2, s15, 2
	v_ashrrev_i32_e32 v13, 31, v12
	v_lshlrev_b64 v[12:13], 12, v[12:13]
	v_lshl_add_u64 v[12:13], v[6:7], 0, v[12:13]
	global_load_dword v217, v[12:13], off nt
.Lcv1_2_39:
	s_or_b64 exec, exec, s[16:17]
	s_and_saveexec_b64 s[16:17], vcc
	s_cbranch_execz .Lcv1_2_41
	v_add3_u32 v12, v2, s15, 4
	v_ashrrev_i32_e32 v13, 31, v12
	v_lshlrev_b64 v[12:13], 12, v[12:13]
	v_lshl_add_u64 v[12:13], v[6:7], 0, v[12:13]
	global_load_dword v218, v[12:13], off nt
.Lcv1_2_41:
	s_or_b64 exec, exec, s[16:17]
	s_and_saveexec_b64 s[16:17], vcc
	s_cbranch_execz .Lcv1_2_43
	v_add3_u32 v12, v2, s15, 6
	v_ashrrev_i32_e32 v13, 31, v12
	v_lshlrev_b64 v[12:13], 12, v[12:13]
	v_lshl_add_u64 v[12:13], v[6:7], 0, v[12:13]
	global_load_dword v219, v[12:13], off nt
.Lcv1_2_43:
	s_or_b64 exec, exec, s[16:17]
	s_and_saveexec_b64 s[16:17], vcc
	s_cbranch_execz .Lcv1_2_45
	v_add3_u32 v12, v2, s15, 8
	v_ashrrev_i32_e32 v13, 31, v12
	v_lshlrev_b64 v[12:13], 12, v[12:13]
	v_lshl_add_u64 v[12:13], v[6:7], 0, v[12:13]
	global_load_dword v220, v[12:13], off nt
.Lcv1_2_45:
	s_or_b64 exec, exec, s[16:17]
	s_and_saveexec_b64 s[16:17], vcc
	s_cbranch_execz .Lcv1_2_47
	v_add3_u32 v12, v2, s15, 10
	v_ashrrev_i32_e32 v13, 31, v12
	v_lshlrev_b64 v[12:13], 12, v[12:13]
	v_lshl_add_u64 v[12:13], v[6:7], 0, v[12:13]
	global_load_dword v221, v[12:13], off nt
.Lcv1_2_47:
	s_or_b64 exec, exec, s[16:17]
	s_and_saveexec_b64 s[16:17], vcc
	s_cbranch_execz .Lcv1_2_49
	v_add3_u32 v12, v2, s15, 12
	v_ashrrev_i32_e32 v13, 31, v12
	v_lshlrev_b64 v[12:13], 12, v[12:13]
	v_lshl_add_u64 v[12:13], v[6:7], 0, v[12:13]
	global_load_dword v222, v[12:13], off nt
.Lcv1_2_49:
	s_or_b64 exec, exec, s[16:17]
	s_and_saveexec_b64 s[16:17], vcc
	s_cbranch_execz .Lcv1_2_end
	v_add3_u32 v12, v2, s15, 14
	v_ashrrev_i32_e32 v13, 31, v12
	v_lshlrev_b64 v[12:13], 12, v[12:13]
	v_lshl_add_u64 v[12:13], v[6:7], 0, v[12:13]
	global_load_dword v223, v[12:13], off nt
.Lcv1_2_end:
	s_or_b64 exec, exec, s[16:17]
	s_add_i32 s15, s15, 16
	s_and_saveexec_b64 s[16:17], vcc
	s_cbranch_execz .Lcv1_3_37
	v_add_u32_e32 v12, s15, v2
	v_ashrrev_i32_e32 v13, 31, v12
	v_lshlrev_b64 v[12:13], 12, v[12:13]
	v_lshl_add_u64 v[12:13], v[6:7], 0, v[12:13]
	global_load_dword v224, v[12:13], off nt
.Lcv1_3_37:
	s_or_b64 exec, exec, s[16:17]
	s_and_saveexec_b64 s[16:17], vcc
	s_cbranch_execz .Lcv1_3_39
	v_add3_u32 v12, v2, s15, 2
	v_ashrrev_i32_e32 v13, 31, v12
	v_lshlrev_b64 v[12:13], 12, v[12:13]
	v_lshl_add_u64 v[12:13], v[6:7], 0, v[12:13]
	global_load_dword v225, v[12:13], off nt
.Lcv1_3_39:
	s_or_b64 exec, exec, s[16:17]
	s_and_saveexec_b64 s[16:17], vcc
	s_cbranch_execz .Lcv1_3_41
	v_add3_u32 v12, v2, s15, 4
	v_ashrrev_i32_e32 v13, 31, v12
	v_lshlrev_b64 v[12:13], 12, v[12:13]
	v_lshl_add_u64 v[12:13], v[6:7], 0, v[12:13]
	global_load_dword v226, v[12:13], off nt
.Lcv1_3_41:
	s_or_b64 exec, exec, s[16:17]
	s_and_saveexec_b64 s[16:17], vcc
	s_cbranch_execz .Lcv1_3_43
	v_add3_u32 v12, v2, s15, 6
	v_ashrrev_i32_e32 v13, 31, v12
	v_lshlrev_b64 v[12:13], 12, v[12:13]
	v_lshl_add_u64 v[12:13], v[6:7], 0, v[12:13]
	global_load_dword v227, v[12:13], off nt
.Lcv1_3_43:
	s_or_b64 exec, exec, s[16:17]
	s_and_saveexec_b64 s[16:17], vcc
	s_cbranch_execz .Lcv1_3_45
	v_add3_u32 v12, v2, s15, 8
	v_ashrrev_i32_e32 v13, 31, v12
	v_lshlrev_b64 v[12:13], 12, v[12:13]
	v_lshl_add_u64 v[12:13], v[6:7], 0, v[12:13]
	global_load_dword v228, v[12:13], off nt
.Lcv1_3_45:
	s_or_b64 exec, exec, s[16:17]
	s_and_saveexec_b64 s[16:17], vcc
	s_cbranch_execz .Lcv1_3_47
	v_add3_u32 v12, v2, s15, 10
	v_ashrrev_i32_e32 v13, 31, v12
	v_lshlrev_b64 v[12:13], 12, v[12:13]
	v_lshl_add_u64 v[12:13], v[6:7], 0, v[12:13]
	global_load_dword v229, v[12:13], off nt
.Lcv1_3_47:
	s_or_b64 exec, exec, s[16:17]
	s_and_saveexec_b64 s[16:17], vcc
	s_cbranch_execz .Lcv1_3_49
	v_add3_u32 v12, v2, s15, 12
	v_ashrrev_i32_e32 v13, 31, v12
	v_lshlrev_b64 v[12:13], 12, v[12:13]
	v_lshl_add_u64 v[12:13], v[6:7], 0, v[12:13]
	global_load_dword v230, v[12:13], off nt
.Lcv1_3_49:
	s_or_b64 exec, exec, s[16:17]
	s_and_saveexec_b64 s[16:17], vcc
	s_cbranch_execz .Lcv1_3_end
	v_add3_u32 v12, v2, s15, 14
	v_ashrrev_i32_e32 v13, 31, v12
	v_lshlrev_b64 v[12:13], 12, v[12:13]
	v_lshl_add_u64 v[12:13], v[6:7], 0, v[12:13]
	global_load_dword v231, v[12:13], off nt

.LBB0_56:
	v_mov_b32_e32 v200, 0
	v_mov_b32_e32 v201, 0
	v_mov_b32_e32 v202, 0
	v_mov_b32_e32 v203, 0
	v_mov_b32_e32 v204, 0
	v_mov_b32_e32 v205, 0
	v_mov_b32_e32 v206, 0
	v_mov_b32_e32 v207, 0
	v_mov_b32_e32 v208, 0
	v_mov_b32_e32 v209, 0
	v_mov_b32_e32 v210, 0
	v_mov_b32_e32 v211, 0
	v_mov_b32_e32 v212, 0
	v_mov_b32_e32 v213, 0
	v_mov_b32_e32 v214, 0
	v_mov_b32_e32 v215, 0
	v_mov_b32_e32 v216, 0
	v_mov_b32_e32 v217, 0
	v_mov_b32_e32 v218, 0
	v_mov_b32_e32 v219, 0
	v_mov_b32_e32 v220, 0
	v_mov_b32_e32 v221, 0
	v_mov_b32_e32 v222, 0
	v_mov_b32_e32 v223, 0
	v_mov_b32_e32 v224, 0
	v_mov_b32_e32 v225, 0
	v_mov_b32_e32 v226, 0
	v_mov_b32_e32 v227, 0
	v_mov_b32_e32 v228, 0
	v_mov_b32_e32 v229, 0
	v_mov_b32_e32 v230, 0
	v_mov_b32_e32 v231, 0
	s_and_saveexec_b64 s[16:17], vcc
	s_cbranch_execz .Lcv2_0_58
	v_add_u32_e32 v16, s15, v3
	v_ashrrev_i32_e32 v17, 31, v16
	v_lshlrev_b64 v[16:17], 11, v[16:17]
	v_lshl_add_u64 v[16:17], v[8:9], 0, v[16:17]
	global_load_dword v200, v[16:17], off nt

.Lcv2_0_end:
	s_or_b64 exec, exec, s[16:17]
	s_add_i32 s15, s15, 16
	s_and_saveexec_b64 s[16:17], vcc
	s_cbranch_execz .Lcv2_1_58
	v_add_u32_e32 v16, s15, v3
	v_ashrrev_i32_e32 v17, 31, v16
	v_lshlrev_b64 v[16:17], 11, v[16:17]
	v_lshl_add_u64 v[16:17], v[8:9], 0, v[16:17]
	global_load_dword v208, v[16:17], off nt
.Lcv2_1_58:
	s_or_b64 exec, exec, s[16:17]
	s_and_saveexec_b64 s[16:17], vcc
	s_cbranch_execz .Lcv2_1_60
	v_add3_u32 v16, v3, s15, 2
	v_ashrrev_i32_e32 v17, 31, v16
	v_lshlrev_b64 v[16:17], 11, v[16:17]
	v_lshl_add_u64 v[16:17], v[8:9], 0, v[16:17]
	global_load_dword v209, v[16:17], off nt
.Lcv2_1_60:
	s_or_b64 exec, exec, s[16:17]
	s_and_saveexec_b64 s[16:17], vcc
	s_cbranch_execz .Lcv2_1_62
	v_add3_u32 v16, v3, s15, 4
	v_ashrrev_i32_e32 v17, 31, v16
	v_lshlrev_b64 v[16:17], 11, v[16:17]
	v_lshl_add_u64 v[16:17], v[8:9], 0, v[16:17]
	global_load_dword v210, v[16:17], off nt
.Lcv2_1_62:
	s_or_b64 exec, exec, s[16:17]
	s_and_saveexec_b64 s[16:17], vcc
	s_cbranch_execz .Lcv2_1_64
	v_add3_u32 v16, v3, s15, 6
	v_ashrrev_i32_e32 v17, 31, v16
	v_lshlrev_b64 v[16:17], 11, v[16:17]
	v_lshl_add_u64 v[16:17], v[8:9], 0, v[16:17]
	global_load_dword v211, v[16:17], off nt
.Lcv2_1_64:
	s_or_b64 exec, exec, s[16:17]
	s_and_saveexec_b64 s[16:17], vcc
	s_cbranch_execz .Lcv2_1_66
	v_add3_u32 v16, v3, s15, 8
	v_ashrrev_i32_e32 v17, 31, v16
	v_lshlrev_b64 v[16:17], 11, v[16:17]
	v_lshl_add_u64 v[16:17], v[8:9], 0, v[16:17]
	global_load_dword v212, v[16:17], off nt
.Lcv2_1_66:
	s_or_b64 exec, exec, s[16:17]
	s_and_saveexec_b64 s[16:17], vcc
	s_cbranch_execz .Lcv2_1_68
	v_add3_u32 v16, v3, s15, 10
	v_ashrrev_i32_e32 v17, 31, v16
	v_lshlrev_b64 v[16:17], 11, v[16:17]
	v_lshl_add_u64 v[16:17], v[8:9], 0, v[16:17]
	global_load_dword v213, v[16:17], off nt
.Lcv2_1_68:
	s_or_b64 exec, exec, s[16:17]
	s_and_saveexec_b64 s[16:17], vcc
	s_cbranch_execz .Lcv2_1_70
	v_add3_u32 v16, v3, s15, 12
	v_ashrrev_i32_e32 v17, 31, v16
	v_lshlrev_b64 v[16:17], 11, v[16:17]
	v_lshl_add_u64 v[16:17], v[8:9], 0, v[16:17]
	global_load_dword v214, v[16:17], off nt
.Lcv2_1_70:
	s_or_b64 exec, exec, s[16:17]
	s_and_saveexec_b64 s[16:17], vcc
	s_cbranch_execz .Lcv2_1_end
	v_add3_u32 v16, v3, s15, 14
	v_ashrrev_i32_e32 v17, 31, v16
	v_lshlrev_b64 v[16:17], 11, v[16:17]
	v_lshl_add_u64 v[16:17], v[8:9], 0, v[16:17]
	global_load_dword v215, v[16:17], off nt
.Lcv2_1_end:
	s_or_b64 exec, exec, s[16:17]
	s_add_i32 s15, s15, 16
	s_and_saveexec_b64 s[16:17], vcc
	s_cbranch_execz .Lcv2_2_58
	v_add_u32_e32 v16, s15, v3
	v_ashrrev_i32_e32 v17, 31, v16
	v_lshlrev_b64 v[16:17], 11, v[16:17]
	v_lshl_add_u64 v[16:17], v[8:9], 0, v[16:17]
	global_load_dword v216, v[16:17], off nt
.Lcv2_2_58:
	s_or_b64 exec, exec, s[16:17]
	s_and_saveexec_b64 s[16:17], vcc
	s_cbranch_execz .Lcv2_2_60
	v_add3_u32 v16, v3, s15, 2
	v_ashrrev_i32_e32 v17, 31, v16
	v_lshlrev_b64 v[16:17], 11, v[16:17]
	v_lshl_add_u64 v[16:17], v[8:9], 0, v[16:17]
	global_load_dword v217, v[16:17], off nt
.Lcv2_2_60:
	s_or_b64 exec, exec, s[16:17]
	s_and_saveexec_b64 s[16:17], vcc
	s_cbranch_execz .Lcv2_2_62
	v_add3_u32 v16, v3, s15, 4
	v_ashrrev_i32_e32 v17, 31, v16
	v_lshlrev_b64 v[16:17], 11, v[16:17]
	v_lshl_add_u64 v[16:17], v[8:9], 0, v[16:17]
	global_load_dword v218, v[16:17], off nt
.Lcv2_2_62:
	s_or_b64 exec, exec, s[16:17]
	s_and_saveexec_b64 s[16:17], vcc
	s_cbranch_execz .Lcv2_2_64
	v_add3_u32 v16, v3, s15, 6
	v_ashrrev_i32_e32 v17, 31, v16
	v_lshlrev_b64 v[16:17], 11, v[16:17]
	v_lshl_add_u64 v[16:17], v[8:9], 0, v[16:17]
	global_load_dword v219, v[16:17], off nt
.Lcv2_2_64:
	s_or_b64 exec, exec, s[16:17]
	s_and_saveexec_b64 s[16:17], vcc
	s_cbranch_execz .Lcv2_2_66
	v_add3_u32 v16, v3, s15, 8
	v_ashrrev_i32_e32 v17, 31, v16
	v_lshlrev_b64 v[16:17], 11, v[16:17]
	v_lshl_add_u64 v[16:17], v[8:9], 0, v[16:17]
	global_load_dword v220, v[16:17], off nt
.Lcv2_2_66:
	s_or_b64 exec, exec, s[16:17]
	s_and_saveexec_b64 s[16:17], vcc
	s_cbranch_execz .Lcv2_2_68
	v_add3_u32 v16, v3, s15, 10
	v_ashrrev_i32_e32 v17, 31, v16
	v_lshlrev_b64 v[16:17], 11, v[16:17]
	v_lshl_add_u64 v[16:17], v[8:9], 0, v[16:17]
	global_load_dword v221, v[16:17], off nt
.Lcv2_2_68:
	s_or_b64 exec, exec, s[16:17]
	s_and_saveexec_b64 s[16:17], vcc
	s_cbranch_execz .Lcv2_2_70
	v_add3_u32 v16, v3, s15, 12
	v_ashrrev_i32_e32 v17, 31, v16
	v_lshlrev_b64 v[16:17], 11, v[16:17]
	v_lshl_add_u64 v[16:17], v[8:9], 0, v[16:17]
	global_load_dword v222, v[16:17], off nt
.Lcv2_2_70:
	s_or_b64 exec, exec, s[16:17]
	s_and_saveexec_b64 s[16:17], vcc
	s_cbranch_execz .Lcv2_2_end
	v_add3_u32 v16, v3, s15, 14
	v_ashrrev_i32_e32 v17, 31, v16
	v_lshlrev_b64 v[16:17], 11, v[16:17]
	v_lshl_add_u64 v[16:17], v[8:9], 0, v[16:17]
	global_load_dword v223, v[16:17], off nt
.Lcv2_2_end:
	s_or_b64 exec, exec, s[16:17]
	s_add_i32 s15, s15, 16
	s_and_saveexec_b64 s[16:17], vcc
	s_cbranch_execz .Lcv2_3_58
	v_add_u32_e32 v16, s15, v3
	v_ashrrev_i32_e32 v17, 31, v16
	v_lshlrev_b64 v[16:17], 11, v[16:17]
	v_lshl_add_u64 v[16:17], v[8:9], 0, v[16:17]
	global_load_dword v224, v[16:17], off nt
.Lcv2_3_58:
	s_or_b64 exec, exec, s[16:17]
	s_and_saveexec_b64 s[16:17], vcc
	s_cbranch_execz .Lcv2_3_60
	v_add3_u32 v16, v3, s15, 2
	v_ashrrev_i32_e32 v17, 31, v16
	v_lshlrev_b64 v[16:17], 11, v[16:17]
	v_lshl_add_u64 v[16:17], v[8:9], 0, v[16:17]
	global_load_dword v225, v[16:17], off nt
.Lcv2_3_60:
	s_or_b64 exec, exec, s[16:17]
	s_and_saveexec_b64 s[16:17], vcc
	s_cbranch_execz .Lcv2_3_62
	v_add3_u32 v16, v3, s15, 4
	v_ashrrev_i32_e32 v17, 31, v16
	v_lshlrev_b64 v[16:17], 11, v[16:17]
	v_lshl_add_u64 v[16:17], v[8:9], 0, v[16:17]
	global_load_dword v226, v[16:17], off nt
.Lcv2_3_62:
	s_or_b64 exec, exec, s[16:17]
	s_and_saveexec_b64 s[16:17], vcc
	s_cbranch_execz .Lcv2_3_64
	v_add3_u32 v16, v3, s15, 6
	v_ashrrev_i32_e32 v17, 31, v16
	v_lshlrev_b64 v[16:17], 11, v[16:17]
	v_lshl_add_u64 v[16:17], v[8:9], 0, v[16:17]
	global_load_dword v227, v[16:17], off nt
.Lcv2_3_64:
	s_or_b64 exec, exec, s[16:17]
	s_and_saveexec_b64 s[16:17], vcc
	s_cbranch_execz .Lcv2_3_66
	v_add3_u32 v16, v3, s15, 8
	v_ashrrev_i32_e32 v17, 31, v16
	v_lshlrev_b64 v[16:17], 11, v[16:17]
	v_lshl_add_u64 v[16:17], v[8:9], 0, v[16:17]
	global_load_dword v228, v[16:17], off nt
.Lcv2_3_66:
	s_or_b64 exec, exec, s[16:17]
	s_and_saveexec_b64 s[16:17], vcc
	s_cbranch_execz .Lcv2_3_68
	v_add3_u32 v16, v3, s15, 10
	v_ashrrev_i32_e32 v17, 31, v16
	v_lshlrev_b64 v[16:17], 11, v[16:17]
	v_lshl_add_u64 v[16:17], v[8:9], 0, v[16:17]
	global_load_dword v229, v[16:17], off nt
.Lcv2_3_68:
	s_or_b64 exec, exec, s[16:17]
	s_and_saveexec_b64 s[16:17], vcc
	s_cbranch_execz .Lcv2_3_70
	v_add3_u32 v16, v3, s15, 12
	v_ashrrev_i32_e32 v17, 31, v16
	v_lshlrev_b64 v[16:17], 11, v[16:17]
	v_lshl_add_u64 v[16:17], v[8:9], 0, v[16:17]
	global_load_dword v230, v[16:17], off nt
.Lcv2_3_70:
	s_or_b64 exec, exec, s[16:17]
	s_and_saveexec_b64 s[16:17], vcc
	s_cbranch_execz .Lcv2_3_end
	v_add3_u32 v16, v3, s15, 14
	v_ashrrev_i32_e32 v17, 31, v16
	v_lshlrev_b64 v[16:17], 11, v[16:17]
	v_lshl_add_u64 v[16:17], v[8:9], 0, v[16:17]
	global_load_dword v231, v[16:17], off nt
.Lcv2_3_end:
	s_or_b64 exec, exec, s[16:17]
	s_add_i32 s15, s15, 16
	s_waitcnt vmcnt(0)
	ds_write_b32 v4, v200
	ds_write_b32 v4, v201 offset:264
	ds_write_b32 v4, v202 offset:528
	ds_write_b32 v4, v203 offset:792
	ds_write_b32 v4, v204 offset:1056
	ds_write_b32 v4, v205 offset:1320
	ds_write_b32 v4, v206 offset:1584
	ds_write_b32 v4, v207 offset:1848
	ds_write_b32 v4, v208 offset:2112
	ds_write_b32 v4, v209 offset:2376
	ds_write_b32 v4, v210 offset:2640
	ds_write_b32 v4, v211 offset:2904
	ds_write_b32 v4, v212 offset:3168
	ds_write_b32 v4, v213 offset:3432
	ds_write_b32 v4, v214 offset:3696
	ds_write_b32 v4, v215 offset:3960
	ds_write_b32 v4, v216 offset:4224
	ds_write_b32 v4, v217 offset:4488
	ds_write_b32 v4, v218 offset:4752
	ds_write_b32 v4, v219 offset:5016
	ds_write_b32 v4, v220 offset:5280
	ds_write_b32 v4, v221 offset:5544
	ds_write_b32 v4, v222 offset:5808
	ds_write_b32 v4, v223 offset:6072
	ds_write_b32 v4, v224 offset:6336
	ds_write_b32 v4, v225 offset:6600
	ds_write_b32 v4, v226 offset:6864
	ds_write_b32 v4, v227 offset:7128
	ds_write_b32 v4, v228 offset:7392
	ds_write_b32 v4, v229 offset:7656
	ds_write_b32 v4, v230 offset:7920
	ds_write_b32 v4, v231 offset:8184
	s_branch .LBB0_53

.LBB0_76:
	v_mov_b32_e32 v200, 0
	v_mov_b32_e32 v201, 0
	v_mov_b32_e32 v202, 0
	v_mov_b32_e32 v203, 0
	v_mov_b32_e32 v204, 0
	v_mov_b32_e32 v205, 0
	v_mov_b32_e32 v206, 0
	v_mov_b32_e32 v207, 0
	v_mov_b32_e32 v208, 0
	v_mov_b32_e32 v209, 0
	v_mov_b32_e32 v210, 0
	v_mov_b32_e32 v211, 0
	v_mov_b32_e32 v212, 0
	v_mov_b32_e32 v213, 0
	v_mov_b32_e32 v214, 0
	v_mov_b32_e32 v215, 0
	v_mov_b32_e32 v216, 0
	v_mov_b32_e32 v217, 0
	v_mov_b32_e32 v218, 0
	v_mov_b32_e32 v219, 0
	v_mov_b32_e32 v220, 0
	v_mov_b32_e32 v221, 0
	v_mov_b32_e32 v222, 0
	v_mov_b32_e32 v223, 0
	v_mov_b32_e32 v224, 0
	v_mov_b32_e32 v225, 0
	v_mov_b32_e32 v226, 0
	v_mov_b32_e32 v227, 0
	v_mov_b32_e32 v228, 0
	v_mov_b32_e32 v229, 0
	v_mov_b32_e32 v230, 0
	v_mov_b32_e32 v231, 0
	s_and_saveexec_b64 s[16:17], vcc
	s_cbranch_execz .Lcv3_0_78
	v_add_u32_e32 v16, s15, v2
	v_ashrrev_i32_e32 v17, 31, v16
	v_lshlrev_b64 v[16:17], 11, v[16:17]
	v_lshl_add_u64 v[16:17], v[6:7], 0, v[16:17]
	global_load_dword v200, v[16:17], off nt

.Lcv3_0_end:
	s_or_b64 exec, exec, s[16:17]
	s_add_i32 s15, s15, 16
	s_and_saveexec_b64 s[16:17], vcc
	s_cbranch_execz .Lcv3_1_78
	v_add_u32_e32 v16, s15, v2
	v_ashrrev_i32_e32 v17, 31, v16
	v_lshlrev_b64 v[16:17], 11, v[16:17]
	v_lshl_add_u64 v[16:17], v[6:7], 0, v[16:17]
	global_load_dword v208, v[16:17], off nt
.Lcv3_1_78:
	s_or_b64 exec, exec, s[16:17]
	s_and_saveexec_b64 s[16:17], vcc
	s_cbranch_execz .Lcv3_1_80
	v_add3_u32 v16, v2, s15, 2
	v_ashrrev_i32_e32 v17, 31, v16
	v_lshlrev_b64 v[16:17], 11, v[16:17]
	v_lshl_add_u64 v[16:17], v[6:7], 0, v[16:17]
	global_load_dword v209, v[16:17], off nt
.Lcv3_1_80:
	s_or_b64 exec, exec, s[16:17]
	s_and_saveexec_b64 s[16:17], vcc
	s_cbranch_execz .Lcv3_1_82
	v_add3_u32 v16, v2, s15, 4
	v_ashrrev_i32_e32 v17, 31, v16
	v_lshlrev_b64 v[16:17], 11, v[16:17]
	v_lshl_add_u64 v[16:17], v[6:7], 0, v[16:17]
	global_load_dword v210, v[16:17], off nt
.Lcv3_1_82:
	s_or_b64 exec, exec, s[16:17]
	s_and_saveexec_b64 s[16:17], vcc
	s_cbranch_execz .Lcv3_1_84
	v_add3_u32 v16, v2, s15, 6
	v_ashrrev_i32_e32 v17, 31, v16
	v_lshlrev_b64 v[16:17], 11, v[16:17]
	v_lshl_add_u64 v[16:17], v[6:7], 0, v[16:17]
	global_load_dword v211, v[16:17], off nt
.Lcv3_1_84:
	s_or_b64 exec, exec, s[16:17]
	s_and_saveexec_b64 s[16:17], vcc
	s_cbranch_execz .Lcv3_1_86
	v_add3_u32 v16, v2, s15, 8
	v_ashrrev_i32_e32 v17, 31, v16
	v_lshlrev_b64 v[16:17], 11, v[16:17]
	v_lshl_add_u64 v[16:17], v[6:7], 0, v[16:17]
	global_load_dword v212, v[16:17], off nt
.Lcv3_1_86:
	s_or_b64 exec, exec, s[16:17]
	s_and_saveexec_b64 s[16:17], vcc
	s_cbranch_execz .Lcv3_1_88
	v_add3_u32 v16, v2, s15, 10
	v_ashrrev_i32_e32 v17, 31, v16
	v_lshlrev_b64 v[16:17], 11, v[16:17]
	v_lshl_add_u64 v[16:17], v[6:7], 0, v[16:17]
	global_load_dword v213, v[16:17], off nt
.Lcv3_1_88:
	s_or_b64 exec, exec, s[16:17]
	s_and_saveexec_b64 s[16:17], vcc
	s_cbranch_execz .Lcv3_1_90
	v_add3_u32 v16, v2, s15, 12
	v_ashrrev_i32_e32 v17, 31, v16
	v_lshlrev_b64 v[16:17], 11, v[16:17]
	v_lshl_add_u64 v[16:17], v[6:7], 0, v[16:17]
	global_load_dword v214, v[16:17], off nt
.Lcv3_1_90:
	s_or_b64 exec, exec, s[16:17]
	s_and_saveexec_b64 s[16:17], vcc
	s_cbranch_execz .Lcv3_1_end
	v_add3_u32 v16, v2, s15, 14
	v_ashrrev_i32_e32 v17, 31, v16
	v_lshlrev_b64 v[16:17], 11, v[16:17]
	v_lshl_add_u64 v[16:17], v[6:7], 0, v[16:17]
	global_load_dword v215, v[16:17], off nt
.Lcv3_1_end:
	s_or_b64 exec, exec, s[16:17]
	s_add_i32 s15, s15, 16
	s_and_saveexec_b64 s[16:17], vcc
	s_cbranch_execz .Lcv3_2_78
	v_add_u32_e32 v16, s15, v2
	v_ashrrev_i32_e32 v17, 31, v16
	v_lshlrev_b64 v[16:17], 11, v[16:17]
	v_lshl_add_u64 v[16:17], v[6:7], 0, v[16:17]
	global_load_dword v216, v[16:17], off nt
.Lcv3_2_78:
	s_or_b64 exec, exec, s[16:17]
	s_and_saveexec_b64 s[16:17], vcc
	s_cbranch_execz .Lcv3_2_80
	v_add3_u32 v16, v2, s15, 2
	v_ashrrev_i32_e32 v17, 31, v16
	v_lshlrev_b64 v[16:17], 11, v[16:17]
	v_lshl_add_u64 v[16:17], v[6:7], 0, v[16:17]
	global_load_dword v217, v[16:17], off nt
.Lcv3_2_80:
	s_or_b64 exec, exec, s[16:17]
	s_and_saveexec_b64 s[16:17], vcc
	s_cbranch_execz .Lcv3_2_82
	v_add3_u32 v16, v2, s15, 4
	v_ashrrev_i32_e32 v17, 31, v16
	v_lshlrev_b64 v[16:17], 11, v[16:17]
	v_lshl_add_u64 v[16:17], v[6:7], 0, v[16:17]
	global_load_dword v218, v[16:17], off nt
.Lcv3_2_82:
	s_or_b64 exec, exec, s[16:17]
	s_and_saveexec_b64 s[16:17], vcc
	s_cbranch_execz .Lcv3_2_84
	v_add3_u32 v16, v2, s15, 6
	v_ashrrev_i32_e32 v17, 31, v16
	v_lshlrev_b64 v[16:17], 11, v[16:17]
	v_lshl_add_u64 v[16:17], v[6:7], 0, v[16:17]
	global_load_dword v219, v[16:17], off nt
.Lcv3_2_84:
	s_or_b64 exec, exec, s[16:17]
	s_and_saveexec_b64 s[16:17], vcc
	s_cbranch_execz .Lcv3_2_86
	v_add3_u32 v16, v2, s15, 8
	v_ashrrev_i32_e32 v17, 31, v16
	v_lshlrev_b64 v[16:17], 11, v[16:17]
	v_lshl_add_u64 v[16:17], v[6:7], 0, v[16:17]
	global_load_dword v220, v[16:17], off nt
.Lcv3_2_86:
	s_or_b64 exec, exec, s[16:17]
	s_and_saveexec_b64 s[16:17], vcc
	s_cbranch_execz .Lcv3_2_88
	v_add3_u32 v16, v2, s15, 10
	v_ashrrev_i32_e32 v17, 31, v16
	v_lshlrev_b64 v[16:17], 11, v[16:17]
	v_lshl_add_u64 v[16:17], v[6:7], 0, v[16:17]
	global_load_dword v221, v[16:17], off nt
.Lcv3_2_88:
	s_or_b64 exec, exec, s[16:17]
	s_and_saveexec_b64 s[16:17], vcc
	s_cbranch_execz .Lcv3_2_90
	v_add3_u32 v16, v2, s15, 12
	v_ashrrev_i32_e32 v17, 31, v16
	v_lshlrev_b64 v[16:17], 11, v[16:17]
	v_lshl_add_u64 v[16:17], v[6:7], 0, v[16:17]
	global_load_dword v222, v[16:17], off nt
.Lcv3_2_90:
	s_or_b64 exec, exec, s[16:17]
	s_and_saveexec_b64 s[16:17], vcc
	s_cbranch_execz .Lcv3_2_end
	v_add3_u32 v16, v2, s15, 14
	v_ashrrev_i32_e32 v17, 31, v16
	v_lshlrev_b64 v[16:17], 11, v[16:17]
	v_lshl_add_u64 v[16:17], v[6:7], 0, v[16:17]
	global_load_dword v223, v[16:17], off nt
.Lcv3_2_end:
	s_or_b64 exec, exec, s[16:17]
	s_add_i32 s15, s15, 16
	s_and_saveexec_b64 s[16:17], vcc
	s_cbranch_execz .Lcv3_3_78
	v_add_u32_e32 v16, s15, v2
	v_ashrrev_i32_e32 v17, 31, v16
	v_lshlrev_b64 v[16:17], 11, v[16:17]
	v_lshl_add_u64 v[16:17], v[6:7], 0, v[16:17]
	global_load_dword v224, v[16:17], off nt
.Lcv3_3_78:
	s_or_b64 exec, exec, s[16:17]
	s_and_saveexec_b64 s[16:17], vcc
	s_cbranch_execz .Lcv3_3_80
	v_add3_u32 v16, v2, s15, 2
	v_ashrrev_i32_e32 v17, 31, v16
	v_lshlrev_b64 v[16:17], 11, v[16:17]
	v_lshl_add_u64 v[16:17], v[6:7], 0, v[16:17]
	global_load_dword v225, v[16:17], off nt
.Lcv3_3_80:
	s_or_b64 exec, exec, s[16:17]
	s_and_saveexec_b64 s[16:17], vcc
	s_cbranch_execz .Lcv3_3_82
	v_add3_u32 v16, v2, s15, 4
	v_ashrrev_i32_e32 v17, 31, v16
	v_lshlrev_b64 v[16:17], 11, v[16:17]
	v_lshl_add_u64 v[16:17], v[6:7], 0, v[16:17]
	global_load_dword v226, v[16:17], off nt
.Lcv3_3_82:
	s_or_b64 exec, exec, s[16:17]
	s_and_saveexec_b64 s[16:17], vcc
	s_cbranch_execz .Lcv3_3_84
	v_add3_u32 v16, v2, s15, 6
	v_ashrrev_i32_e32 v17, 31, v16
	v_lshlrev_b64 v[16:17], 11, v[16:17]
	v_lshl_add_u64 v[16:17], v[6:7], 0, v[16:17]
	global_load_dword v227, v[16:17], off nt
.Lcv3_3_84:
	s_or_b64 exec, exec, s[16:17]
	s_and_saveexec_b64 s[16:17], vcc
	s_cbranch_execz .Lcv3_3_86
	v_add3_u32 v16, v2, s15, 8
	v_ashrrev_i32_e32 v17, 31, v16
	v_lshlrev_b64 v[16:17], 11, v[16:17]
	v_lshl_add_u64 v[16:17], v[6:7], 0, v[16:17]
	global_load_dword v228, v[16:17], off nt
.Lcv3_3_86:
	s_or_b64 exec, exec, s[16:17]
	s_and_saveexec_b64 s[16:17], vcc
	s_cbranch_execz .Lcv3_3_88
	v_add3_u32 v16, v2, s15, 10
	v_ashrrev_i32_e32 v17, 31, v16
	v_lshlrev_b64 v[16:17], 11, v[16:17]
	v_lshl_add_u64 v[16:17], v[6:7], 0, v[16:17]
	global_load_dword v229, v[16:17], off nt
.Lcv3_3_88:
	s_or_b64 exec, exec, s[16:17]
	s_and_saveexec_b64 s[16:17], vcc
	s_cbranch_execz .Lcv3_3_90
	v_add3_u32 v16, v2, s15, 12
	v_ashrrev_i32_e32 v17, 31, v16
	v_lshlrev_b64 v[16:17], 11, v[16:17]
	v_lshl_add_u64 v[16:17], v[6:7], 0, v[16:17]
	global_load_dword v230, v[16:17], off nt
.Lcv3_3_90:
	s_or_b64 exec, exec, s[16:17]
	s_and_saveexec_b64 s[16:17], vcc
	s_cbranch_execz .Lcv3_3_end
	v_add3_u32 v16, v2, s15, 14
	v_ashrrev_i32_e32 v17, 31, v16
	v_lshlrev_b64 v[16:17], 11, v[16:17]
	v_lshl_add_u64 v[16:17], v[6:7], 0, v[16:17]
	global_load_dword v231, v[16:17], off nt
.Lcv3_3_end:
	s_or_b64 exec, exec, s[16:17]
	s_add_i32 s15, s15, 16
	s_waitcnt vmcnt(0)
	ds_write_b32 v8, v200
	ds_write_b32 v8, v201 offset:264
	ds_write_b32 v8, v202 offset:528
	ds_write_b32 v8, v203 offset:792
	ds_write_b32 v8, v204 offset:1056
	ds_write_b32 v8, v205 offset:1320
	ds_write_b32 v8, v206 offset:1584
	ds_write_b32 v8, v207 offset:1848
	ds_write_b32 v8, v208 offset:2112
	ds_write_b32 v8, v209 offset:2376
	ds_write_b32 v8, v210 offset:2640
	ds_write_b32 v8, v211 offset:2904
	ds_write_b32 v8, v212 offset:3168
	ds_write_b32 v8, v213 offset:3432
	ds_write_b32 v8, v214 offset:3696
	ds_write_b32 v8, v215 offset:3960
	ds_write_b32 v8, v216 offset:4224
	ds_write_b32 v8, v217 offset:4488
	ds_write_b32 v8, v218 offset:4752
	ds_write_b32 v8, v219 offset:5016
	ds_write_b32 v8, v220 offset:5280
	ds_write_b32 v8, v221 offset:5544
	ds_write_b32 v8, v222 offset:5808
	ds_write_b32 v8, v223 offset:6072
	ds_write_b32 v8, v224 offset:6336
	ds_write_b32 v8, v225 offset:6600
	ds_write_b32 v8, v226 offset:6864
	ds_write_b32 v8, v227 offset:7128
	ds_write_b32 v8, v228 offset:7392
	ds_write_b32 v8, v229 offset:7656
	ds_write_b32 v8, v230 offset:7920
	ds_write_b32 v8, v231 offset:8184
	s_branch .LBB0_73

.LBB0_97:
	v_mov_b32_e32 v200, 0
	v_mov_b32_e32 v201, 0
	v_mov_b32_e32 v202, 0
	v_mov_b32_e32 v203, 0
	v_mov_b32_e32 v204, 0
	v_mov_b32_e32 v205, 0
	v_mov_b32_e32 v206, 0
	v_mov_b32_e32 v207, 0
	v_mov_b32_e32 v208, 0
	v_mov_b32_e32 v209, 0
	v_mov_b32_e32 v210, 0
	v_mov_b32_e32 v211, 0
	v_mov_b32_e32 v212, 0
	v_mov_b32_e32 v213, 0
	v_mov_b32_e32 v214, 0
	v_mov_b32_e32 v215, 0
	v_mov_b32_e32 v216, 0
	v_mov_b32_e32 v217, 0
	v_mov_b32_e32 v218, 0
	v_mov_b32_e32 v219, 0
	v_mov_b32_e32 v220, 0
	v_mov_b32_e32 v221, 0
	v_mov_b32_e32 v222, 0
	v_mov_b32_e32 v223, 0
	v_mov_b32_e32 v224, 0
	v_mov_b32_e32 v225, 0
	v_mov_b32_e32 v226, 0
	v_mov_b32_e32 v227, 0
	v_mov_b32_e32 v228, 0
	v_mov_b32_e32 v229, 0
	v_mov_b32_e32 v230, 0
	v_mov_b32_e32 v231, 0
	s_and_saveexec_b64 s[16:17], vcc
	s_cbranch_execz .Lcv4_0_99
	v_add_u32_e32 v12, s15, v2
	v_ashrrev_i32_e32 v13, 31, v12
	v_lshlrev_b64 v[12:13], 11, v[12:13]
	v_lshl_add_u64 v[12:13], v[6:7], 0, v[12:13]
	global_load_dword v200, v[12:13], off nt

.Lcv4_0_end:
	s_or_b64 exec, exec, s[16:17]
	s_add_i32 s15, s15, 16
	s_and_saveexec_b64 s[16:17], vcc
	s_cbranch_execz .Lcv4_1_99
	v_add_u32_e32 v12, s15, v2
	v_ashrrev_i32_e32 v13, 31, v12
	v_lshlrev_b64 v[12:13], 11, v[12:13]
	v_lshl_add_u64 v[12:13], v[6:7], 0, v[12:13]
	global_load_dword v208, v[12:13], off nt
.Lcv4_1_99:
	s_or_b64 exec, exec, s[16:17]
	s_and_saveexec_b64 s[16:17], vcc
	s_cbranch_execz .Lcv4_1_101
	v_add3_u32 v12, v2, s15, 2
	v_ashrrev_i32_e32 v13, 31, v12
	v_lshlrev_b64 v[12:13], 11, v[12:13]
	v_lshl_add_u64 v[12:13], v[6:7], 0, v[12:13]
	global_load_dword v209, v[12:13], off nt
.Lcv4_1_101:
	s_or_b64 exec, exec, s[16:17]
	s_and_saveexec_b64 s[16:17], vcc
	s_cbranch_execz .Lcv4_1_103
	v_add3_u32 v12, v2, s15, 4
	v_ashrrev_i32_e32 v13, 31, v12
	v_lshlrev_b64 v[12:13], 11, v[12:13]
	v_lshl_add_u64 v[12:13], v[6:7], 0, v[12:13]
	global_load_dword v210, v[12:13], off nt
.Lcv4_1_103:
	s_or_b64 exec, exec, s[16:17]
	s_and_saveexec_b64 s[16:17], vcc
	s_cbranch_execz .Lcv4_1_105
	v_add3_u32 v12, v2, s15, 6
	v_ashrrev_i32_e32 v13, 31, v12
	v_lshlrev_b64 v[12:13], 11, v[12:13]
	v_lshl_add_u64 v[12:13], v[6:7], 0, v[12:13]
	global_load_dword v211, v[12:13], off nt
.Lcv4_1_105:
	s_or_b64 exec, exec, s[16:17]
	s_and_saveexec_b64 s[16:17], vcc
	s_cbranch_execz .Lcv4_1_107
	v_add3_u32 v12, v2, s15, 8
	v_ashrrev_i32_e32 v13, 31, v12
	v_lshlrev_b64 v[12:13], 11, v[12:13]
	v_lshl_add_u64 v[12:13], v[6:7], 0, v[12:13]
	global_load_dword v212, v[12:13], off nt
.Lcv4_1_107:
	s_or_b64 exec, exec, s[16:17]
	s_and_saveexec_b64 s[16:17], vcc
	s_cbranch_execz .Lcv4_1_109
	v_add3_u32 v12, v2, s15, 10
	v_ashrrev_i32_e32 v13, 31, v12
	v_lshlrev_b64 v[12:13], 11, v[12:13]
	v_lshl_add_u64 v[12:13], v[6:7], 0, v[12:13]
	global_load_dword v213, v[12:13], off nt
.Lcv4_1_109:
	s_or_b64 exec, exec, s[16:17]
	s_and_saveexec_b64 s[16:17], vcc
	s_cbranch_execz .Lcv4_1_111
	v_add3_u32 v12, v2, s15, 12
	v_ashrrev_i32_e32 v13, 31, v12
	v_lshlrev_b64 v[12:13], 11, v[12:13]
	v_lshl_add_u64 v[12:13], v[6:7], 0, v[12:13]
	global_load_dword v214, v[12:13], off nt
.Lcv4_1_111:
	s_or_b64 exec, exec, s[16:17]
	s_and_saveexec_b64 s[16:17], vcc
	s_cbranch_execz .Lcv4_1_end
	v_add3_u32 v12, v2, s15, 14
	v_ashrrev_i32_e32 v13, 31, v12
	v_lshlrev_b64 v[12:13], 11, v[12:13]
	v_lshl_add_u64 v[12:13], v[6:7], 0, v[12:13]
	global_load_dword v215, v[12:13], off nt
.Lcv4_1_end:
	s_or_b64 exec, exec, s[16:17]
	s_add_i32 s15, s15, 16
	s_and_saveexec_b64 s[16:17], vcc
	s_cbranch_execz .Lcv4_2_99
	v_add_u32_e32 v12, s15, v2
	v_ashrrev_i32_e32 v13, 31, v12
	v_lshlrev_b64 v[12:13], 11, v[12:13]
	v_lshl_add_u64 v[12:13], v[6:7], 0, v[12:13]
	global_load_dword v216, v[12:13], off nt
.Lcv4_2_99:
	s_or_b64 exec, exec, s[16:17]
	s_and_saveexec_b64 s[16:17], vcc
	s_cbranch_execz .Lcv4_2_101
	v_add3_u32 v12, v2, s15, 2
	v_ashrrev_i32_e32 v13, 31, v12
	v_lshlrev_b64 v[12:13], 11, v[12:13]
	v_lshl_add_u64 v[12:13], v[6:7], 0, v[12:13]
	global_load_dword v217, v[12:13], off nt
.Lcv4_2_101:
	s_or_b64 exec, exec, s[16:17]
	s_and_saveexec_b64 s[16:17], vcc
	s_cbranch_execz .Lcv4_2_103
	v_add3_u32 v12, v2, s15, 4
	v_ashrrev_i32_e32 v13, 31, v12
	v_lshlrev_b64 v[12:13], 11, v[12:13]
	v_lshl_add_u64 v[12:13], v[6:7], 0, v[12:13]
	global_load_dword v218, v[12:13], off nt
.Lcv4_2_103:
	s_or_b64 exec, exec, s[16:17]
	s_and_saveexec_b64 s[16:17], vcc
	s_cbranch_execz .Lcv4_2_105
	v_add3_u32 v12, v2, s15, 6
	v_ashrrev_i32_e32 v13, 31, v12
	v_lshlrev_b64 v[12:13], 11, v[12:13]
	v_lshl_add_u64 v[12:13], v[6:7], 0, v[12:13]
	global_load_dword v219, v[12:13], off nt
.Lcv4_2_105:
	s_or_b64 exec, exec, s[16:17]
	s_and_saveexec_b64 s[16:17], vcc
	s_cbranch_execz .Lcv4_2_107
	v_add3_u32 v12, v2, s15, 8
	v_ashrrev_i32_e32 v13, 31, v12
	v_lshlrev_b64 v[12:13], 11, v[12:13]
	v_lshl_add_u64 v[12:13], v[6:7], 0, v[12:13]
	global_load_dword v220, v[12:13], off nt
.Lcv4_2_107:
	s_or_b64 exec, exec, s[16:17]
	s_and_saveexec_b64 s[16:17], vcc
	s_cbranch_execz .Lcv4_2_109
	v_add3_u32 v12, v2, s15, 10
	v_ashrrev_i32_e32 v13, 31, v12
	v_lshlrev_b64 v[12:13], 11, v[12:13]
	v_lshl_add_u64 v[12:13], v[6:7], 0, v[12:13]
	global_load_dword v221, v[12:13], off nt
.Lcv4_2_109:
	s_or_b64 exec, exec, s[16:17]
	s_and_saveexec_b64 s[16:17], vcc
	s_cbranch_execz .Lcv4_2_111
	v_add3_u32 v12, v2, s15, 12
	v_ashrrev_i32_e32 v13, 31, v12
	v_lshlrev_b64 v[12:13], 11, v[12:13]
	v_lshl_add_u64 v[12:13], v[6:7], 0, v[12:13]
	global_load_dword v222, v[12:13], off nt
.Lcv4_2_111:
	s_or_b64 exec, exec, s[16:17]
	s_and_saveexec_b64 s[16:17], vcc
	s_cbranch_execz .Lcv4_2_end
	v_add3_u32 v12, v2, s15, 14
	v_ashrrev_i32_e32 v13, 31, v12
	v_lshlrev_b64 v[12:13], 11, v[12:13]
	v_lshl_add_u64 v[12:13], v[6:7], 0, v[12:13]
	global_load_dword v223, v[12:13], off nt
.Lcv4_2_end:
	s_or_b64 exec, exec, s[16:17]
	s_add_i32 s15, s15, 16
	s_and_saveexec_b64 s[16:17], vcc
	s_cbranch_execz .Lcv4_3_99
	v_add_u32_e32 v12, s15, v2
	v_ashrrev_i32_e32 v13, 31, v12
	v_lshlrev_b64 v[12:13], 11, v[12:13]
	v_lshl_add_u64 v[12:13], v[6:7], 0, v[12:13]
	global_load_dword v224, v[12:13], off nt
.Lcv4_3_99:
	s_or_b64 exec, exec, s[16:17]
	s_and_saveexec_b64 s[16:17], vcc
	s_cbranch_execz .Lcv4_3_101
	v_add3_u32 v12, v2, s15, 2
	v_ashrrev_i32_e32 v13, 31, v12
	v_lshlrev_b64 v[12:13], 11, v[12:13]
	v_lshl_add_u64 v[12:13], v[6:7], 0, v[12:13]
	global_load_dword v225, v[12:13], off nt
.Lcv4_3_101:
	s_or_b64 exec, exec, s[16:17]
	s_and_saveexec_b64 s[16:17], vcc
	s_cbranch_execz .Lcv4_3_103
	v_add3_u32 v12, v2, s15, 4
	v_ashrrev_i32_e32 v13, 31, v12
	v_lshlrev_b64 v[12:13], 11, v[12:13]
	v_lshl_add_u64 v[12:13], v[6:7], 0, v[12:13]
	global_load_dword v226, v[12:13], off nt
.Lcv4_3_103:
	s_or_b64 exec, exec, s[16:17]
	s_and_saveexec_b64 s[16:17], vcc
	s_cbranch_execz .Lcv4_3_105
	v_add3_u32 v12, v2, s15, 6
	v_ashrrev_i32_e32 v13, 31, v12
	v_lshlrev_b64 v[12:13], 11, v[12:13]
	v_lshl_add_u64 v[12:13], v[6:7], 0, v[12:13]
	global_load_dword v227, v[12:13], off nt
.Lcv4_3_105:
	s_or_b64 exec, exec, s[16:17]
	s_and_saveexec_b64 s[16:17], vcc
	s_cbranch_execz .Lcv4_3_107
	v_add3_u32 v12, v2, s15, 8
	v_ashrrev_i32_e32 v13, 31, v12
	v_lshlrev_b64 v[12:13], 11, v[12:13]
	v_lshl_add_u64 v[12:13], v[6:7], 0, v[12:13]
	global_load_dword v228, v[12:13], off nt
.Lcv4_3_107:
	s_or_b64 exec, exec, s[16:17]
	s_and_saveexec_b64 s[16:17], vcc
	s_cbranch_execz .Lcv4_3_109
	v_add3_u32 v12, v2, s15, 10
	v_ashrrev_i32_e32 v13, 31, v12
	v_lshlrev_b64 v[12:13], 11, v[12:13]
	v_lshl_add_u64 v[12:13], v[6:7], 0, v[12:13]
	global_load_dword v229, v[12:13], off nt
.Lcv4_3_109:
	s_or_b64 exec, exec, s[16:17]
	s_and_saveexec_b64 s[16:17], vcc
	s_cbranch_execz .Lcv4_3_111
	v_add3_u32 v12, v2, s15, 12
	v_ashrrev_i32_e32 v13, 31, v12
	v_lshlrev_b64 v[12:13], 11, v[12:13]
	v_lshl_add_u64 v[12:13], v[6:7], 0, v[12:13]
	global_load_dword v230, v[12:13], off nt
.Lcv4_3_111:
	s_or_b64 exec, exec, s[16:17]
	s_and_saveexec_b64 s[16:17], vcc
	s_cbranch_execz .Lcv4_3_end
	v_add3_u32 v12, v2, s15, 14
	v_ashrrev_i32_e32 v13, 31, v12
	v_lshlrev_b64 v[12:13], 11, v[12:13]
	v_lshl_add_u64 v[12:13], v[6:7], 0, v[12:13]
	global_load_dword v231, v[12:13], off nt

.LBB0_118:
	v_mov_b32_e32 v200, 0
	v_mov_b32_e32 v201, 0
	v_mov_b32_e32 v202, 0
	v_mov_b32_e32 v203, 0
	v_mov_b32_e32 v204, 0
	v_mov_b32_e32 v205, 0
	v_mov_b32_e32 v206, 0
	v_mov_b32_e32 v207, 0
	v_mov_b32_e32 v208, 0
	v_mov_b32_e32 v209, 0
	v_mov_b32_e32 v210, 0
	v_mov_b32_e32 v211, 0
	v_mov_b32_e32 v212, 0
	v_mov_b32_e32 v213, 0
	v_mov_b32_e32 v214, 0
	v_mov_b32_e32 v215, 0
	v_mov_b32_e32 v216, 0
	v_mov_b32_e32 v217, 0
	v_mov_b32_e32 v218, 0
	v_mov_b32_e32 v219, 0
	v_mov_b32_e32 v220, 0
	v_mov_b32_e32 v221, 0
	v_mov_b32_e32 v222, 0
	v_mov_b32_e32 v223, 0
	v_mov_b32_e32 v224, 0
	v_mov_b32_e32 v225, 0
	v_mov_b32_e32 v226, 0
	v_mov_b32_e32 v227, 0
	v_mov_b32_e32 v228, 0
	v_mov_b32_e32 v229, 0
	v_mov_b32_e32 v230, 0
	v_mov_b32_e32 v231, 0
	s_and_b64 vcc, exec, s[4:5]
	s_cbranch_vccnz .Lcv5_0_120
	v_lshl_add_u64 v[38:39], v[20:21], 0, s[18:19]
	global_load_dword v200, v[38:39], off nt

.Lcv5_0_end:
	s_add_u32 s18, s18, 0x58000
	s_addc_u32 s19, s19, 0
	s_and_b64 vcc, exec, s[4:5]
	s_cbranch_vccnz .Lcv5_1_120
	v_lshl_add_u64 v[38:39], v[20:21], 0, s[18:19]
	global_load_dword v208, v[38:39], off nt
.Lcv5_1_120:
	s_and_b64 vcc, exec, s[4:5]
	s_cbranch_vccnz .Lcv5_1_122
	v_lshl_add_u64 v[36:37], v[18:19], 0, s[18:19]
	global_load_dword v209, v[36:37], off nt
.Lcv5_1_122:
	s_and_b64 vcc, exec, s[4:5]
	s_cbranch_vccnz .Lcv5_1_124
	v_lshl_add_u64 v[38:39], v[16:17], 0, s[18:19]
	global_load_dword v210, v[38:39], off nt
.Lcv5_1_124:
	s_and_b64 vcc, exec, s[4:5]
	s_cbranch_vccnz .Lcv5_1_126
	v_lshl_add_u64 v[36:37], v[14:15], 0, s[18:19]
	global_load_dword v211, v[36:37], off nt
.Lcv5_1_126:
	s_and_b64 vcc, exec, s[4:5]
	s_cbranch_vccnz .Lcv5_1_128
	v_lshl_add_u64 v[38:39], v[12:13], 0, s[18:19]
	global_load_dword v212, v[38:39], off nt
.Lcv5_1_128:
	s_and_b64 vcc, exec, s[4:5]
	s_cbranch_vccnz .Lcv5_1_130
	v_lshl_add_u64 v[36:37], v[10:11], 0, s[18:19]
	global_load_dword v213, v[36:37], off nt
.Lcv5_1_130:
	s_and_b64 vcc, exec, s[4:5]
	s_cbranch_vccnz .Lcv5_1_132
	v_lshl_add_u64 v[38:39], v[8:9], 0, s[18:19]
	global_load_dword v214, v[38:39], off nt
.Lcv5_1_132:
	s_and_b64 vcc, exec, s[4:5]
	s_cbranch_vccnz .Lcv5_1_end
	v_lshl_add_u64 v[36:37], v[6:7], 0, s[18:19]
	global_load_dword v215, v[36:37], off nt
.Lcv5_1_end:
	s_add_u32 s18, s18, 0x58000
	s_addc_u32 s19, s19, 0
	s_and_b64 vcc, exec, s[4:5]
	s_cbranch_vccnz .Lcv5_2_120
	v_lshl_add_u64 v[38:39], v[20:21], 0, s[18:19]
	global_load_dword v216, v[38:39], off nt
.Lcv5_2_120:
	s_and_b64 vcc, exec, s[4:5]
	s_cbranch_vccnz .Lcv5_2_122
	v_lshl_add_u64 v[36:37], v[18:19], 0, s[18:19]
	global_load_dword v217, v[36:37], off nt
.Lcv5_2_122:
	s_and_b64 vcc, exec, s[4:5]
	s_cbranch_vccnz .Lcv5_2_124
	v_lshl_add_u64 v[38:39], v[16:17], 0, s[18:19]
	global_load_dword v218, v[38:39], off nt
.Lcv5_2_124:
	s_and_b64 vcc, exec, s[4:5]
	s_cbranch_vccnz .Lcv5_2_126
	v_lshl_add_u64 v[36:37], v[14:15], 0, s[18:19]
	global_load_dword v219, v[36:37], off nt
.Lcv5_2_126:
	s_and_b64 vcc, exec, s[4:5]
	s_cbranch_vccnz .Lcv5_2_128
	v_lshl_add_u64 v[38:39], v[12:13], 0, s[18:19]
	global_load_dword v220, v[38:39], off nt
.Lcv5_2_128:
	s_and_b64 vcc, exec, s[4:5]
	s_cbranch_vccnz .Lcv5_2_130
	v_lshl_add_u64 v[36:37], v[10:11], 0, s[18:19]
	global_load_dword v221, v[36:37], off nt
.Lcv5_2_130:
	s_and_b64 vcc, exec, s[4:5]
	s_cbranch_vccnz .Lcv5_2_132
	v_lshl_add_u64 v[38:39], v[8:9], 0, s[18:19]
	global_load_dword v222, v[38:39], off nt
.Lcv5_2_132:
	s_and_b64 vcc, exec, s[4:5]
	s_cbranch_vccnz .Lcv5_2_end
	v_lshl_add_u64 v[36:37], v[6:7], 0, s[18:19]
	global_load_dword v223, v[36:37], off nt
.Lcv5_2_end:
	s_add_u32 s18, s18, 0x58000
	s_addc_u32 s19, s19, 0
	s_and_b64 vcc, exec, s[4:5]
	s_cbranch_vccnz .Lcv5_3_120
	v_lshl_add_u64 v[38:39], v[20:21], 0, s[18:19]
	global_load_dword v224, v[38:39], off nt
.Lcv5_3_120:
	s_and_b64 vcc, exec, s[4:5]
	s_cbranch_vccnz .Lcv5_3_122
	v_lshl_add_u64 v[36:37], v[18:19], 0, s[18:19]
	global_load_dword v225, v[36:37], off nt
.Lcv5_3_122:
	s_and_b64 vcc, exec, s[4:5]
	s_cbranch_vccnz .Lcv5_3_124
	v_lshl_add_u64 v[38:39], v[16:17], 0, s[18:19]
	global_load_dword v226, v[38:39], off nt
.Lcv5_3_124:
	s_and_b64 vcc, exec, s[4:5]
	s_cbranch_vccnz .Lcv5_3_126
	v_lshl_add_u64 v[36:37], v[14:15], 0, s[18:19]
	global_load_dword v227, v[36:37], off nt
.Lcv5_3_126:
	s_and_b64 vcc, exec, s[4:5]
	s_cbranch_vccnz .Lcv5_3_128
	v_lshl_add_u64 v[38:39], v[12:13], 0, s[18:19]
	global_load_dword v228, v[38:39], off nt
.Lcv5_3_128:
	s_and_b64 vcc, exec, s[4:5]
	s_cbranch_vccnz .Lcv5_3_130
	v_lshl_add_u64 v[36:37], v[10:11], 0, s[18:19]
	global_load_dword v229, v[36:37], off nt
.Lcv5_3_130:
	s_and_b64 vcc, exec, s[4:5]
	s_cbranch_vccnz .Lcv5_3_132
	v_lshl_add_u64 v[38:39], v[8:9], 0, s[18:19]
	global_load_dword v230, v[38:39], off nt
.Lcv5_3_132:
	s_and_b64 vcc, exec, s[4:5]
	s_cbranch_vccnz .Lcv5_3_end
	v_lshl_add_u64 v[36:37], v[6:7], 0, s[18:19]
	global_load_dword v231, v[36:37], off nt
.Lcv5_3_end:
	s_add_u32 s18, s18, 0x58000
	s_addc_u32 s19, s19, 0
	s_waitcnt vmcnt(0)
	ds_write_b32 v2, v200
	ds_write_b32 v2, v201 offset:264
	ds_write_b32 v2, v202 offset:528
	ds_write_b32 v2, v203 offset:792
	ds_write_b32 v2, v204 offset:1056
	ds_write_b32 v2, v205 offset:1320
	ds_write_b32 v2, v206 offset:1584
	ds_write_b32 v2, v207 offset:1848
	ds_write_b32 v2, v208 offset:2112
	ds_write_b32 v2, v209 offset:2376
	ds_write_b32 v2, v210 offset:2640
	ds_write_b32 v2, v211 offset:2904
	ds_write_b32 v2, v212 offset:3168
	ds_write_b32 v2, v213 offset:3432
	ds_write_b32 v2, v214 offset:3696
	ds_write_b32 v2, v215 offset:3960
	ds_write_b32 v2, v216 offset:4224
	ds_write_b32 v2, v217 offset:4488
	ds_write_b32 v2, v218 offset:4752
	ds_write_b32 v2, v219 offset:5016
	ds_write_b32 v2, v220 offset:5280
	ds_write_b32 v2, v221 offset:5544
	ds_write_b32 v2, v222 offset:5808
	ds_write_b32 v2, v223 offset:6072
	ds_write_b32 v2, v224 offset:6336
	ds_write_b32 v2, v225 offset:6600
	ds_write_b32 v2, v226 offset:6864
	ds_write_b32 v2, v227 offset:7128
	ds_write_b32 v2, v228 offset:7392
	ds_write_b32 v2, v229 offset:7656
	ds_write_b32 v2, v230 offset:7920
	ds_write_b32 v2, v231 offset:8184
	s_branch .LBB0_115

.LBB0_1442:
	v_mov_b32_e32 v200, 0
	v_mov_b32_e32 v201, 0
	v_mov_b32_e32 v202, 0
	v_mov_b32_e32 v203, 0
	v_mov_b32_e32 v204, 0
	v_mov_b32_e32 v205, 0
	v_mov_b32_e32 v206, 0
	v_mov_b32_e32 v207, 0
	v_mov_b32_e32 v208, 0
	v_mov_b32_e32 v209, 0
	v_mov_b32_e32 v210, 0
	v_mov_b32_e32 v211, 0
	v_mov_b32_e32 v212, 0
	v_mov_b32_e32 v213, 0
	v_mov_b32_e32 v214, 0
	v_mov_b32_e32 v215, 0
	v_mov_b32_e32 v216, 0
	v_mov_b32_e32 v217, 0
	v_mov_b32_e32 v218, 0
	v_mov_b32_e32 v219, 0
	v_mov_b32_e32 v220, 0
	v_mov_b32_e32 v221, 0
	v_mov_b32_e32 v222, 0
	v_mov_b32_e32 v223, 0
	v_mov_b32_e32 v224, 0
	v_mov_b32_e32 v225, 0
	v_mov_b32_e32 v226, 0
	v_mov_b32_e32 v227, 0
	v_mov_b32_e32 v228, 0
	v_mov_b32_e32 v229, 0
	v_mov_b32_e32 v230, 0
	v_mov_b32_e32 v231, 0
	s_and_saveexec_b64 s[18:19], vcc
	s_cbranch_execz .Lcv7_0_1444
	v_add_u32_e32 v10, s7, v0
	v_mad_i64_i32 v[10:11], s[20:21], v10, s4, v[4:5]
	global_load_dword v200, v[10:11], off nt

.Lcv7_0_end:
	s_or_b64 exec, exec, s[18:19]
	s_add_i32 s7, s7, 16
	s_and_saveexec_b64 s[18:19], vcc
	s_cbranch_execz .Lcv7_1_1444
	v_add_u32_e32 v10, s7, v0
	v_mad_i64_i32 v[10:11], s[20:21], v10, s4, v[4:5]
	global_load_dword v208, v[10:11], off nt
.Lcv7_1_1444:
	s_or_b64 exec, exec, s[18:19]
	s_and_saveexec_b64 s[18:19], vcc
	s_cbranch_execz .Lcv7_1_1446
	v_add3_u32 v9, v0, s7, 2
	v_mad_i64_i32 v[10:11], s[20:21], v9, s4, v[4:5]
	global_load_dword v209, v[10:11], off nt
.Lcv7_1_1446:
	s_or_b64 exec, exec, s[18:19]
	s_and_saveexec_b64 s[18:19], vcc
	s_cbranch_execz .Lcv7_1_1448
	v_add3_u32 v10, v0, s7, 4
	v_mad_i64_i32 v[10:11], s[20:21], v10, s4, v[4:5]
	global_load_dword v210, v[10:11], off nt
.Lcv7_1_1448:
	s_or_b64 exec, exec, s[18:19]
	s_and_saveexec_b64 s[18:19], vcc
	s_cbranch_execz .Lcv7_1_1450
	v_add3_u32 v9, v0, s7, 6
	v_mad_i64_i32 v[10:11], s[20:21], v9, s4, v[4:5]
	global_load_dword v211, v[10:11], off nt
.Lcv7_1_1450:
	s_or_b64 exec, exec, s[18:19]
	s_and_saveexec_b64 s[18:19], vcc
	s_cbranch_execz .Lcv7_1_1452
	v_add3_u32 v10, v0, s7, 8
	v_mad_i64_i32 v[10:11], s[20:21], v10, s4, v[4:5]
	global_load_dword v212, v[10:11], off nt
.Lcv7_1_1452:
	s_or_b64 exec, exec, s[18:19]
	s_and_saveexec_b64 s[18:19], vcc
	s_cbranch_execz .Lcv7_1_1454
	v_add3_u32 v9, v0, s7, 10
	v_mad_i64_i32 v[10:11], s[20:21], v9, s4, v[4:5]
	global_load_dword v213, v[10:11], off nt
.Lcv7_1_1454:
	s_or_b64 exec, exec, s[18:19]
	s_and_saveexec_b64 s[18:19], vcc
	s_cbranch_execz .Lcv7_1_1456
	v_add3_u32 v10, v0, s7, 12
	v_mad_i64_i32 v[10:11], s[20:21], v10, s4, v[4:5]
	global_load_dword v214, v[10:11], off nt
.Lcv7_1_1456:
	s_or_b64 exec, exec, s[18:19]
	s_and_saveexec_b64 s[18:19], vcc
	s_cbranch_execz .Lcv7_1_end
	v_add3_u32 v9, v0, s7, 14
	v_mad_i64_i32 v[10:11], s[20:21], v9, s4, v[4:5]
	global_load_dword v215, v[10:11], off nt
.Lcv7_1_end:
	s_or_b64 exec, exec, s[18:19]
	s_add_i32 s7, s7, 16
	s_and_saveexec_b64 s[18:19], vcc
	s_cbranch_execz .Lcv7_2_1444
	v_add_u32_e32 v10, s7, v0
	v_mad_i64_i32 v[10:11], s[20:21], v10, s4, v[4:5]
	global_load_dword v216, v[10:11], off nt
.Lcv7_2_1444:
	s_or_b64 exec, exec, s[18:19]
	s_and_saveexec_b64 s[18:19], vcc
	s_cbranch_execz .Lcv7_2_1446
	v_add3_u32 v9, v0, s7, 2
	v_mad_i64_i32 v[10:11], s[20:21], v9, s4, v[4:5]
	global_load_dword v217, v[10:11], off nt
.Lcv7_2_1446:
	s_or_b64 exec, exec, s[18:19]
	s_and_saveexec_b64 s[18:19], vcc
	s_cbranch_execz .Lcv7_2_1448
	v_add3_u32 v10, v0, s7, 4
	v_mad_i64_i32 v[10:11], s[20:21], v10, s4, v[4:5]
	global_load_dword v218, v[10:11], off nt
.Lcv7_2_1448:
	s_or_b64 exec, exec, s[18:19]
	s_and_saveexec_b64 s[18:19], vcc
	s_cbranch_execz .Lcv7_2_1450
	v_add3_u32 v9, v0, s7, 6
	v_mad_i64_i32 v[10:11], s[20:21], v9, s4, v[4:5]
	global_load_dword v219, v[10:11], off nt
.Lcv7_2_1450:
	s_or_b64 exec, exec, s[18:19]
	s_and_saveexec_b64 s[18:19], vcc
	s_cbranch_execz .Lcv7_2_1452
	v_add3_u32 v10, v0, s7, 8
	v_mad_i64_i32 v[10:11], s[20:21], v10, s4, v[4:5]
	global_load_dword v220, v[10:11], off nt
.Lcv7_2_1452:
	s_or_b64 exec, exec, s[18:19]
	s_and_saveexec_b64 s[18:19], vcc
	s_cbranch_execz .Lcv7_2_1454
	v_add3_u32 v9, v0, s7, 10
	v_mad_i64_i32 v[10:11], s[20:21], v9, s4, v[4:5]
	global_load_dword v221, v[10:11], off nt
.Lcv7_2_1454:
	s_or_b64 exec, exec, s[18:19]
	s_and_saveexec_b64 s[18:19], vcc
	s_cbranch_execz .Lcv7_2_1456
	v_add3_u32 v10, v0, s7, 12
	v_mad_i64_i32 v[10:11], s[20:21], v10, s4, v[4:5]
	global_load_dword v222, v[10:11], off nt
.Lcv7_2_1456:
	s_or_b64 exec, exec, s[18:19]
	s_and_saveexec_b64 s[18:19], vcc
	s_cbranch_execz .Lcv7_2_end
	v_add3_u32 v9, v0, s7, 14
	v_mad_i64_i32 v[10:11], s[20:21], v9, s4, v[4:5]
	global_load_dword v223, v[10:11], off nt
.Lcv7_2_end:
	s_or_b64 exec, exec, s[18:19]
	s_add_i32 s7, s7, 16
	s_and_saveexec_b64 s[18:19], vcc
	s_cbranch_execz .Lcv7_3_1444
	v_add_u32_e32 v10, s7, v0
	v_mad_i64_i32 v[10:11], s[20:21], v10, s4, v[4:5]
	global_load_dword v224, v[10:11], off nt
.Lcv7_3_1444:
	s_or_b64 exec, exec, s[18:19]
	s_and_saveexec_b64 s[18:19], vcc
	s_cbranch_execz .Lcv7_3_1446
	v_add3_u32 v9, v0, s7, 2
	v_mad_i64_i32 v[10:11], s[20:21], v9, s4, v[4:5]
	global_load_dword v225, v[10:11], off nt
.Lcv7_3_1446:
	s_or_b64 exec, exec, s[18:19]
	s_and_saveexec_b64 s[18:19], vcc
	s_cbranch_execz .Lcv7_3_1448
	v_add3_u32 v10, v0, s7, 4
	v_mad_i64_i32 v[10:11], s[20:21], v10, s4, v[4:5]
	global_load_dword v226, v[10:11], off nt
.Lcv7_3_1448:
	s_or_b64 exec, exec, s[18:19]
	s_and_saveexec_b64 s[18:19], vcc
	s_cbranch_execz .Lcv7_3_1450
	v_add3_u32 v9, v0, s7, 6
	v_mad_i64_i32 v[10:11], s[20:21], v9, s4, v[4:5]
	global_load_dword v227, v[10:11], off nt
.Lcv7_3_1450:
	s_or_b64 exec, exec, s[18:19]
	s_and_saveexec_b64 s[18:19], vcc
	s_cbranch_execz .Lcv7_3_1452
	v_add3_u32 v10, v0, s7, 8
	v_mad_i64_i32 v[10:11], s[20:21], v10, s4, v[4:5]
	global_load_dword v228, v[10:11], off nt
.Lcv7_3_1452:
	s_or_b64 exec, exec, s[18:19]
	s_and_saveexec_b64 s[18:19], vcc
	s_cbranch_execz .Lcv7_3_1454
	v_add3_u32 v9, v0, s7, 10
	v_mad_i64_i32 v[10:11], s[20:21], v9, s4, v[4:5]
	global_load_dword v229, v[10:11], off nt
.Lcv7_3_1454:
	s_or_b64 exec, exec, s[18:19]
	s_and_saveexec_b64 s[18:19], vcc
	s_cbranch_execz .Lcv7_3_1456
	v_add3_u32 v10, v0, s7, 12
	v_mad_i64_i32 v[10:11], s[20:21], v10, s4, v[4:5]
	global_load_dword v230, v[10:11], off nt
.Lcv7_3_1456:
	s_or_b64 exec, exec, s[18:19]
	s_and_saveexec_b64 s[18:19], vcc
	s_cbranch_execz .Lcv7_3_end
	v_add3_u32 v9, v0, s7, 14
	v_mad_i64_i32 v[10:11], s[20:21], v9, s4, v[4:5]
	global_load_dword v231, v[10:11], off nt
.Lcv7_3_end:
	s_or_b64 exec, exec, s[18:19]
	s_add_i32 s7, s7, 16
	s_waitcnt vmcnt(0)
	ds_write_b32 v8, v200
	ds_write_b32 v8, v201 offset:264
	ds_write_b32 v8, v202 offset:528
	ds_write_b32 v8, v203 offset:792
	ds_write_b32 v8, v204 offset:1056
	ds_write_b32 v8, v205 offset:1320
	ds_write_b32 v8, v206 offset:1584
	ds_write_b32 v8, v207 offset:1848
	ds_write_b32 v8, v208 offset:2112
	ds_write_b32 v8, v209 offset:2376
	ds_write_b32 v8, v210 offset:2640
	ds_write_b32 v8, v211 offset:2904
	ds_write_b32 v8, v212 offset:3168
	ds_write_b32 v8, v213 offset:3432
	ds_write_b32 v8, v214 offset:3696
	ds_write_b32 v8, v215 offset:3960
	ds_write_b32 v8, v216 offset:4224
	ds_write_b32 v8, v217 offset:4488
	ds_write_b32 v8, v218 offset:4752
	ds_write_b32 v8, v219 offset:5016
	ds_write_b32 v8, v220 offset:5280
	ds_write_b32 v8, v221 offset:5544
	ds_write_b32 v8, v222 offset:5808
	ds_write_b32 v8, v223 offset:6072
	ds_write_b32 v8, v224 offset:6336
	ds_write_b32 v8, v225 offset:6600
	ds_write_b32 v8, v226 offset:6864
	ds_write_b32 v8, v227 offset:7128
	ds_write_b32 v8, v228 offset:7392
	ds_write_b32 v8, v229 offset:7656
	ds_write_b32 v8, v230 offset:7920
	ds_write_b32 v8, v231 offset:8184
	s_branch .LBB0_1437

.LBB0_1463:
	v_mov_b32_e32 v200, 0
	v_mov_b32_e32 v201, 0
	v_mov_b32_e32 v202, 0
	v_mov_b32_e32 v203, 0
	v_mov_b32_e32 v204, 0
	v_mov_b32_e32 v205, 0
	v_mov_b32_e32 v206, 0
	v_mov_b32_e32 v207, 0
	v_mov_b32_e32 v208, 0
	v_mov_b32_e32 v209, 0
	v_mov_b32_e32 v210, 0
	v_mov_b32_e32 v211, 0
	v_mov_b32_e32 v212, 0
	v_mov_b32_e32 v213, 0
	v_mov_b32_e32 v214, 0
	v_mov_b32_e32 v215, 0
	v_mov_b32_e32 v216, 0
	v_mov_b32_e32 v217, 0
	v_mov_b32_e32 v218, 0
	v_mov_b32_e32 v219, 0
	v_mov_b32_e32 v220, 0
	v_mov_b32_e32 v221, 0
	v_mov_b32_e32 v222, 0
	v_mov_b32_e32 v223, 0
	v_mov_b32_e32 v224, 0
	v_mov_b32_e32 v225, 0
	v_mov_b32_e32 v226, 0
	v_mov_b32_e32 v227, 0
	v_mov_b32_e32 v228, 0
	v_mov_b32_e32 v229, 0
	v_mov_b32_e32 v230, 0
	v_mov_b32_e32 v231, 0
	s_and_saveexec_b64 s[18:19], vcc
	s_cbranch_execz .Lcv8_0_1465
	v_add_u32_e32 v10, s6, v0
	v_ashrrev_i32_e32 v11, 31, v10
	v_lshlrev_b64 v[10:11], 12, v[10:11]
	v_lshl_add_u64 v[10:11], v[4:5], 0, v[10:11]
	global_load_dword v200, v[10:11], off nt

.Lcv8_0_end:
	s_or_b64 exec, exec, s[18:19]
	s_add_i32 s6, s6, 16
	s_and_saveexec_b64 s[18:19], vcc
	s_cbranch_execz .Lcv8_1_1465
	v_add_u32_e32 v10, s6, v0
	v_ashrrev_i32_e32 v11, 31, v10
	v_lshlrev_b64 v[10:11], 12, v[10:11]
	v_lshl_add_u64 v[10:11], v[4:5], 0, v[10:11]
	global_load_dword v208, v[10:11], off nt
.Lcv8_1_1465:
	s_or_b64 exec, exec, s[18:19]
	s_and_saveexec_b64 s[18:19], vcc
	s_cbranch_execz .Lcv8_1_1467
	v_add3_u32 v10, v0, s6, 2
	v_ashrrev_i32_e32 v11, 31, v10
	v_lshlrev_b64 v[10:11], 12, v[10:11]
	v_lshl_add_u64 v[10:11], v[4:5], 0, v[10:11]
	global_load_dword v209, v[10:11], off nt
.Lcv8_1_1467:
	s_or_b64 exec, exec, s[18:19]
	s_and_saveexec_b64 s[18:19], vcc
	s_cbranch_execz .Lcv8_1_1469
	v_add3_u32 v10, v0, s6, 4
	v_ashrrev_i32_e32 v11, 31, v10
	v_lshlrev_b64 v[10:11], 12, v[10:11]
	v_lshl_add_u64 v[10:11], v[4:5], 0, v[10:11]
	global_load_dword v210, v[10:11], off nt
.Lcv8_1_1469:
	s_or_b64 exec, exec, s[18:19]
	s_and_saveexec_b64 s[18:19], vcc
	s_cbranch_execz .Lcv8_1_1471
	v_add3_u32 v10, v0, s6, 6
	v_ashrrev_i32_e32 v11, 31, v10
	v_lshlrev_b64 v[10:11], 12, v[10:11]
	v_lshl_add_u64 v[10:11], v[4:5], 0, v[10:11]
	global_load_dword v211, v[10:11], off nt
.Lcv8_1_1471:
	s_or_b64 exec, exec, s[18:19]
	s_and_saveexec_b64 s[18:19], vcc
	s_cbranch_execz .Lcv8_1_1473
	v_add3_u32 v10, v0, s6, 8
	v_ashrrev_i32_e32 v11, 31, v10
	v_lshlrev_b64 v[10:11], 12, v[10:11]
	v_lshl_add_u64 v[10:11], v[4:5], 0, v[10:11]
	global_load_dword v212, v[10:11], off nt
.Lcv8_1_1473:
	s_or_b64 exec, exec, s[18:19]
	s_and_saveexec_b64 s[18:19], vcc
	s_cbranch_execz .Lcv8_1_1475
	v_add3_u32 v10, v0, s6, 10
	v_ashrrev_i32_e32 v11, 31, v10
	v_lshlrev_b64 v[10:11], 12, v[10:11]
	v_lshl_add_u64 v[10:11], v[4:5], 0, v[10:11]
	global_load_dword v213, v[10:11], off nt
.Lcv8_1_1475:
	s_or_b64 exec, exec, s[18:19]
	s_and_saveexec_b64 s[18:19], vcc
	s_cbranch_execz .Lcv8_1_1477
	v_add3_u32 v10, v0, s6, 12
	v_ashrrev_i32_e32 v11, 31, v10
	v_lshlrev_b64 v[10:11], 12, v[10:11]
	v_lshl_add_u64 v[10:11], v[4:5], 0, v[10:11]
	global_load_dword v214, v[10:11], off nt
.Lcv8_1_1477:
	s_or_b64 exec, exec, s[18:19]
	s_and_saveexec_b64 s[18:19], vcc
	s_cbranch_execz .Lcv8_1_end
	v_add3_u32 v10, v0, s6, 14
	v_ashrrev_i32_e32 v11, 31, v10
	v_lshlrev_b64 v[10:11], 12, v[10:11]
	v_lshl_add_u64 v[10:11], v[4:5], 0, v[10:11]
	global_load_dword v215, v[10:11], off nt
.Lcv8_1_end:
	s_or_b64 exec, exec, s[18:19]
	s_add_i32 s6, s6, 16
	s_and_saveexec_b64 s[18:19], vcc
	s_cbranch_execz .Lcv8_2_1465
	v_add_u32_e32 v10, s6, v0
	v_ashrrev_i32_e32 v11, 31, v10
	v_lshlrev_b64 v[10:11], 12, v[10:11]
	v_lshl_add_u64 v[10:11], v[4:5], 0, v[10:11]
	global_load_dword v216, v[10:11], off nt
.Lcv8_2_1465:
	s_or_b64 exec, exec, s[18:19]
	s_and_saveexec_b64 s[18:19], vcc
	s_cbranch_execz .Lcv8_2_1467
	v_add3_u32 v10, v0, s6, 2
	v_ashrrev_i32_e32 v11, 31, v10
	v_lshlrev_b64 v[10:11], 12, v[10:11]
	v_lshl_add_u64 v[10:11], v[4:5], 0, v[10:11]
	global_load_dword v217, v[10:11], off nt
.Lcv8_2_1467:
	s_or_b64 exec, exec, s[18:19]
	s_and_saveexec_b64 s[18:19], vcc
	s_cbranch_execz .Lcv8_2_1469
	v_add3_u32 v10, v0, s6, 4
	v_ashrrev_i32_e32 v11, 31, v10
	v_lshlrev_b64 v[10:11], 12, v[10:11]
	v_lshl_add_u64 v[10:11], v[4:5], 0, v[10:11]
	global_load_dword v218, v[10:11], off nt
.Lcv8_2_1469:
	s_or_b64 exec, exec, s[18:19]
	s_and_saveexec_b64 s[18:19], vcc
	s_cbranch_execz .Lcv8_2_1471
	v_add3_u32 v10, v0, s6, 6
	v_ashrrev_i32_e32 v11, 31, v10
	v_lshlrev_b64 v[10:11], 12, v[10:11]
	v_lshl_add_u64 v[10:11], v[4:5], 0, v[10:11]
	global_load_dword v219, v[10:11], off nt
.Lcv8_2_1471:
	s_or_b64 exec, exec, s[18:19]
	s_and_saveexec_b64 s[18:19], vcc
	s_cbranch_execz .Lcv8_2_1473
	v_add3_u32 v10, v0, s6, 8
	v_ashrrev_i32_e32 v11, 31, v10
	v_lshlrev_b64 v[10:11], 12, v[10:11]
	v_lshl_add_u64 v[10:11], v[4:5], 0, v[10:11]
	global_load_dword v220, v[10:11], off nt
.Lcv8_2_1473:
	s_or_b64 exec, exec, s[18:19]
	s_and_saveexec_b64 s[18:19], vcc
	s_cbranch_execz .Lcv8_2_1475
	v_add3_u32 v10, v0, s6, 10
	v_ashrrev_i32_e32 v11, 31, v10
	v_lshlrev_b64 v[10:11], 12, v[10:11]
	v_lshl_add_u64 v[10:11], v[4:5], 0, v[10:11]
	global_load_dword v221, v[10:11], off nt
.Lcv8_2_1475:
	s_or_b64 exec, exec, s[18:19]
	s_and_saveexec_b64 s[18:19], vcc
	s_cbranch_execz .Lcv8_2_1477
	v_add3_u32 v10, v0, s6, 12
	v_ashrrev_i32_e32 v11, 31, v10
	v_lshlrev_b64 v[10:11], 12, v[10:11]
	v_lshl_add_u64 v[10:11], v[4:5], 0, v[10:11]
	global_load_dword v222, v[10:11], off nt
.Lcv8_2_1477:
	s_or_b64 exec, exec, s[18:19]
	s_and_saveexec_b64 s[18:19], vcc
	s_cbranch_execz .Lcv8_2_end
	v_add3_u32 v10, v0, s6, 14
	v_ashrrev_i32_e32 v11, 31, v10
	v_lshlrev_b64 v[10:11], 12, v[10:11]
	v_lshl_add_u64 v[10:11], v[4:5], 0, v[10:11]
	global_load_dword v223, v[10:11], off nt
.Lcv8_2_end:
	s_or_b64 exec, exec, s[18:19]
	s_add_i32 s6, s6, 16
	s_and_saveexec_b64 s[18:19], vcc
	s_cbranch_execz .Lcv8_3_1465
	v_add_u32_e32 v10, s6, v0
	v_ashrrev_i32_e32 v11, 31, v10
	v_lshlrev_b64 v[10:11], 12, v[10:11]
	v_lshl_add_u64 v[10:11], v[4:5], 0, v[10:11]
	global_load_dword v224, v[10:11], off nt
.Lcv8_3_1465:
	s_or_b64 exec, exec, s[18:19]
	s_and_saveexec_b64 s[18:19], vcc
	s_cbranch_execz .Lcv8_3_1467
	v_add3_u32 v10, v0, s6, 2
	v_ashrrev_i32_e32 v11, 31, v10
	v_lshlrev_b64 v[10:11], 12, v[10:11]
	v_lshl_add_u64 v[10:11], v[4:5], 0, v[10:11]
	global_load_dword v225, v[10:11], off nt
.Lcv8_3_1467:
	s_or_b64 exec, exec, s[18:19]
	s_and_saveexec_b64 s[18:19], vcc
	s_cbranch_execz .Lcv8_3_1469
	v_add3_u32 v10, v0, s6, 4
	v_ashrrev_i32_e32 v11, 31, v10
	v_lshlrev_b64 v[10:11], 12, v[10:11]
	v_lshl_add_u64 v[10:11], v[4:5], 0, v[10:11]
	global_load_dword v226, v[10:11], off nt
.Lcv8_3_1469:
	s_or_b64 exec, exec, s[18:19]
	s_and_saveexec_b64 s[18:19], vcc
	s_cbranch_execz .Lcv8_3_1471
	v_add3_u32 v10, v0, s6, 6
	v_ashrrev_i32_e32 v11, 31, v10
	v_lshlrev_b64 v[10:11], 12, v[10:11]
	v_lshl_add_u64 v[10:11], v[4:5], 0, v[10:11]
	global_load_dword v227, v[10:11], off nt
.Lcv8_3_1471:
	s_or_b64 exec, exec, s[18:19]
	s_and_saveexec_b64 s[18:19], vcc
	s_cbranch_execz .Lcv8_3_1473
	v_add3_u32 v10, v0, s6, 8
	v_ashrrev_i32_e32 v11, 31, v10
	v_lshlrev_b64 v[10:11], 12, v[10:11]
	v_lshl_add_u64 v[10:11], v[4:5], 0, v[10:11]
	global_load_dword v228, v[10:11], off nt
.Lcv8_3_1473:
	s_or_b64 exec, exec, s[18:19]
	s_and_saveexec_b64 s[18:19], vcc
	s_cbranch_execz .Lcv8_3_1475
	v_add3_u32 v10, v0, s6, 10
	v_ashrrev_i32_e32 v11, 31, v10
	v_lshlrev_b64 v[10:11], 12, v[10:11]
	v_lshl_add_u64 v[10:11], v[4:5], 0, v[10:11]
	global_load_dword v229, v[10:11], off nt
.Lcv8_3_1475:
	s_or_b64 exec, exec, s[18:19]
	s_and_saveexec_b64 s[18:19], vcc
	s_cbranch_execz .Lcv8_3_1477
	v_add3_u32 v10, v0, s6, 12
	v_ashrrev_i32_e32 v11, 31, v10
	v_lshlrev_b64 v[10:11], 12, v[10:11]
	v_lshl_add_u64 v[10:11], v[4:5], 0, v[10:11]
	global_load_dword v230, v[10:11], off nt
.Lcv8_3_1477:
	s_or_b64 exec, exec, s[18:19]
	s_and_saveexec_b64 s[18:19], vcc
	s_cbranch_execz .Lcv8_3_end
	v_add3_u32 v10, v0, s6, 14
	v_ashrrev_i32_e32 v11, 31, v10
	v_lshlrev_b64 v[10:11], 12, v[10:11]
	v_lshl_add_u64 v[10:11], v[4:5], 0, v[10:11]
	global_load_dword v231, v[10:11], off nt
.Lcv8_3_end:
	s_or_b64 exec, exec, s[18:19]
	s_add_i32 s6, s6, 16
	s_waitcnt vmcnt(0)
	ds_write_b32 v8, v200
	ds_write_b32 v8, v201 offset:264
	ds_write_b32 v8, v202 offset:528
	ds_write_b32 v8, v203 offset:792
	ds_write_b32 v8, v204 offset:1056
	ds_write_b32 v8, v205 offset:1320
	ds_write_b32 v8, v206 offset:1584
	ds_write_b32 v8, v207 offset:1848
	ds_write_b32 v8, v208 offset:2112
	ds_write_b32 v8, v209 offset:2376
	ds_write_b32 v8, v210 offset:2640
	ds_write_b32 v8, v211 offset:2904
	ds_write_b32 v8, v212 offset:3168
	ds_write_b32 v8, v213 offset:3432
	ds_write_b32 v8, v214 offset:3696
	ds_write_b32 v8, v215 offset:3960
	ds_write_b32 v8, v216 offset:4224
	ds_write_b32 v8, v217 offset:4488
	ds_write_b32 v8, v218 offset:4752
	ds_write_b32 v8, v219 offset:5016
	ds_write_b32 v8, v220 offset:5280
	ds_write_b32 v8, v221 offset:5544
	ds_write_b32 v8, v222 offset:5808
	ds_write_b32 v8, v223 offset:6072
	ds_write_b32 v8, v224 offset:6336
	ds_write_b32 v8, v225 offset:6600
	ds_write_b32 v8, v226 offset:6864
	ds_write_b32 v8, v227 offset:7128
	ds_write_b32 v8, v228 offset:7392
	ds_write_b32 v8, v229 offset:7656
	ds_write_b32 v8, v230 offset:7920
	ds_write_b32 v8, v231 offset:8184
	s_branch .LBB0_1460

.LBB0_1484:
	v_mov_b32_e32 v200, 0
	v_mov_b32_e32 v201, 0
	v_mov_b32_e32 v202, 0
	v_mov_b32_e32 v203, 0
	v_mov_b32_e32 v204, 0
	v_mov_b32_e32 v205, 0
	v_mov_b32_e32 v206, 0
	v_mov_b32_e32 v207, 0
	v_mov_b32_e32 v208, 0
	v_mov_b32_e32 v209, 0
	v_mov_b32_e32 v210, 0
	v_mov_b32_e32 v211, 0
	v_mov_b32_e32 v212, 0
	v_mov_b32_e32 v213, 0
	v_mov_b32_e32 v214, 0
	v_mov_b32_e32 v215, 0
	v_mov_b32_e32 v216, 0
	v_mov_b32_e32 v217, 0
	v_mov_b32_e32 v218, 0
	v_mov_b32_e32 v219, 0
	v_mov_b32_e32 v220, 0
	v_mov_b32_e32 v221, 0
	v_mov_b32_e32 v222, 0
	v_mov_b32_e32 v223, 0
	v_mov_b32_e32 v224, 0
	v_mov_b32_e32 v225, 0
	v_mov_b32_e32 v226, 0
	v_mov_b32_e32 v227, 0
	v_mov_b32_e32 v228, 0
	v_mov_b32_e32 v229, 0
	v_mov_b32_e32 v230, 0
	v_mov_b32_e32 v231, 0
	s_and_b64 vcc, exec, s[8:9]
	s_cbranch_vccnz .Lcv9_0_1486
	v_lshl_add_u64 v[34:35], v[18:19], 0, s[20:21]
	global_load_dword v200, v[34:35], off nt

.Lcv9_0_end:
	s_add_u32 s20, s20, 0x58000
	s_addc_u32 s21, s21, 0
	s_and_b64 vcc, exec, s[8:9]
	s_cbranch_vccnz .Lcv9_1_1486
	v_lshl_add_u64 v[34:35], v[18:19], 0, s[20:21]
	global_load_dword v208, v[34:35], off nt
.Lcv9_1_1486:
	s_and_b64 vcc, exec, s[8:9]
	s_cbranch_vccnz .Lcv9_1_1488
	v_lshl_add_u64 v[34:35], v[16:17], 0, s[20:21]
	global_load_dword v209, v[34:35], off nt
.Lcv9_1_1488:
	s_and_b64 vcc, exec, s[8:9]
	s_cbranch_vccnz .Lcv9_1_1490
	v_lshl_add_u64 v[34:35], v[14:15], 0, s[20:21]
	global_load_dword v210, v[34:35], off nt
.Lcv9_1_1490:
	s_and_b64 vcc, exec, s[8:9]
	s_cbranch_vccnz .Lcv9_1_1492
	v_lshl_add_u64 v[34:35], v[12:13], 0, s[20:21]
	global_load_dword v211, v[34:35], off nt
.Lcv9_1_1492:
	s_and_b64 vcc, exec, s[8:9]
	s_cbranch_vccnz .Lcv9_1_1494
	v_lshl_add_u64 v[34:35], v[10:11], 0, s[20:21]
	global_load_dword v212, v[34:35], off nt
.Lcv9_1_1494:
	s_and_b64 vcc, exec, s[8:9]
	s_cbranch_vccnz .Lcv9_1_1496
	v_lshl_add_u64 v[34:35], v[8:9], 0, s[20:21]
	global_load_dword v213, v[34:35], off nt
.Lcv9_1_1496:
	s_and_b64 vcc, exec, s[8:9]
	s_cbranch_vccnz .Lcv9_1_1498
	v_lshl_add_u64 v[34:35], v[6:7], 0, s[20:21]
	global_load_dword v214, v[34:35], off nt
.Lcv9_1_1498:
	s_and_b64 vcc, exec, s[8:9]
	s_cbranch_vccnz .Lcv9_1_end
	v_lshl_add_u64 v[34:35], v[4:5], 0, s[20:21]
	global_load_dword v215, v[34:35], off nt
.Lcv9_1_end:
	s_add_u32 s20, s20, 0x58000
	s_addc_u32 s21, s21, 0
	s_and_b64 vcc, exec, s[8:9]
	s_cbranch_vccnz .Lcv9_2_1486
	v_lshl_add_u64 v[34:35], v[18:19], 0, s[20:21]
	global_load_dword v216, v[34:35], off nt
.Lcv9_2_1486:
	s_and_b64 vcc, exec, s[8:9]
	s_cbranch_vccnz .Lcv9_2_1488
	v_lshl_add_u64 v[34:35], v[16:17], 0, s[20:21]
	global_load_dword v217, v[34:35], off nt
.Lcv9_2_1488:
	s_and_b64 vcc, exec, s[8:9]
	s_cbranch_vccnz .Lcv9_2_1490
	v_lshl_add_u64 v[34:35], v[14:15], 0, s[20:21]
	global_load_dword v218, v[34:35], off nt
.Lcv9_2_1490:
	s_and_b64 vcc, exec, s[8:9]
	s_cbranch_vccnz .Lcv9_2_1492
	v_lshl_add_u64 v[34:35], v[12:13], 0, s[20:21]
	global_load_dword v219, v[34:35], off nt
.Lcv9_2_1492:
	s_and_b64 vcc, exec, s[8:9]
	s_cbranch_vccnz .Lcv9_2_1494
	v_lshl_add_u64 v[34:35], v[10:11], 0, s[20:21]
	global_load_dword v220, v[34:35], off nt
.Lcv9_2_1494:
	s_and_b64 vcc, exec, s[8:9]
	s_cbranch_vccnz .Lcv9_2_1496
	v_lshl_add_u64 v[34:35], v[8:9], 0, s[20:21]
	global_load_dword v221, v[34:35], off nt
.Lcv9_2_1496:
	s_and_b64 vcc, exec, s[8:9]
	s_cbranch_vccnz .Lcv9_2_1498
	v_lshl_add_u64 v[34:35], v[6:7], 0, s[20:21]
	global_load_dword v222, v[34:35], off nt
.Lcv9_2_1498:
	s_and_b64 vcc, exec, s[8:9]
	s_cbranch_vccnz .Lcv9_2_end
	v_lshl_add_u64 v[34:35], v[4:5], 0, s[20:21]
	global_load_dword v223, v[34:35], off nt
.Lcv9_2_end:
	s_add_u32 s20, s20, 0x58000
	s_addc_u32 s21, s21, 0
	s_and_b64 vcc, exec, s[8:9]
	s_cbranch_vccnz .Lcv9_3_1486
	v_lshl_add_u64 v[34:35], v[18:19], 0, s[20:21]
	global_load_dword v224, v[34:35], off nt
.Lcv9_3_1486:
	s_and_b64 vcc, exec, s[8:9]
	s_cbranch_vccnz .Lcv9_3_1488
	v_lshl_add_u64 v[34:35], v[16:17], 0, s[20:21]
	global_load_dword v225, v[34:35], off nt
.Lcv9_3_1488:
	s_and_b64 vcc, exec, s[8:9]
	s_cbranch_vccnz .Lcv9_3_1490
	v_lshl_add_u64 v[34:35], v[14:15], 0, s[20:21]
	global_load_dword v226, v[34:35], off nt
.Lcv9_3_1490:
	s_and_b64 vcc, exec, s[8:9]
	s_cbranch_vccnz .Lcv9_3_1492
	v_lshl_add_u64 v[34:35], v[12:13], 0, s[20:21]
	global_load_dword v227, v[34:35], off nt
.Lcv9_3_1492:
	s_and_b64 vcc, exec, s[8:9]
	s_cbranch_vccnz .Lcv9_3_1494
	v_lshl_add_u64 v[34:35], v[10:11], 0, s[20:21]
	global_load_dword v228, v[34:35], off nt
.Lcv9_3_1494:
	s_and_b64 vcc, exec, s[8:9]
	s_cbranch_vccnz .Lcv9_3_1496
	v_lshl_add_u64 v[34:35], v[8:9], 0, s[20:21]
	global_load_dword v229, v[34:35], off nt
.Lcv9_3_1496:
	s_and_b64 vcc, exec, s[8:9]
	s_cbranch_vccnz .Lcv9_3_1498
	v_lshl_add_u64 v[34:35], v[6:7], 0, s[20:21]
	global_load_dword v230, v[34:35], off nt
.Lcv9_3_1498:
	s_and_b64 vcc, exec, s[8:9]
	s_cbranch_vccnz .Lcv9_3_end
	v_lshl_add_u64 v[34:35], v[4:5], 0, s[20:21]
	global_load_dword v231, v[34:35], off nt
.Lcv9_3_end:
	s_add_u32 s20, s20, 0x58000
	s_addc_u32 s21, s21, 0
	s_waitcnt vmcnt(0)
	ds_write_b32 v0, v200
	ds_write_b32 v0, v201 offset:264
	ds_write_b32 v0, v202 offset:528
	ds_write_b32 v0, v203 offset:792
	ds_write_b32 v0, v204 offset:1056
	ds_write_b32 v0, v205 offset:1320
	ds_write_b32 v0, v206 offset:1584
	ds_write_b32 v0, v207 offset:1848
	ds_write_b32 v0, v208 offset:2112
	ds_write_b32 v0, v209 offset:2376
	ds_write_b32 v0, v210 offset:2640
	ds_write_b32 v0, v211 offset:2904
	ds_write_b32 v0, v212 offset:3168
	ds_write_b32 v0, v213 offset:3432
	ds_write_b32 v0, v214 offset:3696
	ds_write_b32 v0, v215 offset:3960
	ds_write_b32 v0, v216 offset:4224
	ds_write_b32 v0, v217 offset:4488
	ds_write_b32 v0, v218 offset:4752
	ds_write_b32 v0, v219 offset:5016
	ds_write_b32 v0, v220 offset:5280
	ds_write_b32 v0, v221 offset:5544
	ds_write_b32 v0, v222 offset:5808
	ds_write_b32 v0, v223 offset:6072
	ds_write_b32 v0, v224 offset:6336
	ds_write_b32 v0, v225 offset:6600
	ds_write_b32 v0, v226 offset:6864
	ds_write_b32 v0, v227 offset:7128
	ds_write_b32 v0, v228 offset:7392
	ds_write_b32 v0, v229 offset:7656
	ds_write_b32 v0, v230 offset:7920
	ds_write_b32 v0, v231 offset:8184
	s_branch .LBB0_1481

.LBB0_1505:
	v_mov_b32_e32 v200, 0
	v_mov_b32_e32 v201, 0
	v_mov_b32_e32 v202, 0
	v_mov_b32_e32 v203, 0
	v_mov_b32_e32 v204, 0
	v_mov_b32_e32 v205, 0
	v_mov_b32_e32 v206, 0
	v_mov_b32_e32 v207, 0
	v_mov_b32_e32 v208, 0
	v_mov_b32_e32 v209, 0
	v_mov_b32_e32 v210, 0
	v_mov_b32_e32 v211, 0
	v_mov_b32_e32 v212, 0
	v_mov_b32_e32 v213, 0
	v_mov_b32_e32 v214, 0
	v_mov_b32_e32 v215, 0
	v_mov_b32_e32 v216, 0
	v_mov_b32_e32 v217, 0
	v_mov_b32_e32 v218, 0
	v_mov_b32_e32 v219, 0
	v_mov_b32_e32 v220, 0
	v_mov_b32_e32 v221, 0
	v_mov_b32_e32 v222, 0
	v_mov_b32_e32 v223, 0
	v_mov_b32_e32 v224, 0
	v_mov_b32_e32 v225, 0
	v_mov_b32_e32 v226, 0
	v_mov_b32_e32 v227, 0
	v_mov_b32_e32 v228, 0
	v_mov_b32_e32 v229, 0
	v_mov_b32_e32 v230, 0
	v_mov_b32_e32 v231, 0
	s_and_saveexec_b64 s[14:15], vcc
	s_cbranch_execz .Lcv10_0_1507
	v_add_u32_e32 v10, s4, v0
	v_ashrrev_i32_e32 v11, 31, v10
	v_lshlrev_b64 v[10:11], 12, v[10:11]
	v_lshl_add_u64 v[10:11], v[4:5], 0, v[10:11]
	global_load_dword v200, v[10:11], off nt

.Lcv10_0_end:
	s_or_b64 exec, exec, s[14:15]
	s_add_i32 s4, s4, 16
	s_and_saveexec_b64 s[14:15], vcc
	s_cbranch_execz .Lcv10_1_1507
	v_add_u32_e32 v10, s4, v0
	v_ashrrev_i32_e32 v11, 31, v10
	v_lshlrev_b64 v[10:11], 12, v[10:11]
	v_lshl_add_u64 v[10:11], v[4:5], 0, v[10:11]
	global_load_dword v208, v[10:11], off nt
.Lcv10_1_1507:
	s_or_b64 exec, exec, s[14:15]
	s_and_saveexec_b64 s[14:15], vcc
	s_cbranch_execz .Lcv10_1_1509
	v_add3_u32 v10, v0, s4, 2
	v_ashrrev_i32_e32 v11, 31, v10
	v_lshlrev_b64 v[10:11], 12, v[10:11]
	v_lshl_add_u64 v[10:11], v[4:5], 0, v[10:11]
	global_load_dword v209, v[10:11], off nt
.Lcv10_1_1509:
	s_or_b64 exec, exec, s[14:15]
	s_and_saveexec_b64 s[14:15], vcc
	s_cbranch_execz .Lcv10_1_1511
	v_add3_u32 v10, v0, s4, 4
	v_ashrrev_i32_e32 v11, 31, v10
	v_lshlrev_b64 v[10:11], 12, v[10:11]
	v_lshl_add_u64 v[10:11], v[4:5], 0, v[10:11]
	global_load_dword v210, v[10:11], off nt
.Lcv10_1_1511:
	s_or_b64 exec, exec, s[14:15]
	s_and_saveexec_b64 s[14:15], vcc
	s_cbranch_execz .Lcv10_1_1513
	v_add3_u32 v10, v0, s4, 6
	v_ashrrev_i32_e32 v11, 31, v10
	v_lshlrev_b64 v[10:11], 12, v[10:11]
	v_lshl_add_u64 v[10:11], v[4:5], 0, v[10:11]
	global_load_dword v211, v[10:11], off nt
.Lcv10_1_1513:
	s_or_b64 exec, exec, s[14:15]
	s_and_saveexec_b64 s[14:15], vcc
	s_cbranch_execz .Lcv10_1_1515
	v_add3_u32 v10, v0, s4, 8
	v_ashrrev_i32_e32 v11, 31, v10
	v_lshlrev_b64 v[10:11], 12, v[10:11]
	v_lshl_add_u64 v[10:11], v[4:5], 0, v[10:11]
	global_load_dword v212, v[10:11], off nt
.Lcv10_1_1515:
	s_or_b64 exec, exec, s[14:15]
	s_and_saveexec_b64 s[14:15], vcc
	s_cbranch_execz .Lcv10_1_1517
	v_add3_u32 v10, v0, s4, 10
	v_ashrrev_i32_e32 v11, 31, v10
	v_lshlrev_b64 v[10:11], 12, v[10:11]
	v_lshl_add_u64 v[10:11], v[4:5], 0, v[10:11]
	global_load_dword v213, v[10:11], off nt
.Lcv10_1_1517:
	s_or_b64 exec, exec, s[14:15]
	s_and_saveexec_b64 s[14:15], vcc
	s_cbranch_execz .Lcv10_1_1519
	v_add3_u32 v10, v0, s4, 12
	v_ashrrev_i32_e32 v11, 31, v10
	v_lshlrev_b64 v[10:11], 12, v[10:11]
	v_lshl_add_u64 v[10:11], v[4:5], 0, v[10:11]
	global_load_dword v214, v[10:11], off nt
.Lcv10_1_1519:
	s_or_b64 exec, exec, s[14:15]
	s_and_saveexec_b64 s[14:15], vcc
	s_cbranch_execz .Lcv10_1_end
	v_add3_u32 v10, v0, s4, 14
	v_ashrrev_i32_e32 v11, 31, v10
	v_lshlrev_b64 v[10:11], 12, v[10:11]
	v_lshl_add_u64 v[10:11], v[4:5], 0, v[10:11]
	global_load_dword v215, v[10:11], off nt
.Lcv10_1_end:
	s_or_b64 exec, exec, s[14:15]
	s_add_i32 s4, s4, 16
	s_and_saveexec_b64 s[14:15], vcc
	s_cbranch_execz .Lcv10_2_1507
	v_add_u32_e32 v10, s4, v0
	v_ashrrev_i32_e32 v11, 31, v10
	v_lshlrev_b64 v[10:11], 12, v[10:11]
	v_lshl_add_u64 v[10:11], v[4:5], 0, v[10:11]
	global_load_dword v216, v[10:11], off nt
.Lcv10_2_1507:
	s_or_b64 exec, exec, s[14:15]
	s_and_saveexec_b64 s[14:15], vcc
	s_cbranch_execz .Lcv10_2_1509
	v_add3_u32 v10, v0, s4, 2
	v_ashrrev_i32_e32 v11, 31, v10
	v_lshlrev_b64 v[10:11], 12, v[10:11]
	v_lshl_add_u64 v[10:11], v[4:5], 0, v[10:11]
	global_load_dword v217, v[10:11], off nt
.Lcv10_2_1509:
	s_or_b64 exec, exec, s[14:15]
	s_and_saveexec_b64 s[14:15], vcc
	s_cbranch_execz .Lcv10_2_1511
	v_add3_u32 v10, v0, s4, 4
	v_ashrrev_i32_e32 v11, 31, v10
	v_lshlrev_b64 v[10:11], 12, v[10:11]
	v_lshl_add_u64 v[10:11], v[4:5], 0, v[10:11]
	global_load_dword v218, v[10:11], off nt
.Lcv10_2_1511:
	s_or_b64 exec, exec, s[14:15]
	s_and_saveexec_b64 s[14:15], vcc
	s_cbranch_execz .Lcv10_2_1513
	v_add3_u32 v10, v0, s4, 6
	v_ashrrev_i32_e32 v11, 31, v10
	v_lshlrev_b64 v[10:11], 12, v[10:11]
	v_lshl_add_u64 v[10:11], v[4:5], 0, v[10:11]
	global_load_dword v219, v[10:11], off nt
.Lcv10_2_1513:
	s_or_b64 exec, exec, s[14:15]
	s_and_saveexec_b64 s[14:15], vcc
	s_cbranch_execz .Lcv10_2_1515
	v_add3_u32 v10, v0, s4, 8
	v_ashrrev_i32_e32 v11, 31, v10
	v_lshlrev_b64 v[10:11], 12, v[10:11]
	v_lshl_add_u64 v[10:11], v[4:5], 0, v[10:11]
	global_load_dword v220, v[10:11], off nt
.Lcv10_2_1515:
	s_or_b64 exec, exec, s[14:15]
	s_and_saveexec_b64 s[14:15], vcc
	s_cbranch_execz .Lcv10_2_1517
	v_add3_u32 v10, v0, s4, 10
	v_ashrrev_i32_e32 v11, 31, v10
	v_lshlrev_b64 v[10:11], 12, v[10:11]
	v_lshl_add_u64 v[10:11], v[4:5], 0, v[10:11]
	global_load_dword v221, v[10:11], off nt
.Lcv10_2_1517:
	s_or_b64 exec, exec, s[14:15]
	s_and_saveexec_b64 s[14:15], vcc
	s_cbranch_execz .Lcv10_2_1519
	v_add3_u32 v10, v0, s4, 12
	v_ashrrev_i32_e32 v11, 31, v10
	v_lshlrev_b64 v[10:11], 12, v[10:11]
	v_lshl_add_u64 v[10:11], v[4:5], 0, v[10:11]
	global_load_dword v222, v[10:11], off nt
.Lcv10_2_1519:
	s_or_b64 exec, exec, s[14:15]
	s_and_saveexec_b64 s[14:15], vcc
	s_cbranch_execz .Lcv10_2_end
	v_add3_u32 v10, v0, s4, 14
	v_ashrrev_i32_e32 v11, 31, v10
	v_lshlrev_b64 v[10:11], 12, v[10:11]
	v_lshl_add_u64 v[10:11], v[4:5], 0, v[10:11]
	global_load_dword v223, v[10:11], off nt
.Lcv10_2_end:
	s_or_b64 exec, exec, s[14:15]
	s_add_i32 s4, s4, 16
	s_and_saveexec_b64 s[14:15], vcc
	s_cbranch_execz .Lcv10_3_1507
	v_add_u32_e32 v10, s4, v0
	v_ashrrev_i32_e32 v11, 31, v10
	v_lshlrev_b64 v[10:11], 12, v[10:11]
	v_lshl_add_u64 v[10:11], v[4:5], 0, v[10:11]
	global_load_dword v224, v[10:11], off nt
.Lcv10_3_1507:
	s_or_b64 exec, exec, s[14:15]
	s_and_saveexec_b64 s[14:15], vcc
	s_cbranch_execz .Lcv10_3_1509
	v_add3_u32 v10, v0, s4, 2
	v_ashrrev_i32_e32 v11, 31, v10
	v_lshlrev_b64 v[10:11], 12, v[10:11]
	v_lshl_add_u64 v[10:11], v[4:5], 0, v[10:11]
	global_load_dword v225, v[10:11], off nt
.Lcv10_3_1509:
	s_or_b64 exec, exec, s[14:15]
	s_and_saveexec_b64 s[14:15], vcc
	s_cbranch_execz .Lcv10_3_1511
	v_add3_u32 v10, v0, s4, 4
	v_ashrrev_i32_e32 v11, 31, v10
	v_lshlrev_b64 v[10:11], 12, v[10:11]
	v_lshl_add_u64 v[10:11], v[4:5], 0, v[10:11]
	global_load_dword v226, v[10:11], off nt
.Lcv10_3_1511:
	s_or_b64 exec, exec, s[14:15]
	s_and_saveexec_b64 s[14:15], vcc
	s_cbranch_execz .Lcv10_3_1513
	v_add3_u32 v10, v0, s4, 6
	v_ashrrev_i32_e32 v11, 31, v10
	v_lshlrev_b64 v[10:11], 12, v[10:11]
	v_lshl_add_u64 v[10:11], v[4:5], 0, v[10:11]
	global_load_dword v227, v[10:11], off nt
.Lcv10_3_1513:
	s_or_b64 exec, exec, s[14:15]
	s_and_saveexec_b64 s[14:15], vcc
	s_cbranch_execz .Lcv10_3_1515
	v_add3_u32 v10, v0, s4, 8
	v_ashrrev_i32_e32 v11, 31, v10
	v_lshlrev_b64 v[10:11], 12, v[10:11]
	v_lshl_add_u64 v[10:11], v[4:5], 0, v[10:11]
	global_load_dword v228, v[10:11], off nt
.Lcv10_3_1515:
	s_or_b64 exec, exec, s[14:15]
	s_and_saveexec_b64 s[14:15], vcc
	s_cbranch_execz .Lcv10_3_1517
	v_add3_u32 v10, v0, s4, 10
	v_ashrrev_i32_e32 v11, 31, v10
	v_lshlrev_b64 v[10:11], 12, v[10:11]
	v_lshl_add_u64 v[10:11], v[4:5], 0, v[10:11]
	global_load_dword v229, v[10:11], off nt
.Lcv10_3_1517:
	s_or_b64 exec, exec, s[14:15]
	s_and_saveexec_b64 s[14:15], vcc
	s_cbranch_execz .Lcv10_3_1519
	v_add3_u32 v10, v0, s4, 12
	v_ashrrev_i32_e32 v11, 31, v10
	v_lshlrev_b64 v[10:11], 12, v[10:11]
	v_lshl_add_u64 v[10:11], v[4:5], 0, v[10:11]
	global_load_dword v230, v[10:11], off nt
.Lcv10_3_1519:
	s_or_b64 exec, exec, s[14:15]
	s_and_saveexec_b64 s[14:15], vcc
	s_cbranch_execz .Lcv10_3_end
	v_add3_u32 v10, v0, s4, 14
	v_ashrrev_i32_e32 v11, 31, v10
	v_lshlrev_b64 v[10:11], 12, v[10:11]
	v_lshl_add_u64 v[10:11], v[4:5], 0, v[10:11]
	global_load_dword v231, v[10:11], off nt
.Lcv10_3_end:
	s_or_b64 exec, exec, s[14:15]
	s_add_i32 s4, s4, 16
	s_waitcnt vmcnt(0)
	ds_write_b32 v8, v200
	ds_write_b32 v8, v201 offset:264
	ds_write_b32 v8, v202 offset:528
	ds_write_b32 v8, v203 offset:792
	ds_write_b32 v8, v204 offset:1056
	ds_write_b32 v8, v205 offset:1320
	ds_write_b32 v8, v206 offset:1584
	ds_write_b32 v8, v207 offset:1848
	ds_write_b32 v8, v208 offset:2112
	ds_write_b32 v8, v209 offset:2376
	ds_write_b32 v8, v210 offset:2640
	ds_write_b32 v8, v211 offset:2904
	ds_write_b32 v8, v212 offset:3168
	ds_write_b32 v8, v213 offset:3432
	ds_write_b32 v8, v214 offset:3696
	ds_write_b32 v8, v215 offset:3960
	ds_write_b32 v8, v216 offset:4224
	ds_write_b32 v8, v217 offset:4488
	ds_write_b32 v8, v218 offset:4752
	ds_write_b32 v8, v219 offset:5016
	ds_write_b32 v8, v220 offset:5280
	ds_write_b32 v8, v221 offset:5544
	ds_write_b32 v8, v222 offset:5808
	ds_write_b32 v8, v223 offset:6072
	ds_write_b32 v8, v224 offset:6336
	ds_write_b32 v8, v225 offset:6600
	ds_write_b32 v8, v226 offset:6864
	ds_write_b32 v8, v227 offset:7128
	ds_write_b32 v8, v228 offset:7392
	ds_write_b32 v8, v229 offset:7656
	ds_write_b32 v8, v230 offset:7920
	ds_write_b32 v8, v231 offset:8184
	s_branch .LBB0_1502

.LBB0_2135:
	v_mov_b32_e32 v200, 0
	v_mov_b32_e32 v201, 0
	v_mov_b32_e32 v202, 0
	v_mov_b32_e32 v203, 0
	v_mov_b32_e32 v204, 0
	v_mov_b32_e32 v205, 0
	v_mov_b32_e32 v206, 0
	v_mov_b32_e32 v207, 0
	v_mov_b32_e32 v208, 0
	v_mov_b32_e32 v209, 0
	v_mov_b32_e32 v210, 0
	v_mov_b32_e32 v211, 0
	v_mov_b32_e32 v212, 0
	v_mov_b32_e32 v213, 0
	v_mov_b32_e32 v214, 0
	v_mov_b32_e32 v215, 0
	v_mov_b32_e32 v216, 0
	v_mov_b32_e32 v217, 0
	v_mov_b32_e32 v218, 0
	v_mov_b32_e32 v219, 0
	v_mov_b32_e32 v220, 0
	v_mov_b32_e32 v221, 0
	v_mov_b32_e32 v222, 0
	v_mov_b32_e32 v223, 0
	v_mov_b32_e32 v224, 0
	v_mov_b32_e32 v225, 0
	v_mov_b32_e32 v226, 0
	v_mov_b32_e32 v227, 0
	v_mov_b32_e32 v228, 0
	v_mov_b32_e32 v229, 0
	v_mov_b32_e32 v230, 0
	v_mov_b32_e32 v231, 0
	s_and_saveexec_b64 s[20:21], vcc
	s_cbranch_execz .Lcv11_0_2137
	v_add_u32_e32 v10, s8, v0
	v_mad_i64_i32 v[10:11], s[22:23], v10, s5, v[4:5]
	global_load_dword v200, v[10:11], off nt

.Lcv11_0_end:
	s_or_b64 exec, exec, s[20:21]
	s_add_i32 s8, s8, 16
	s_and_saveexec_b64 s[20:21], vcc
	s_cbranch_execz .Lcv11_1_2137
	v_add_u32_e32 v10, s8, v0
	v_mad_i64_i32 v[10:11], s[22:23], v10, s5, v[4:5]
	global_load_dword v208, v[10:11], off nt
.Lcv11_1_2137:
	s_or_b64 exec, exec, s[20:21]
	s_and_saveexec_b64 s[20:21], vcc
	s_cbranch_execz .Lcv11_1_2139
	v_add3_u32 v9, v0, s8, 2
	v_mad_i64_i32 v[10:11], s[22:23], v9, s5, v[4:5]
	global_load_dword v209, v[10:11], off nt
.Lcv11_1_2139:
	s_or_b64 exec, exec, s[20:21]
	s_and_saveexec_b64 s[20:21], vcc
	s_cbranch_execz .Lcv11_1_2141
	v_add3_u32 v10, v0, s8, 4
	v_mad_i64_i32 v[10:11], s[22:23], v10, s5, v[4:5]
	global_load_dword v210, v[10:11], off nt
.Lcv11_1_2141:
	s_or_b64 exec, exec, s[20:21]
	s_and_saveexec_b64 s[20:21], vcc
	s_cbranch_execz .Lcv11_1_2143
	v_add3_u32 v9, v0, s8, 6
	v_mad_i64_i32 v[10:11], s[22:23], v9, s5, v[4:5]
	global_load_dword v211, v[10:11], off nt
.Lcv11_1_2143:
	s_or_b64 exec, exec, s[20:21]
	s_and_saveexec_b64 s[20:21], vcc
	s_cbranch_execz .Lcv11_1_2145
	v_add3_u32 v10, v0, s8, 8
	v_mad_i64_i32 v[10:11], s[22:23], v10, s5, v[4:5]
	global_load_dword v212, v[10:11], off nt
.Lcv11_1_2145:
	s_or_b64 exec, exec, s[20:21]
	s_and_saveexec_b64 s[20:21], vcc
	s_cbranch_execz .Lcv11_1_2147
	v_add3_u32 v9, v0, s8, 10
	v_mad_i64_i32 v[10:11], s[22:23], v9, s5, v[4:5]
	global_load_dword v213, v[10:11], off nt
.Lcv11_1_2147:
	s_or_b64 exec, exec, s[20:21]
	s_and_saveexec_b64 s[20:21], vcc
	s_cbranch_execz .Lcv11_1_2149
	v_add3_u32 v10, v0, s8, 12
	v_mad_i64_i32 v[10:11], s[22:23], v10, s5, v[4:5]
	global_load_dword v214, v[10:11], off nt
.Lcv11_1_2149:
	s_or_b64 exec, exec, s[20:21]
	s_and_saveexec_b64 s[20:21], vcc
	s_cbranch_execz .Lcv11_1_end
	v_add3_u32 v9, v0, s8, 14
	v_mad_i64_i32 v[10:11], s[22:23], v9, s5, v[4:5]
	global_load_dword v215, v[10:11], off nt
.Lcv11_1_end:
	s_or_b64 exec, exec, s[20:21]
	s_add_i32 s8, s8, 16
	s_and_saveexec_b64 s[20:21], vcc
	s_cbranch_execz .Lcv11_2_2137
	v_add_u32_e32 v10, s8, v0
	v_mad_i64_i32 v[10:11], s[22:23], v10, s5, v[4:5]
	global_load_dword v216, v[10:11], off nt
.Lcv11_2_2137:
	s_or_b64 exec, exec, s[20:21]
	s_and_saveexec_b64 s[20:21], vcc
	s_cbranch_execz .Lcv11_2_2139
	v_add3_u32 v9, v0, s8, 2
	v_mad_i64_i32 v[10:11], s[22:23], v9, s5, v[4:5]
	global_load_dword v217, v[10:11], off nt
.Lcv11_2_2139:
	s_or_b64 exec, exec, s[20:21]
	s_and_saveexec_b64 s[20:21], vcc
	s_cbranch_execz .Lcv11_2_2141
	v_add3_u32 v10, v0, s8, 4
	v_mad_i64_i32 v[10:11], s[22:23], v10, s5, v[4:5]
	global_load_dword v218, v[10:11], off nt
.Lcv11_2_2141:
	s_or_b64 exec, exec, s[20:21]
	s_and_saveexec_b64 s[20:21], vcc
	s_cbranch_execz .Lcv11_2_2143
	v_add3_u32 v9, v0, s8, 6
	v_mad_i64_i32 v[10:11], s[22:23], v9, s5, v[4:5]
	global_load_dword v219, v[10:11], off nt
.Lcv11_2_2143:
	s_or_b64 exec, exec, s[20:21]
	s_and_saveexec_b64 s[20:21], vcc
	s_cbranch_execz .Lcv11_2_2145
	v_add3_u32 v10, v0, s8, 8
	v_mad_i64_i32 v[10:11], s[22:23], v10, s5, v[4:5]
	global_load_dword v220, v[10:11], off nt
.Lcv11_2_2145:
	s_or_b64 exec, exec, s[20:21]
	s_and_saveexec_b64 s[20:21], vcc
	s_cbranch_execz .Lcv11_2_2147
	v_add3_u32 v9, v0, s8, 10
	v_mad_i64_i32 v[10:11], s[22:23], v9, s5, v[4:5]
	global_load_dword v221, v[10:11], off nt
.Lcv11_2_2147:
	s_or_b64 exec, exec, s[20:21]
	s_and_saveexec_b64 s[20:21], vcc
	s_cbranch_execz .Lcv11_2_2149
	v_add3_u32 v10, v0, s8, 12
	v_mad_i64_i32 v[10:11], s[22:23], v10, s5, v[4:5]
	global_load_dword v222, v[10:11], off nt
.Lcv11_2_2149:
	s_or_b64 exec, exec, s[20:21]
	s_and_saveexec_b64 s[20:21], vcc
	s_cbranch_execz .Lcv11_2_end
	v_add3_u32 v9, v0, s8, 14
	v_mad_i64_i32 v[10:11], s[22:23], v9, s5, v[4:5]
	global_load_dword v223, v[10:11], off nt
.Lcv11_2_end:
	s_or_b64 exec, exec, s[20:21]
	s_add_i32 s8, s8, 16
	s_and_saveexec_b64 s[20:21], vcc
	s_cbranch_execz .Lcv11_3_2137
	v_add_u32_e32 v10, s8, v0
	v_mad_i64_i32 v[10:11], s[22:23], v10, s5, v[4:5]
	global_load_dword v224, v[10:11], off nt
.Lcv11_3_2137:
	s_or_b64 exec, exec, s[20:21]
	s_and_saveexec_b64 s[20:21], vcc
	s_cbranch_execz .Lcv11_3_2139
	v_add3_u32 v9, v0, s8, 2
	v_mad_i64_i32 v[10:11], s[22:23], v9, s5, v[4:5]
	global_load_dword v225, v[10:11], off nt
.Lcv11_3_2139:
	s_or_b64 exec, exec, s[20:21]
	s_and_saveexec_b64 s[20:21], vcc
	s_cbranch_execz .Lcv11_3_2141
	v_add3_u32 v10, v0, s8, 4
	v_mad_i64_i32 v[10:11], s[22:23], v10, s5, v[4:5]
	global_load_dword v226, v[10:11], off nt
.Lcv11_3_2141:
	s_or_b64 exec, exec, s[20:21]
	s_and_saveexec_b64 s[20:21], vcc
	s_cbranch_execz .Lcv11_3_2143
	v_add3_u32 v9, v0, s8, 6
	v_mad_i64_i32 v[10:11], s[22:23], v9, s5, v[4:5]
	global_load_dword v227, v[10:11], off nt
.Lcv11_3_2143:
	s_or_b64 exec, exec, s[20:21]
	s_and_saveexec_b64 s[20:21], vcc
	s_cbranch_execz .Lcv11_3_2145
	v_add3_u32 v10, v0, s8, 8
	v_mad_i64_i32 v[10:11], s[22:23], v10, s5, v[4:5]
	global_load_dword v228, v[10:11], off nt
.Lcv11_3_2145:
	s_or_b64 exec, exec, s[20:21]
	s_and_saveexec_b64 s[20:21], vcc
	s_cbranch_execz .Lcv11_3_2147
	v_add3_u32 v9, v0, s8, 10
	v_mad_i64_i32 v[10:11], s[22:23], v9, s5, v[4:5]
	global_load_dword v229, v[10:11], off nt
.Lcv11_3_2147:
	s_or_b64 exec, exec, s[20:21]
	s_and_saveexec_b64 s[20:21], vcc
	s_cbranch_execz .Lcv11_3_2149
	v_add3_u32 v10, v0, s8, 12
	v_mad_i64_i32 v[10:11], s[22:23], v10, s5, v[4:5]
	global_load_dword v230, v[10:11], off nt
.Lcv11_3_2149:
	s_or_b64 exec, exec, s[20:21]
	s_and_saveexec_b64 s[20:21], vcc
	s_cbranch_execz .Lcv11_3_end
	v_add3_u32 v9, v0, s8, 14
	v_mad_i64_i32 v[10:11], s[22:23], v9, s5, v[4:5]
	global_load_dword v231, v[10:11], off nt
.Lcv11_3_end:
	s_or_b64 exec, exec, s[20:21]
	s_add_i32 s8, s8, 16
	s_waitcnt vmcnt(0)
	ds_write_b32 v8, v200
	ds_write_b32 v8, v201 offset:264
	ds_write_b32 v8, v202 offset:528
	ds_write_b32 v8, v203 offset:792
	ds_write_b32 v8, v204 offset:1056
	ds_write_b32 v8, v205 offset:1320
	ds_write_b32 v8, v206 offset:1584
	ds_write_b32 v8, v207 offset:1848
	ds_write_b32 v8, v208 offset:2112
	ds_write_b32 v8, v209 offset:2376
	ds_write_b32 v8, v210 offset:2640
	ds_write_b32 v8, v211 offset:2904
	ds_write_b32 v8, v212 offset:3168
	ds_write_b32 v8, v213 offset:3432
	ds_write_b32 v8, v214 offset:3696
	ds_write_b32 v8, v215 offset:3960
	ds_write_b32 v8, v216 offset:4224
	ds_write_b32 v8, v217 offset:4488
	ds_write_b32 v8, v218 offset:4752
	ds_write_b32 v8, v219 offset:5016
	ds_write_b32 v8, v220 offset:5280
	ds_write_b32 v8, v221 offset:5544
	ds_write_b32 v8, v222 offset:5808
	ds_write_b32 v8, v223 offset:6072
	ds_write_b32 v8, v224 offset:6336
	ds_write_b32 v8, v225 offset:6600
	ds_write_b32 v8, v226 offset:6864
	ds_write_b32 v8, v227 offset:7128
	ds_write_b32 v8, v228 offset:7392
	ds_write_b32 v8, v229 offset:7656
	ds_write_b32 v8, v230 offset:7920
	ds_write_b32 v8, v231 offset:8184
	s_branch .LBB0_2126

.LBB0_2156:
	v_mov_b32_e32 v200, 0
	v_mov_b32_e32 v201, 0
	v_mov_b32_e32 v202, 0
	v_mov_b32_e32 v203, 0
	v_mov_b32_e32 v204, 0
	v_mov_b32_e32 v205, 0
	v_mov_b32_e32 v206, 0
	v_mov_b32_e32 v207, 0
	v_mov_b32_e32 v208, 0
	v_mov_b32_e32 v209, 0
	v_mov_b32_e32 v210, 0
	v_mov_b32_e32 v211, 0
	v_mov_b32_e32 v212, 0
	v_mov_b32_e32 v213, 0
	v_mov_b32_e32 v214, 0
	v_mov_b32_e32 v215, 0
	v_mov_b32_e32 v216, 0
	v_mov_b32_e32 v217, 0
	v_mov_b32_e32 v218, 0
	v_mov_b32_e32 v219, 0
	v_mov_b32_e32 v220, 0
	v_mov_b32_e32 v221, 0
	v_mov_b32_e32 v222, 0
	v_mov_b32_e32 v223, 0
	v_mov_b32_e32 v224, 0
	v_mov_b32_e32 v225, 0
	v_mov_b32_e32 v226, 0
	v_mov_b32_e32 v227, 0
	v_mov_b32_e32 v228, 0
	v_mov_b32_e32 v229, 0
	v_mov_b32_e32 v230, 0
	v_mov_b32_e32 v231, 0
	s_and_saveexec_b64 s[20:21], vcc
	s_cbranch_execz .Lcv12_0_2158
	v_add_u32_e32 v10, s6, v0
	v_ashrrev_i32_e32 v11, 31, v10
	v_lshlrev_b64 v[10:11], 12, v[10:11]
	v_lshl_add_u64 v[10:11], v[4:5], 0, v[10:11]
	global_load_dword v200, v[10:11], off nt

.Lcv12_0_end:
	s_or_b64 exec, exec, s[20:21]
	s_add_i32 s6, s6, 16
	s_and_saveexec_b64 s[20:21], vcc
	s_cbranch_execz .Lcv12_1_2158
	v_add_u32_e32 v10, s6, v0
	v_ashrrev_i32_e32 v11, 31, v10
	v_lshlrev_b64 v[10:11], 12, v[10:11]
	v_lshl_add_u64 v[10:11], v[4:5], 0, v[10:11]
	global_load_dword v208, v[10:11], off nt
.Lcv12_1_2158:
	s_or_b64 exec, exec, s[20:21]
	s_and_saveexec_b64 s[20:21], vcc
	s_cbranch_execz .Lcv12_1_2160
	v_add3_u32 v10, v0, s6, 2
	v_ashrrev_i32_e32 v11, 31, v10
	v_lshlrev_b64 v[10:11], 12, v[10:11]
	v_lshl_add_u64 v[10:11], v[4:5], 0, v[10:11]
	global_load_dword v209, v[10:11], off nt
.Lcv12_1_2160:
	s_or_b64 exec, exec, s[20:21]
	s_and_saveexec_b64 s[20:21], vcc
	s_cbranch_execz .Lcv12_1_2162
	v_add3_u32 v10, v0, s6, 4
	v_ashrrev_i32_e32 v11, 31, v10
	v_lshlrev_b64 v[10:11], 12, v[10:11]
	v_lshl_add_u64 v[10:11], v[4:5], 0, v[10:11]
	global_load_dword v210, v[10:11], off nt
.Lcv12_1_2162:
	s_or_b64 exec, exec, s[20:21]
	s_and_saveexec_b64 s[20:21], vcc
	s_cbranch_execz .Lcv12_1_2164
	v_add3_u32 v10, v0, s6, 6
	v_ashrrev_i32_e32 v11, 31, v10
	v_lshlrev_b64 v[10:11], 12, v[10:11]
	v_lshl_add_u64 v[10:11], v[4:5], 0, v[10:11]
	global_load_dword v211, v[10:11], off nt
.Lcv12_1_2164:
	s_or_b64 exec, exec, s[20:21]
	s_and_saveexec_b64 s[20:21], vcc
	s_cbranch_execz .Lcv12_1_2166
	v_add3_u32 v10, v0, s6, 8
	v_ashrrev_i32_e32 v11, 31, v10
	v_lshlrev_b64 v[10:11], 12, v[10:11]
	v_lshl_add_u64 v[10:11], v[4:5], 0, v[10:11]
	global_load_dword v212, v[10:11], off nt
.Lcv12_1_2166:
	s_or_b64 exec, exec, s[20:21]
	s_and_saveexec_b64 s[20:21], vcc
	s_cbranch_execz .Lcv12_1_2168
	v_add3_u32 v10, v0, s6, 10
	v_ashrrev_i32_e32 v11, 31, v10
	v_lshlrev_b64 v[10:11], 12, v[10:11]
	v_lshl_add_u64 v[10:11], v[4:5], 0, v[10:11]
	global_load_dword v213, v[10:11], off nt
.Lcv12_1_2168:
	s_or_b64 exec, exec, s[20:21]
	s_and_saveexec_b64 s[20:21], vcc
	s_cbranch_execz .Lcv12_1_2170
	v_add3_u32 v10, v0, s6, 12
	v_ashrrev_i32_e32 v11, 31, v10
	v_lshlrev_b64 v[10:11], 12, v[10:11]
	v_lshl_add_u64 v[10:11], v[4:5], 0, v[10:11]
	global_load_dword v214, v[10:11], off nt
.Lcv12_1_2170:
	s_or_b64 exec, exec, s[20:21]
	s_and_saveexec_b64 s[20:21], vcc
	s_cbranch_execz .Lcv12_1_end
	v_add3_u32 v10, v0, s6, 14
	v_ashrrev_i32_e32 v11, 31, v10
	v_lshlrev_b64 v[10:11], 12, v[10:11]
	v_lshl_add_u64 v[10:11], v[4:5], 0, v[10:11]
	global_load_dword v215, v[10:11], off nt
.Lcv12_1_end:
	s_or_b64 exec, exec, s[20:21]
	s_add_i32 s6, s6, 16
	s_and_saveexec_b64 s[20:21], vcc
	s_cbranch_execz .Lcv12_2_2158
	v_add_u32_e32 v10, s6, v0
	v_ashrrev_i32_e32 v11, 31, v10
	v_lshlrev_b64 v[10:11], 12, v[10:11]
	v_lshl_add_u64 v[10:11], v[4:5], 0, v[10:11]
	global_load_dword v216, v[10:11], off nt
.Lcv12_2_2158:
	s_or_b64 exec, exec, s[20:21]
	s_and_saveexec_b64 s[20:21], vcc
	s_cbranch_execz .Lcv12_2_2160
	v_add3_u32 v10, v0, s6, 2
	v_ashrrev_i32_e32 v11, 31, v10
	v_lshlrev_b64 v[10:11], 12, v[10:11]
	v_lshl_add_u64 v[10:11], v[4:5], 0, v[10:11]
	global_load_dword v217, v[10:11], off nt
.Lcv12_2_2160:
	s_or_b64 exec, exec, s[20:21]
	s_and_saveexec_b64 s[20:21], vcc
	s_cbranch_execz .Lcv12_2_2162
	v_add3_u32 v10, v0, s6, 4
	v_ashrrev_i32_e32 v11, 31, v10
	v_lshlrev_b64 v[10:11], 12, v[10:11]
	v_lshl_add_u64 v[10:11], v[4:5], 0, v[10:11]
	global_load_dword v218, v[10:11], off nt
.Lcv12_2_2162:
	s_or_b64 exec, exec, s[20:21]
	s_and_saveexec_b64 s[20:21], vcc
	s_cbranch_execz .Lcv12_2_2164
	v_add3_u32 v10, v0, s6, 6
	v_ashrrev_i32_e32 v11, 31, v10
	v_lshlrev_b64 v[10:11], 12, v[10:11]
	v_lshl_add_u64 v[10:11], v[4:5], 0, v[10:11]
	global_load_dword v219, v[10:11], off nt
.Lcv12_2_2164:
	s_or_b64 exec, exec, s[20:21]
	s_and_saveexec_b64 s[20:21], vcc
	s_cbranch_execz .Lcv12_2_2166
	v_add3_u32 v10, v0, s6, 8
	v_ashrrev_i32_e32 v11, 31, v10
	v_lshlrev_b64 v[10:11], 12, v[10:11]
	v_lshl_add_u64 v[10:11], v[4:5], 0, v[10:11]
	global_load_dword v220, v[10:11], off nt
.Lcv12_2_2166:
	s_or_b64 exec, exec, s[20:21]
	s_and_saveexec_b64 s[20:21], vcc
	s_cbranch_execz .Lcv12_2_2168
	v_add3_u32 v10, v0, s6, 10
	v_ashrrev_i32_e32 v11, 31, v10
	v_lshlrev_b64 v[10:11], 12, v[10:11]
	v_lshl_add_u64 v[10:11], v[4:5], 0, v[10:11]
	global_load_dword v221, v[10:11], off nt
.Lcv12_2_2168:
	s_or_b64 exec, exec, s[20:21]
	s_and_saveexec_b64 s[20:21], vcc
	s_cbranch_execz .Lcv12_2_2170
	v_add3_u32 v10, v0, s6, 12
	v_ashrrev_i32_e32 v11, 31, v10
	v_lshlrev_b64 v[10:11], 12, v[10:11]
	v_lshl_add_u64 v[10:11], v[4:5], 0, v[10:11]
	global_load_dword v222, v[10:11], off nt
.Lcv12_2_2170:
	s_or_b64 exec, exec, s[20:21]
	s_and_saveexec_b64 s[20:21], vcc
	s_cbranch_execz .Lcv12_2_end
	v_add3_u32 v10, v0, s6, 14
	v_ashrrev_i32_e32 v11, 31, v10
	v_lshlrev_b64 v[10:11], 12, v[10:11]
	v_lshl_add_u64 v[10:11], v[4:5], 0, v[10:11]
	global_load_dword v223, v[10:11], off nt
.Lcv12_2_end:
	s_or_b64 exec, exec, s[20:21]
	s_add_i32 s6, s6, 16
	s_and_saveexec_b64 s[20:21], vcc
	s_cbranch_execz .Lcv12_3_2158
	v_add_u32_e32 v10, s6, v0
	v_ashrrev_i32_e32 v11, 31, v10
	v_lshlrev_b64 v[10:11], 12, v[10:11]
	v_lshl_add_u64 v[10:11], v[4:5], 0, v[10:11]
	global_load_dword v224, v[10:11], off nt
.Lcv12_3_2158:
	s_or_b64 exec, exec, s[20:21]
	s_and_saveexec_b64 s[20:21], vcc
	s_cbranch_execz .Lcv12_3_2160
	v_add3_u32 v10, v0, s6, 2
	v_ashrrev_i32_e32 v11, 31, v10
	v_lshlrev_b64 v[10:11], 12, v[10:11]
	v_lshl_add_u64 v[10:11], v[4:5], 0, v[10:11]
	global_load_dword v225, v[10:11], off nt
.Lcv12_3_2160:
	s_or_b64 exec, exec, s[20:21]
	s_and_saveexec_b64 s[20:21], vcc
	s_cbranch_execz .Lcv12_3_2162
	v_add3_u32 v10, v0, s6, 4
	v_ashrrev_i32_e32 v11, 31, v10
	v_lshlrev_b64 v[10:11], 12, v[10:11]
	v_lshl_add_u64 v[10:11], v[4:5], 0, v[10:11]
	global_load_dword v226, v[10:11], off nt
.Lcv12_3_2162:
	s_or_b64 exec, exec, s[20:21]
	s_and_saveexec_b64 s[20:21], vcc
	s_cbranch_execz .Lcv12_3_2164
	v_add3_u32 v10, v0, s6, 6
	v_ashrrev_i32_e32 v11, 31, v10
	v_lshlrev_b64 v[10:11], 12, v[10:11]
	v_lshl_add_u64 v[10:11], v[4:5], 0, v[10:11]
	global_load_dword v227, v[10:11], off nt
.Lcv12_3_2164:
	s_or_b64 exec, exec, s[20:21]
	s_and_saveexec_b64 s[20:21], vcc
	s_cbranch_execz .Lcv12_3_2166
	v_add3_u32 v10, v0, s6, 8
	v_ashrrev_i32_e32 v11, 31, v10
	v_lshlrev_b64 v[10:11], 12, v[10:11]
	v_lshl_add_u64 v[10:11], v[4:5], 0, v[10:11]
	global_load_dword v228, v[10:11], off nt
.Lcv12_3_2166:
	s_or_b64 exec, exec, s[20:21]
	s_and_saveexec_b64 s[20:21], vcc
	s_cbranch_execz .Lcv12_3_2168
	v_add3_u32 v10, v0, s6, 10
	v_ashrrev_i32_e32 v11, 31, v10
	v_lshlrev_b64 v[10:11], 12, v[10:11]
	v_lshl_add_u64 v[10:11], v[4:5], 0, v[10:11]
	global_load_dword v229, v[10:11], off nt
.Lcv12_3_2168:
	s_or_b64 exec, exec, s[20:21]
	s_and_saveexec_b64 s[20:21], vcc
	s_cbranch_execz .Lcv12_3_2170
	v_add3_u32 v10, v0, s6, 12
	v_ashrrev_i32_e32 v11, 31, v10
	v_lshlrev_b64 v[10:11], 12, v[10:11]
	v_lshl_add_u64 v[10:11], v[4:5], 0, v[10:11]
	global_load_dword v230, v[10:11], off nt
.Lcv12_3_2170:
	s_or_b64 exec, exec, s[20:21]
	s_and_saveexec_b64 s[20:21], vcc
	s_cbranch_execz .Lcv12_3_end
	v_add3_u32 v10, v0, s6, 14
	v_ashrrev_i32_e32 v11, 31, v10
	v_lshlrev_b64 v[10:11], 12, v[10:11]
	v_lshl_add_u64 v[10:11], v[4:5], 0, v[10:11]
	global_load_dword v231, v[10:11], off nt
.Lcv12_3_end:
	s_or_b64 exec, exec, s[20:21]
	s_add_i32 s6, s6, 16
	s_waitcnt vmcnt(0)
	ds_write_b32 v8, v200
	ds_write_b32 v8, v201 offset:264
	ds_write_b32 v8, v202 offset:528
	ds_write_b32 v8, v203 offset:792
	ds_write_b32 v8, v204 offset:1056
	ds_write_b32 v8, v205 offset:1320
	ds_write_b32 v8, v206 offset:1584
	ds_write_b32 v8, v207 offset:1848
	ds_write_b32 v8, v208 offset:2112
	ds_write_b32 v8, v209 offset:2376
	ds_write_b32 v8, v210 offset:2640
	ds_write_b32 v8, v211 offset:2904
	ds_write_b32 v8, v212 offset:3168
	ds_write_b32 v8, v213 offset:3432
	ds_write_b32 v8, v214 offset:3696
	ds_write_b32 v8, v215 offset:3960
	ds_write_b32 v8, v216 offset:4224
	ds_write_b32 v8, v217 offset:4488
	ds_write_b32 v8, v218 offset:4752
	ds_write_b32 v8, v219 offset:5016
	ds_write_b32 v8, v220 offset:5280
	ds_write_b32 v8, v221 offset:5544
	ds_write_b32 v8, v222 offset:5808
	ds_write_b32 v8, v223 offset:6072
	ds_write_b32 v8, v224 offset:6336
	ds_write_b32 v8, v225 offset:6600
	ds_write_b32 v8, v226 offset:6864
	ds_write_b32 v8, v227 offset:7128
	ds_write_b32 v8, v228 offset:7392
	ds_write_b32 v8, v229 offset:7656
	ds_write_b32 v8, v230 offset:7920
	ds_write_b32 v8, v231 offset:8184
	s_branch .LBB0_2153

.LBB0_2177:
	v_mov_b32_e32 v200, 0
	v_mov_b32_e32 v201, 0
	v_mov_b32_e32 v202, 0
	v_mov_b32_e32 v203, 0
	v_mov_b32_e32 v204, 0
	v_mov_b32_e32 v205, 0
	v_mov_b32_e32 v206, 0
	v_mov_b32_e32 v207, 0
	v_mov_b32_e32 v208, 0
	v_mov_b32_e32 v209, 0
	v_mov_b32_e32 v210, 0
	v_mov_b32_e32 v211, 0
	v_mov_b32_e32 v212, 0
	v_mov_b32_e32 v213, 0
	v_mov_b32_e32 v214, 0
	v_mov_b32_e32 v215, 0
	v_mov_b32_e32 v216, 0
	v_mov_b32_e32 v217, 0
	v_mov_b32_e32 v218, 0
	v_mov_b32_e32 v219, 0
	v_mov_b32_e32 v220, 0
	v_mov_b32_e32 v221, 0
	v_mov_b32_e32 v222, 0
	v_mov_b32_e32 v223, 0
	v_mov_b32_e32 v224, 0
	v_mov_b32_e32 v225, 0
	v_mov_b32_e32 v226, 0
	v_mov_b32_e32 v227, 0
	v_mov_b32_e32 v228, 0
	v_mov_b32_e32 v229, 0
	v_mov_b32_e32 v230, 0
	v_mov_b32_e32 v231, 0
	s_and_saveexec_b64 s[20:21], vcc
	s_cbranch_execz .Lcv13_0_2179
	v_add_u32_e32 v14, s6, v1
	v_ashrrev_i32_e32 v15, 31, v14
	v_lshlrev_b64 v[14:15], 11, v[14:15]
	v_lshl_add_u64 v[14:15], v[6:7], 0, v[14:15]
	global_load_dword v200, v[14:15], off nt

.Lcv13_0_end:
	s_or_b64 exec, exec, s[20:21]
	s_add_i32 s6, s6, 16
	s_and_saveexec_b64 s[20:21], vcc
	s_cbranch_execz .Lcv13_1_2179
	v_add_u32_e32 v14, s6, v1
	v_ashrrev_i32_e32 v15, 31, v14
	v_lshlrev_b64 v[14:15], 11, v[14:15]
	v_lshl_add_u64 v[14:15], v[6:7], 0, v[14:15]
	global_load_dword v208, v[14:15], off nt
.Lcv13_1_2179:
	s_or_b64 exec, exec, s[20:21]
	s_and_saveexec_b64 s[20:21], vcc
	s_cbranch_execz .Lcv13_1_2181
	v_add3_u32 v14, v1, s6, 2
	v_ashrrev_i32_e32 v15, 31, v14
	v_lshlrev_b64 v[14:15], 11, v[14:15]
	v_lshl_add_u64 v[14:15], v[6:7], 0, v[14:15]
	global_load_dword v209, v[14:15], off nt
.Lcv13_1_2181:
	s_or_b64 exec, exec, s[20:21]
	s_and_saveexec_b64 s[20:21], vcc
	s_cbranch_execz .Lcv13_1_2183
	v_add3_u32 v14, v1, s6, 4
	v_ashrrev_i32_e32 v15, 31, v14
	v_lshlrev_b64 v[14:15], 11, v[14:15]
	v_lshl_add_u64 v[14:15], v[6:7], 0, v[14:15]
	global_load_dword v210, v[14:15], off nt
.Lcv13_1_2183:
	s_or_b64 exec, exec, s[20:21]
	s_and_saveexec_b64 s[20:21], vcc
	s_cbranch_execz .Lcv13_1_2185
	v_add3_u32 v14, v1, s6, 6
	v_ashrrev_i32_e32 v15, 31, v14
	v_lshlrev_b64 v[14:15], 11, v[14:15]
	v_lshl_add_u64 v[14:15], v[6:7], 0, v[14:15]
	global_load_dword v211, v[14:15], off nt
.Lcv13_1_2185:
	s_or_b64 exec, exec, s[20:21]
	s_and_saveexec_b64 s[20:21], vcc
	s_cbranch_execz .Lcv13_1_2187
	v_add3_u32 v14, v1, s6, 8
	v_ashrrev_i32_e32 v15, 31, v14
	v_lshlrev_b64 v[14:15], 11, v[14:15]
	v_lshl_add_u64 v[14:15], v[6:7], 0, v[14:15]
	global_load_dword v212, v[14:15], off nt
.Lcv13_1_2187:
	s_or_b64 exec, exec, s[20:21]
	s_and_saveexec_b64 s[20:21], vcc
	s_cbranch_execz .Lcv13_1_2189
	v_add3_u32 v14, v1, s6, 10
	v_ashrrev_i32_e32 v15, 31, v14
	v_lshlrev_b64 v[14:15], 11, v[14:15]
	v_lshl_add_u64 v[14:15], v[6:7], 0, v[14:15]
	global_load_dword v213, v[14:15], off nt
.Lcv13_1_2189:
	s_or_b64 exec, exec, s[20:21]
	s_and_saveexec_b64 s[20:21], vcc
	s_cbranch_execz .Lcv13_1_2191
	v_add3_u32 v14, v1, s6, 12
	v_ashrrev_i32_e32 v15, 31, v14
	v_lshlrev_b64 v[14:15], 11, v[14:15]
	v_lshl_add_u64 v[14:15], v[6:7], 0, v[14:15]
	global_load_dword v214, v[14:15], off nt
.Lcv13_1_2191:
	s_or_b64 exec, exec, s[20:21]
	s_and_saveexec_b64 s[20:21], vcc
	s_cbranch_execz .Lcv13_1_end
	v_add3_u32 v14, v1, s6, 14
	v_ashrrev_i32_e32 v15, 31, v14
	v_lshlrev_b64 v[14:15], 11, v[14:15]
	v_lshl_add_u64 v[14:15], v[6:7], 0, v[14:15]
	global_load_dword v215, v[14:15], off nt
.Lcv13_1_end:
	s_or_b64 exec, exec, s[20:21]
	s_add_i32 s6, s6, 16
	s_and_saveexec_b64 s[20:21], vcc
	s_cbranch_execz .Lcv13_2_2179
	v_add_u32_e32 v14, s6, v1
	v_ashrrev_i32_e32 v15, 31, v14
	v_lshlrev_b64 v[14:15], 11, v[14:15]
	v_lshl_add_u64 v[14:15], v[6:7], 0, v[14:15]
	global_load_dword v216, v[14:15], off nt
.Lcv13_2_2179:
	s_or_b64 exec, exec, s[20:21]
	s_and_saveexec_b64 s[20:21], vcc
	s_cbranch_execz .Lcv13_2_2181
	v_add3_u32 v14, v1, s6, 2
	v_ashrrev_i32_e32 v15, 31, v14
	v_lshlrev_b64 v[14:15], 11, v[14:15]
	v_lshl_add_u64 v[14:15], v[6:7], 0, v[14:15]
	global_load_dword v217, v[14:15], off nt
.Lcv13_2_2181:
	s_or_b64 exec, exec, s[20:21]
	s_and_saveexec_b64 s[20:21], vcc
	s_cbranch_execz .Lcv13_2_2183
	v_add3_u32 v14, v1, s6, 4
	v_ashrrev_i32_e32 v15, 31, v14
	v_lshlrev_b64 v[14:15], 11, v[14:15]
	v_lshl_add_u64 v[14:15], v[6:7], 0, v[14:15]
	global_load_dword v218, v[14:15], off nt
.Lcv13_2_2183:
	s_or_b64 exec, exec, s[20:21]
	s_and_saveexec_b64 s[20:21], vcc
	s_cbranch_execz .Lcv13_2_2185
	v_add3_u32 v14, v1, s6, 6
	v_ashrrev_i32_e32 v15, 31, v14
	v_lshlrev_b64 v[14:15], 11, v[14:15]
	v_lshl_add_u64 v[14:15], v[6:7], 0, v[14:15]
	global_load_dword v219, v[14:15], off nt
.Lcv13_2_2185:
	s_or_b64 exec, exec, s[20:21]
	s_and_saveexec_b64 s[20:21], vcc
	s_cbranch_execz .Lcv13_2_2187
	v_add3_u32 v14, v1, s6, 8
	v_ashrrev_i32_e32 v15, 31, v14
	v_lshlrev_b64 v[14:15], 11, v[14:15]
	v_lshl_add_u64 v[14:15], v[6:7], 0, v[14:15]
	global_load_dword v220, v[14:15], off nt
.Lcv13_2_2187:
	s_or_b64 exec, exec, s[20:21]
	s_and_saveexec_b64 s[20:21], vcc
	s_cbranch_execz .Lcv13_2_2189
	v_add3_u32 v14, v1, s6, 10
	v_ashrrev_i32_e32 v15, 31, v14
	v_lshlrev_b64 v[14:15], 11, v[14:15]
	v_lshl_add_u64 v[14:15], v[6:7], 0, v[14:15]
	global_load_dword v221, v[14:15], off nt
.Lcv13_2_2189:
	s_or_b64 exec, exec, s[20:21]
	s_and_saveexec_b64 s[20:21], vcc
	s_cbranch_execz .Lcv13_2_2191
	v_add3_u32 v14, v1, s6, 12
	v_ashrrev_i32_e32 v15, 31, v14
	v_lshlrev_b64 v[14:15], 11, v[14:15]
	v_lshl_add_u64 v[14:15], v[6:7], 0, v[14:15]
	global_load_dword v222, v[14:15], off nt
.Lcv13_2_2191:
	s_or_b64 exec, exec, s[20:21]
	s_and_saveexec_b64 s[20:21], vcc
	s_cbranch_execz .Lcv13_2_end
	v_add3_u32 v14, v1, s6, 14
	v_ashrrev_i32_e32 v15, 31, v14
	v_lshlrev_b64 v[14:15], 11, v[14:15]
	v_lshl_add_u64 v[14:15], v[6:7], 0, v[14:15]
	global_load_dword v223, v[14:15], off nt
.Lcv13_2_end:
	s_or_b64 exec, exec, s[20:21]
	s_add_i32 s6, s6, 16
	s_and_saveexec_b64 s[20:21], vcc
	s_cbranch_execz .Lcv13_3_2179
	v_add_u32_e32 v14, s6, v1
	v_ashrrev_i32_e32 v15, 31, v14
	v_lshlrev_b64 v[14:15], 11, v[14:15]
	v_lshl_add_u64 v[14:15], v[6:7], 0, v[14:15]
	global_load_dword v224, v[14:15], off nt
.Lcv13_3_2179:
	s_or_b64 exec, exec, s[20:21]
	s_and_saveexec_b64 s[20:21], vcc
	s_cbranch_execz .Lcv13_3_2181
	v_add3_u32 v14, v1, s6, 2
	v_ashrrev_i32_e32 v15, 31, v14
	v_lshlrev_b64 v[14:15], 11, v[14:15]
	v_lshl_add_u64 v[14:15], v[6:7], 0, v[14:15]
	global_load_dword v225, v[14:15], off nt
.Lcv13_3_2181:
	s_or_b64 exec, exec, s[20:21]
	s_and_saveexec_b64 s[20:21], vcc
	s_cbranch_execz .Lcv13_3_2183
	v_add3_u32 v14, v1, s6, 4
	v_ashrrev_i32_e32 v15, 31, v14
	v_lshlrev_b64 v[14:15], 11, v[14:15]
	v_lshl_add_u64 v[14:15], v[6:7], 0, v[14:15]
	global_load_dword v226, v[14:15], off nt
.Lcv13_3_2183:
	s_or_b64 exec, exec, s[20:21]
	s_and_saveexec_b64 s[20:21], vcc
	s_cbranch_execz .Lcv13_3_2185
	v_add3_u32 v14, v1, s6, 6
	v_ashrrev_i32_e32 v15, 31, v14
	v_lshlrev_b64 v[14:15], 11, v[14:15]
	v_lshl_add_u64 v[14:15], v[6:7], 0, v[14:15]
	global_load_dword v227, v[14:15], off nt
.Lcv13_3_2185:
	s_or_b64 exec, exec, s[20:21]
	s_and_saveexec_b64 s[20:21], vcc
	s_cbranch_execz .Lcv13_3_2187
	v_add3_u32 v14, v1, s6, 8
	v_ashrrev_i32_e32 v15, 31, v14
	v_lshlrev_b64 v[14:15], 11, v[14:15]
	v_lshl_add_u64 v[14:15], v[6:7], 0, v[14:15]
	global_load_dword v228, v[14:15], off nt
.Lcv13_3_2187:
	s_or_b64 exec, exec, s[20:21]
	s_and_saveexec_b64 s[20:21], vcc
	s_cbranch_execz .Lcv13_3_2189
	v_add3_u32 v14, v1, s6, 10
	v_ashrrev_i32_e32 v15, 31, v14
	v_lshlrev_b64 v[14:15], 11, v[14:15]
	v_lshl_add_u64 v[14:15], v[6:7], 0, v[14:15]
	global_load_dword v229, v[14:15], off nt
.Lcv13_3_2189:
	s_or_b64 exec, exec, s[20:21]
	s_and_saveexec_b64 s[20:21], vcc
	s_cbranch_execz .Lcv13_3_2191
	v_add3_u32 v14, v1, s6, 12
	v_ashrrev_i32_e32 v15, 31, v14
	v_lshlrev_b64 v[14:15], 11, v[14:15]
	v_lshl_add_u64 v[14:15], v[6:7], 0, v[14:15]
	global_load_dword v230, v[14:15], off nt
.Lcv13_3_2191:
	s_or_b64 exec, exec, s[20:21]
	s_and_saveexec_b64 s[20:21], vcc
	s_cbranch_execz .Lcv13_3_end
	v_add3_u32 v14, v1, s6, 14
	v_ashrrev_i32_e32 v15, 31, v14
	v_lshlrev_b64 v[14:15], 11, v[14:15]
	v_lshl_add_u64 v[14:15], v[6:7], 0, v[14:15]
	global_load_dword v231, v[14:15], off nt
.Lcv13_3_end:
	s_or_b64 exec, exec, s[20:21]
	s_add_i32 s6, s6, 16
	s_waitcnt vmcnt(0)
	ds_write_b32 v2, v200
	ds_write_b32 v2, v201 offset:264
	ds_write_b32 v2, v202 offset:528
	ds_write_b32 v2, v203 offset:792
	ds_write_b32 v2, v204 offset:1056
	ds_write_b32 v2, v205 offset:1320
	ds_write_b32 v2, v206 offset:1584
	ds_write_b32 v2, v207 offset:1848
	ds_write_b32 v2, v208 offset:2112
	ds_write_b32 v2, v209 offset:2376
	ds_write_b32 v2, v210 offset:2640
	ds_write_b32 v2, v211 offset:2904
	ds_write_b32 v2, v212 offset:3168
	ds_write_b32 v2, v213 offset:3432
	ds_write_b32 v2, v214 offset:3696
	ds_write_b32 v2, v215 offset:3960
	ds_write_b32 v2, v216 offset:4224
	ds_write_b32 v2, v217 offset:4488
	ds_write_b32 v2, v218 offset:4752
	ds_write_b32 v2, v219 offset:5016
	ds_write_b32 v2, v220 offset:5280
	ds_write_b32 v2, v221 offset:5544
	ds_write_b32 v2, v222 offset:5808
	ds_write_b32 v2, v223 offset:6072
	ds_write_b32 v2, v224 offset:6336
	ds_write_b32 v2, v225 offset:6600
	ds_write_b32 v2, v226 offset:6864
	ds_write_b32 v2, v227 offset:7128
	ds_write_b32 v2, v228 offset:7392
	ds_write_b32 v2, v229 offset:7656
	ds_write_b32 v2, v230 offset:7920
	ds_write_b32 v2, v231 offset:8184
	s_branch .LBB0_2174

.LBB0_2197:
	v_mov_b32_e32 v200, 0
	v_mov_b32_e32 v201, 0
	v_mov_b32_e32 v202, 0
	v_mov_b32_e32 v203, 0
	v_mov_b32_e32 v204, 0
	v_mov_b32_e32 v205, 0
	v_mov_b32_e32 v206, 0
	v_mov_b32_e32 v207, 0
	v_mov_b32_e32 v208, 0
	v_mov_b32_e32 v209, 0
	v_mov_b32_e32 v210, 0
	v_mov_b32_e32 v211, 0
	v_mov_b32_e32 v212, 0
	v_mov_b32_e32 v213, 0
	v_mov_b32_e32 v214, 0
	v_mov_b32_e32 v215, 0
	v_mov_b32_e32 v216, 0
	v_mov_b32_e32 v217, 0
	v_mov_b32_e32 v218, 0
	v_mov_b32_e32 v219, 0
	v_mov_b32_e32 v220, 0
	v_mov_b32_e32 v221, 0
	v_mov_b32_e32 v222, 0
	v_mov_b32_e32 v223, 0
	v_mov_b32_e32 v224, 0
	v_mov_b32_e32 v225, 0
	v_mov_b32_e32 v226, 0
	v_mov_b32_e32 v227, 0
	v_mov_b32_e32 v228, 0
	v_mov_b32_e32 v229, 0
	v_mov_b32_e32 v230, 0
	v_mov_b32_e32 v231, 0
	s_and_saveexec_b64 s[20:21], vcc
	s_cbranch_execz .Lcv14_0_2199
	v_add_u32_e32 v14, s6, v0
	v_ashrrev_i32_e32 v15, 31, v14
	v_lshlrev_b64 v[14:15], 11, v[14:15]
	v_lshl_add_u64 v[14:15], v[4:5], 0, v[14:15]
	global_load_dword v200, v[14:15], off nt

.Lcv14_0_end:
	s_or_b64 exec, exec, s[20:21]
	s_add_i32 s6, s6, 16
	s_and_saveexec_b64 s[20:21], vcc
	s_cbranch_execz .Lcv14_1_2199
	v_add_u32_e32 v14, s6, v0
	v_ashrrev_i32_e32 v15, 31, v14
	v_lshlrev_b64 v[14:15], 11, v[14:15]
	v_lshl_add_u64 v[14:15], v[4:5], 0, v[14:15]
	global_load_dword v208, v[14:15], off nt
.Lcv14_1_2199:
	s_or_b64 exec, exec, s[20:21]
	s_and_saveexec_b64 s[20:21], vcc
	s_cbranch_execz .Lcv14_1_2201
	v_add3_u32 v14, v0, s6, 2
	v_ashrrev_i32_e32 v15, 31, v14
	v_lshlrev_b64 v[14:15], 11, v[14:15]
	v_lshl_add_u64 v[14:15], v[4:5], 0, v[14:15]
	global_load_dword v209, v[14:15], off nt
.Lcv14_1_2201:
	s_or_b64 exec, exec, s[20:21]
	s_and_saveexec_b64 s[20:21], vcc
	s_cbranch_execz .Lcv14_1_2203
	v_add3_u32 v14, v0, s6, 4
	v_ashrrev_i32_e32 v15, 31, v14
	v_lshlrev_b64 v[14:15], 11, v[14:15]
	v_lshl_add_u64 v[14:15], v[4:5], 0, v[14:15]
	global_load_dword v210, v[14:15], off nt
.Lcv14_1_2203:
	s_or_b64 exec, exec, s[20:21]
	s_and_saveexec_b64 s[20:21], vcc
	s_cbranch_execz .Lcv14_1_2205
	v_add3_u32 v14, v0, s6, 6
	v_ashrrev_i32_e32 v15, 31, v14
	v_lshlrev_b64 v[14:15], 11, v[14:15]
	v_lshl_add_u64 v[14:15], v[4:5], 0, v[14:15]
	global_load_dword v211, v[14:15], off nt
.Lcv14_1_2205:
	s_or_b64 exec, exec, s[20:21]
	s_and_saveexec_b64 s[20:21], vcc
	s_cbranch_execz .Lcv14_1_2207
	v_add3_u32 v14, v0, s6, 8
	v_ashrrev_i32_e32 v15, 31, v14
	v_lshlrev_b64 v[14:15], 11, v[14:15]
	v_lshl_add_u64 v[14:15], v[4:5], 0, v[14:15]
	global_load_dword v212, v[14:15], off nt
.Lcv14_1_2207:
	s_or_b64 exec, exec, s[20:21]
	s_and_saveexec_b64 s[20:21], vcc
	s_cbranch_execz .Lcv14_1_2209
	v_add3_u32 v14, v0, s6, 10
	v_ashrrev_i32_e32 v15, 31, v14
	v_lshlrev_b64 v[14:15], 11, v[14:15]
	v_lshl_add_u64 v[14:15], v[4:5], 0, v[14:15]
	global_load_dword v213, v[14:15], off nt
.Lcv14_1_2209:
	s_or_b64 exec, exec, s[20:21]
	s_and_saveexec_b64 s[20:21], vcc
	s_cbranch_execz .Lcv14_1_2211
	v_add3_u32 v14, v0, s6, 12
	v_ashrrev_i32_e32 v15, 31, v14
	v_lshlrev_b64 v[14:15], 11, v[14:15]
	v_lshl_add_u64 v[14:15], v[4:5], 0, v[14:15]
	global_load_dword v214, v[14:15], off nt
.Lcv14_1_2211:
	s_or_b64 exec, exec, s[20:21]
	s_and_saveexec_b64 s[20:21], vcc
	s_cbranch_execz .Lcv14_1_end
	v_add3_u32 v14, v0, s6, 14
	v_ashrrev_i32_e32 v15, 31, v14
	v_lshlrev_b64 v[14:15], 11, v[14:15]
	v_lshl_add_u64 v[14:15], v[4:5], 0, v[14:15]
	global_load_dword v215, v[14:15], off nt
.Lcv14_1_end:
	s_or_b64 exec, exec, s[20:21]
	s_add_i32 s6, s6, 16
	s_and_saveexec_b64 s[20:21], vcc
	s_cbranch_execz .Lcv14_2_2199
	v_add_u32_e32 v14, s6, v0
	v_ashrrev_i32_e32 v15, 31, v14
	v_lshlrev_b64 v[14:15], 11, v[14:15]
	v_lshl_add_u64 v[14:15], v[4:5], 0, v[14:15]
	global_load_dword v216, v[14:15], off nt
.Lcv14_2_2199:
	s_or_b64 exec, exec, s[20:21]
	s_and_saveexec_b64 s[20:21], vcc
	s_cbranch_execz .Lcv14_2_2201
	v_add3_u32 v14, v0, s6, 2
	v_ashrrev_i32_e32 v15, 31, v14
	v_lshlrev_b64 v[14:15], 11, v[14:15]
	v_lshl_add_u64 v[14:15], v[4:5], 0, v[14:15]
	global_load_dword v217, v[14:15], off nt
.Lcv14_2_2201:
	s_or_b64 exec, exec, s[20:21]
	s_and_saveexec_b64 s[20:21], vcc
	s_cbranch_execz .Lcv14_2_2203
	v_add3_u32 v14, v0, s6, 4
	v_ashrrev_i32_e32 v15, 31, v14
	v_lshlrev_b64 v[14:15], 11, v[14:15]
	v_lshl_add_u64 v[14:15], v[4:5], 0, v[14:15]
	global_load_dword v218, v[14:15], off nt
.Lcv14_2_2203:
	s_or_b64 exec, exec, s[20:21]
	s_and_saveexec_b64 s[20:21], vcc
	s_cbranch_execz .Lcv14_2_2205
	v_add3_u32 v14, v0, s6, 6
	v_ashrrev_i32_e32 v15, 31, v14
	v_lshlrev_b64 v[14:15], 11, v[14:15]
	v_lshl_add_u64 v[14:15], v[4:5], 0, v[14:15]
	global_load_dword v219, v[14:15], off nt
.Lcv14_2_2205:
	s_or_b64 exec, exec, s[20:21]
	s_and_saveexec_b64 s[20:21], vcc
	s_cbranch_execz .Lcv14_2_2207
	v_add3_u32 v14, v0, s6, 8
	v_ashrrev_i32_e32 v15, 31, v14
	v_lshlrev_b64 v[14:15], 11, v[14:15]
	v_lshl_add_u64 v[14:15], v[4:5], 0, v[14:15]
	global_load_dword v220, v[14:15], off nt
.Lcv14_2_2207:
	s_or_b64 exec, exec, s[20:21]
	s_and_saveexec_b64 s[20:21], vcc
	s_cbranch_execz .Lcv14_2_2209
	v_add3_u32 v14, v0, s6, 10
	v_ashrrev_i32_e32 v15, 31, v14
	v_lshlrev_b64 v[14:15], 11, v[14:15]
	v_lshl_add_u64 v[14:15], v[4:5], 0, v[14:15]
	global_load_dword v221, v[14:15], off nt
.Lcv14_2_2209:
	s_or_b64 exec, exec, s[20:21]
	s_and_saveexec_b64 s[20:21], vcc
	s_cbranch_execz .Lcv14_2_2211
	v_add3_u32 v14, v0, s6, 12
	v_ashrrev_i32_e32 v15, 31, v14
	v_lshlrev_b64 v[14:15], 11, v[14:15]
	v_lshl_add_u64 v[14:15], v[4:5], 0, v[14:15]
	global_load_dword v222, v[14:15], off nt
.Lcv14_2_2211:
	s_or_b64 exec, exec, s[20:21]
	s_and_saveexec_b64 s[20:21], vcc
	s_cbranch_execz .Lcv14_2_end
	v_add3_u32 v14, v0, s6, 14
	v_ashrrev_i32_e32 v15, 31, v14
	v_lshlrev_b64 v[14:15], 11, v[14:15]
	v_lshl_add_u64 v[14:15], v[4:5], 0, v[14:15]
	global_load_dword v223, v[14:15], off nt
.Lcv14_2_end:
	s_or_b64 exec, exec, s[20:21]
	s_add_i32 s6, s6, 16
	s_and_saveexec_b64 s[20:21], vcc
	s_cbranch_execz .Lcv14_3_2199
	v_add_u32_e32 v14, s6, v0
	v_ashrrev_i32_e32 v15, 31, v14
	v_lshlrev_b64 v[14:15], 11, v[14:15]
	v_lshl_add_u64 v[14:15], v[4:5], 0, v[14:15]
	global_load_dword v224, v[14:15], off nt
.Lcv14_3_2199:
	s_or_b64 exec, exec, s[20:21]
	s_and_saveexec_b64 s[20:21], vcc
	s_cbranch_execz .Lcv14_3_2201
	v_add3_u32 v14, v0, s6, 2
	v_ashrrev_i32_e32 v15, 31, v14
	v_lshlrev_b64 v[14:15], 11, v[14:15]
	v_lshl_add_u64 v[14:15], v[4:5], 0, v[14:15]
	global_load_dword v225, v[14:15], off nt
.Lcv14_3_2201:
	s_or_b64 exec, exec, s[20:21]
	s_and_saveexec_b64 s[20:21], vcc
	s_cbranch_execz .Lcv14_3_2203
	v_add3_u32 v14, v0, s6, 4
	v_ashrrev_i32_e32 v15, 31, v14
	v_lshlrev_b64 v[14:15], 11, v[14:15]
	v_lshl_add_u64 v[14:15], v[4:5], 0, v[14:15]
	global_load_dword v226, v[14:15], off nt
.Lcv14_3_2203:
	s_or_b64 exec, exec, s[20:21]
	s_and_saveexec_b64 s[20:21], vcc
	s_cbranch_execz .Lcv14_3_2205
	v_add3_u32 v14, v0, s6, 6
	v_ashrrev_i32_e32 v15, 31, v14
	v_lshlrev_b64 v[14:15], 11, v[14:15]
	v_lshl_add_u64 v[14:15], v[4:5], 0, v[14:15]
	global_load_dword v227, v[14:15], off nt
.Lcv14_3_2205:
	s_or_b64 exec, exec, s[20:21]
	s_and_saveexec_b64 s[20:21], vcc
	s_cbranch_execz .Lcv14_3_2207
	v_add3_u32 v14, v0, s6, 8
	v_ashrrev_i32_e32 v15, 31, v14
	v_lshlrev_b64 v[14:15], 11, v[14:15]
	v_lshl_add_u64 v[14:15], v[4:5], 0, v[14:15]
	global_load_dword v228, v[14:15], off nt
.Lcv14_3_2207:
	s_or_b64 exec, exec, s[20:21]
	s_and_saveexec_b64 s[20:21], vcc
	s_cbranch_execz .Lcv14_3_2209
	v_add3_u32 v14, v0, s6, 10
	v_ashrrev_i32_e32 v15, 31, v14
	v_lshlrev_b64 v[14:15], 11, v[14:15]
	v_lshl_add_u64 v[14:15], v[4:5], 0, v[14:15]
	global_load_dword v229, v[14:15], off nt
.Lcv14_3_2209:
	s_or_b64 exec, exec, s[20:21]
	s_and_saveexec_b64 s[20:21], vcc
	s_cbranch_execz .Lcv14_3_2211
	v_add3_u32 v14, v0, s6, 12
	v_ashrrev_i32_e32 v15, 31, v14
	v_lshlrev_b64 v[14:15], 11, v[14:15]
	v_lshl_add_u64 v[14:15], v[4:5], 0, v[14:15]
	global_load_dword v230, v[14:15], off nt
.Lcv14_3_2211:
	s_or_b64 exec, exec, s[20:21]
	s_and_saveexec_b64 s[20:21], vcc
	s_cbranch_execz .Lcv14_3_end
	v_add3_u32 v14, v0, s6, 14
	v_ashrrev_i32_e32 v15, 31, v14
	v_lshlrev_b64 v[14:15], 11, v[14:15]
	v_lshl_add_u64 v[14:15], v[4:5], 0, v[14:15]
	global_load_dword v231, v[14:15], off nt
.Lcv14_3_end:
	s_or_b64 exec, exec, s[20:21]
	s_add_i32 s6, s6, 16
	s_waitcnt vmcnt(0)
	ds_write_b32 v6, v200
	ds_write_b32 v6, v201 offset:264
	ds_write_b32 v6, v202 offset:528
	ds_write_b32 v6, v203 offset:792
	ds_write_b32 v6, v204 offset:1056
	ds_write_b32 v6, v205 offset:1320
	ds_write_b32 v6, v206 offset:1584
	ds_write_b32 v6, v207 offset:1848
	ds_write_b32 v6, v208 offset:2112
	ds_write_b32 v6, v209 offset:2376
	ds_write_b32 v6, v210 offset:2640
	ds_write_b32 v6, v211 offset:2904
	ds_write_b32 v6, v212 offset:3168
	ds_write_b32 v6, v213 offset:3432
	ds_write_b32 v6, v214 offset:3696
	ds_write_b32 v6, v215 offset:3960
	ds_write_b32 v6, v216 offset:4224
	ds_write_b32 v6, v217 offset:4488
	ds_write_b32 v6, v218 offset:4752
	ds_write_b32 v6, v219 offset:5016
	ds_write_b32 v6, v220 offset:5280
	ds_write_b32 v6, v221 offset:5544
	ds_write_b32 v6, v222 offset:5808
	ds_write_b32 v6, v223 offset:6072
	ds_write_b32 v6, v224 offset:6336
	ds_write_b32 v6, v225 offset:6600
	ds_write_b32 v6, v226 offset:6864
	ds_write_b32 v6, v227 offset:7128
	ds_write_b32 v6, v228 offset:7392
	ds_write_b32 v6, v229 offset:7656
	ds_write_b32 v6, v230 offset:7920
	ds_write_b32 v6, v231 offset:8184
	s_branch .LBB0_2194

.LBB0_2218:
	v_mov_b32_e32 v200, 0
	v_mov_b32_e32 v201, 0
	v_mov_b32_e32 v202, 0
	v_mov_b32_e32 v203, 0
	v_mov_b32_e32 v204, 0
	v_mov_b32_e32 v205, 0
	v_mov_b32_e32 v206, 0
	v_mov_b32_e32 v207, 0
	v_mov_b32_e32 v208, 0
	v_mov_b32_e32 v209, 0
	v_mov_b32_e32 v210, 0
	v_mov_b32_e32 v211, 0
	v_mov_b32_e32 v212, 0
	v_mov_b32_e32 v213, 0
	v_mov_b32_e32 v214, 0
	v_mov_b32_e32 v215, 0
	v_mov_b32_e32 v216, 0
	v_mov_b32_e32 v217, 0
	v_mov_b32_e32 v218, 0
	v_mov_b32_e32 v219, 0
	v_mov_b32_e32 v220, 0
	v_mov_b32_e32 v221, 0
	v_mov_b32_e32 v222, 0
	v_mov_b32_e32 v223, 0
	v_mov_b32_e32 v224, 0
	v_mov_b32_e32 v225, 0
	v_mov_b32_e32 v226, 0
	v_mov_b32_e32 v227, 0
	v_mov_b32_e32 v228, 0
	v_mov_b32_e32 v229, 0
	v_mov_b32_e32 v230, 0
	v_mov_b32_e32 v231, 0
	s_and_saveexec_b64 s[20:21], vcc
	s_cbranch_execz .Lcv15_0_2220
	v_add_u32_e32 v10, s6, v0
	v_ashrrev_i32_e32 v11, 31, v10
	v_lshlrev_b64 v[10:11], 11, v[10:11]
	v_lshl_add_u64 v[10:11], v[4:5], 0, v[10:11]
	global_load_dword v200, v[10:11], off nt

.Lcv15_0_end:
	s_or_b64 exec, exec, s[20:21]
	s_add_i32 s6, s6, 16
	s_and_saveexec_b64 s[20:21], vcc
	s_cbranch_execz .Lcv15_1_2220
	v_add_u32_e32 v10, s6, v0
	v_ashrrev_i32_e32 v11, 31, v10
	v_lshlrev_b64 v[10:11], 11, v[10:11]
	v_lshl_add_u64 v[10:11], v[4:5], 0, v[10:11]
	global_load_dword v208, v[10:11], off nt
.Lcv15_1_2220:
	s_or_b64 exec, exec, s[20:21]
	s_and_saveexec_b64 s[20:21], vcc
	s_cbranch_execz .Lcv15_1_2222
	v_add3_u32 v10, v0, s6, 2
	v_ashrrev_i32_e32 v11, 31, v10
	v_lshlrev_b64 v[10:11], 11, v[10:11]
	v_lshl_add_u64 v[10:11], v[4:5], 0, v[10:11]
	global_load_dword v209, v[10:11], off nt
.Lcv15_1_2222:
	s_or_b64 exec, exec, s[20:21]
	s_and_saveexec_b64 s[20:21], vcc
	s_cbranch_execz .Lcv15_1_2224
	v_add3_u32 v10, v0, s6, 4
	v_ashrrev_i32_e32 v11, 31, v10
	v_lshlrev_b64 v[10:11], 11, v[10:11]
	v_lshl_add_u64 v[10:11], v[4:5], 0, v[10:11]
	global_load_dword v210, v[10:11], off nt
.Lcv15_1_2224:
	s_or_b64 exec, exec, s[20:21]
	s_and_saveexec_b64 s[20:21], vcc
	s_cbranch_execz .Lcv15_1_2226
	v_add3_u32 v10, v0, s6, 6
	v_ashrrev_i32_e32 v11, 31, v10
	v_lshlrev_b64 v[10:11], 11, v[10:11]
	v_lshl_add_u64 v[10:11], v[4:5], 0, v[10:11]
	global_load_dword v211, v[10:11], off nt
.Lcv15_1_2226:
	s_or_b64 exec, exec, s[20:21]
	s_and_saveexec_b64 s[20:21], vcc
	s_cbranch_execz .Lcv15_1_2228
	v_add3_u32 v10, v0, s6, 8
	v_ashrrev_i32_e32 v11, 31, v10
	v_lshlrev_b64 v[10:11], 11, v[10:11]
	v_lshl_add_u64 v[10:11], v[4:5], 0, v[10:11]
	global_load_dword v212, v[10:11], off nt
.Lcv15_1_2228:
	s_or_b64 exec, exec, s[20:21]
	s_and_saveexec_b64 s[20:21], vcc
	s_cbranch_execz .Lcv15_1_2230
	v_add3_u32 v10, v0, s6, 10
	v_ashrrev_i32_e32 v11, 31, v10
	v_lshlrev_b64 v[10:11], 11, v[10:11]
	v_lshl_add_u64 v[10:11], v[4:5], 0, v[10:11]
	global_load_dword v213, v[10:11], off nt
.Lcv15_1_2230:
	s_or_b64 exec, exec, s[20:21]
	s_and_saveexec_b64 s[20:21], vcc
	s_cbranch_execz .Lcv15_1_2232
	v_add3_u32 v10, v0, s6, 12
	v_ashrrev_i32_e32 v11, 31, v10
	v_lshlrev_b64 v[10:11], 11, v[10:11]
	v_lshl_add_u64 v[10:11], v[4:5], 0, v[10:11]
	global_load_dword v214, v[10:11], off nt
.Lcv15_1_2232:
	s_or_b64 exec, exec, s[20:21]
	s_and_saveexec_b64 s[20:21], vcc
	s_cbranch_execz .Lcv15_1_end
	v_add3_u32 v10, v0, s6, 14
	v_ashrrev_i32_e32 v11, 31, v10
	v_lshlrev_b64 v[10:11], 11, v[10:11]
	v_lshl_add_u64 v[10:11], v[4:5], 0, v[10:11]
	global_load_dword v215, v[10:11], off nt
.Lcv15_1_end:
	s_or_b64 exec, exec, s[20:21]
	s_add_i32 s6, s6, 16
	s_and_saveexec_b64 s[20:21], vcc
	s_cbranch_execz .Lcv15_2_2220
	v_add_u32_e32 v10, s6, v0
	v_ashrrev_i32_e32 v11, 31, v10
	v_lshlrev_b64 v[10:11], 11, v[10:11]
	v_lshl_add_u64 v[10:11], v[4:5], 0, v[10:11]
	global_load_dword v216, v[10:11], off nt
.Lcv15_2_2220:
	s_or_b64 exec, exec, s[20:21]
	s_and_saveexec_b64 s[20:21], vcc
	s_cbranch_execz .Lcv15_2_2222
	v_add3_u32 v10, v0, s6, 2
	v_ashrrev_i32_e32 v11, 31, v10
	v_lshlrev_b64 v[10:11], 11, v[10:11]
	v_lshl_add_u64 v[10:11], v[4:5], 0, v[10:11]
	global_load_dword v217, v[10:11], off nt
.Lcv15_2_2222:
	s_or_b64 exec, exec, s[20:21]
	s_and_saveexec_b64 s[20:21], vcc
	s_cbranch_execz .Lcv15_2_2224
	v_add3_u32 v10, v0, s6, 4
	v_ashrrev_i32_e32 v11, 31, v10
	v_lshlrev_b64 v[10:11], 11, v[10:11]
	v_lshl_add_u64 v[10:11], v[4:5], 0, v[10:11]
	global_load_dword v218, v[10:11], off nt
.Lcv15_2_2224:
	s_or_b64 exec, exec, s[20:21]
	s_and_saveexec_b64 s[20:21], vcc
	s_cbranch_execz .Lcv15_2_2226
	v_add3_u32 v10, v0, s6, 6
	v_ashrrev_i32_e32 v11, 31, v10
	v_lshlrev_b64 v[10:11], 11, v[10:11]
	v_lshl_add_u64 v[10:11], v[4:5], 0, v[10:11]
	global_load_dword v219, v[10:11], off nt
.Lcv15_2_2226:
	s_or_b64 exec, exec, s[20:21]
	s_and_saveexec_b64 s[20:21], vcc
	s_cbranch_execz .Lcv15_2_2228
	v_add3_u32 v10, v0, s6, 8
	v_ashrrev_i32_e32 v11, 31, v10
	v_lshlrev_b64 v[10:11], 11, v[10:11]
	v_lshl_add_u64 v[10:11], v[4:5], 0, v[10:11]
	global_load_dword v220, v[10:11], off nt
.Lcv15_2_2228:
	s_or_b64 exec, exec, s[20:21]
	s_and_saveexec_b64 s[20:21], vcc
	s_cbranch_execz .Lcv15_2_2230
	v_add3_u32 v10, v0, s6, 10
	v_ashrrev_i32_e32 v11, 31, v10
	v_lshlrev_b64 v[10:11], 11, v[10:11]
	v_lshl_add_u64 v[10:11], v[4:5], 0, v[10:11]
	global_load_dword v221, v[10:11], off nt
.Lcv15_2_2230:
	s_or_b64 exec, exec, s[20:21]
	s_and_saveexec_b64 s[20:21], vcc
	s_cbranch_execz .Lcv15_2_2232
	v_add3_u32 v10, v0, s6, 12
	v_ashrrev_i32_e32 v11, 31, v10
	v_lshlrev_b64 v[10:11], 11, v[10:11]
	v_lshl_add_u64 v[10:11], v[4:5], 0, v[10:11]
	global_load_dword v222, v[10:11], off nt
.Lcv15_2_2232:
	s_or_b64 exec, exec, s[20:21]
	s_and_saveexec_b64 s[20:21], vcc
	s_cbranch_execz .Lcv15_2_end
	v_add3_u32 v10, v0, s6, 14
	v_ashrrev_i32_e32 v11, 31, v10
	v_lshlrev_b64 v[10:11], 11, v[10:11]
	v_lshl_add_u64 v[10:11], v[4:5], 0, v[10:11]
	global_load_dword v223, v[10:11], off nt
.Lcv15_2_end:
	s_or_b64 exec, exec, s[20:21]
	s_add_i32 s6, s6, 16
	s_and_saveexec_b64 s[20:21], vcc
	s_cbranch_execz .Lcv15_3_2220
	v_add_u32_e32 v10, s6, v0
	v_ashrrev_i32_e32 v11, 31, v10
	v_lshlrev_b64 v[10:11], 11, v[10:11]
	v_lshl_add_u64 v[10:11], v[4:5], 0, v[10:11]
	global_load_dword v224, v[10:11], off nt
.Lcv15_3_2220:
	s_or_b64 exec, exec, s[20:21]
	s_and_saveexec_b64 s[20:21], vcc
	s_cbranch_execz .Lcv15_3_2222
	v_add3_u32 v10, v0, s6, 2
	v_ashrrev_i32_e32 v11, 31, v10
	v_lshlrev_b64 v[10:11], 11, v[10:11]
	v_lshl_add_u64 v[10:11], v[4:5], 0, v[10:11]
	global_load_dword v225, v[10:11], off nt
.Lcv15_3_2222:
	s_or_b64 exec, exec, s[20:21]
	s_and_saveexec_b64 s[20:21], vcc
	s_cbranch_execz .Lcv15_3_2224
	v_add3_u32 v10, v0, s6, 4
	v_ashrrev_i32_e32 v11, 31, v10
	v_lshlrev_b64 v[10:11], 11, v[10:11]
	v_lshl_add_u64 v[10:11], v[4:5], 0, v[10:11]
	global_load_dword v226, v[10:11], off nt
.Lcv15_3_2224:
	s_or_b64 exec, exec, s[20:21]
	s_and_saveexec_b64 s[20:21], vcc
	s_cbranch_execz .Lcv15_3_2226
	v_add3_u32 v10, v0, s6, 6
	v_ashrrev_i32_e32 v11, 31, v10
	v_lshlrev_b64 v[10:11], 11, v[10:11]
	v_lshl_add_u64 v[10:11], v[4:5], 0, v[10:11]
	global_load_dword v227, v[10:11], off nt
.Lcv15_3_2226:
	s_or_b64 exec, exec, s[20:21]
	s_and_saveexec_b64 s[20:21], vcc
	s_cbranch_execz .Lcv15_3_2228
	v_add3_u32 v10, v0, s6, 8
	v_ashrrev_i32_e32 v11, 31, v10
	v_lshlrev_b64 v[10:11], 11, v[10:11]
	v_lshl_add_u64 v[10:11], v[4:5], 0, v[10:11]
	global_load_dword v228, v[10:11], off nt
.Lcv15_3_2228:
	s_or_b64 exec, exec, s[20:21]
	s_and_saveexec_b64 s[20:21], vcc
	s_cbranch_execz .Lcv15_3_2230
	v_add3_u32 v10, v0, s6, 10
	v_ashrrev_i32_e32 v11, 31, v10
	v_lshlrev_b64 v[10:11], 11, v[10:11]
	v_lshl_add_u64 v[10:11], v[4:5], 0, v[10:11]
	global_load_dword v229, v[10:11], off nt
.Lcv15_3_2230:
	s_or_b64 exec, exec, s[20:21]
	s_and_saveexec_b64 s[20:21], vcc
	s_cbranch_execz .Lcv15_3_2232
	v_add3_u32 v10, v0, s6, 12
	v_ashrrev_i32_e32 v11, 31, v10
	v_lshlrev_b64 v[10:11], 11, v[10:11]
	v_lshl_add_u64 v[10:11], v[4:5], 0, v[10:11]
	global_load_dword v230, v[10:11], off nt
.Lcv15_3_2232:
	s_or_b64 exec, exec, s[20:21]
	s_and_saveexec_b64 s[20:21], vcc
	s_cbranch_execz .Lcv15_3_end
	v_add3_u32 v10, v0, s6, 14
	v_ashrrev_i32_e32 v11, 31, v10
	v_lshlrev_b64 v[10:11], 11, v[10:11]
	v_lshl_add_u64 v[10:11], v[4:5], 0, v[10:11]
	global_load_dword v231, v[10:11], off nt

.LBB0_2239:
	v_mov_b32_e32 v200, 0
	v_mov_b32_e32 v201, 0
	v_mov_b32_e32 v202, 0
	v_mov_b32_e32 v203, 0
	v_mov_b32_e32 v204, 0
	v_mov_b32_e32 v205, 0
	v_mov_b32_e32 v206, 0
	v_mov_b32_e32 v207, 0
	v_mov_b32_e32 v208, 0
	v_mov_b32_e32 v209, 0
	v_mov_b32_e32 v210, 0
	v_mov_b32_e32 v211, 0
	v_mov_b32_e32 v212, 0
	v_mov_b32_e32 v213, 0
	v_mov_b32_e32 v214, 0
	v_mov_b32_e32 v215, 0
	v_mov_b32_e32 v216, 0
	v_mov_b32_e32 v217, 0
	v_mov_b32_e32 v218, 0
	v_mov_b32_e32 v219, 0
	v_mov_b32_e32 v220, 0
	v_mov_b32_e32 v221, 0
	v_mov_b32_e32 v222, 0
	v_mov_b32_e32 v223, 0
	v_mov_b32_e32 v224, 0
	v_mov_b32_e32 v225, 0
	v_mov_b32_e32 v226, 0
	v_mov_b32_e32 v227, 0
	v_mov_b32_e32 v228, 0
	v_mov_b32_e32 v229, 0
	v_mov_b32_e32 v230, 0
	v_mov_b32_e32 v231, 0
	s_and_b64 vcc, exec, s[10:11]
	s_cbranch_vccnz .Lcv16_0_2241
	v_lshl_add_u64 v[34:35], v[18:19], 0, s[22:23]
	global_load_dword v200, v[34:35], off nt

.Lcv16_0_end:
	s_add_u32 s22, s22, 0x58000
	s_addc_u32 s23, s23, 0
	s_and_b64 vcc, exec, s[10:11]
	s_cbranch_vccnz .Lcv16_1_2241
	v_lshl_add_u64 v[34:35], v[18:19], 0, s[22:23]
	global_load_dword v208, v[34:35], off nt
.Lcv16_1_2241:
	s_and_b64 vcc, exec, s[10:11]
	s_cbranch_vccnz .Lcv16_1_2243
	v_lshl_add_u64 v[34:35], v[16:17], 0, s[22:23]
	global_load_dword v209, v[34:35], off nt
.Lcv16_1_2243:
	s_and_b64 vcc, exec, s[10:11]
	s_cbranch_vccnz .Lcv16_1_2245
	v_lshl_add_u64 v[34:35], v[14:15], 0, s[22:23]
	global_load_dword v210, v[34:35], off nt
.Lcv16_1_2245:
	s_and_b64 vcc, exec, s[10:11]
	s_cbranch_vccnz .Lcv16_1_2247
	v_lshl_add_u64 v[34:35], v[12:13], 0, s[22:23]
	global_load_dword v211, v[34:35], off nt
.Lcv16_1_2247:
	s_and_b64 vcc, exec, s[10:11]
	s_cbranch_vccnz .Lcv16_1_2249
	v_lshl_add_u64 v[34:35], v[10:11], 0, s[22:23]
	global_load_dword v212, v[34:35], off nt
.Lcv16_1_2249:
	s_and_b64 vcc, exec, s[10:11]
	s_cbranch_vccnz .Lcv16_1_2251
	v_lshl_add_u64 v[34:35], v[8:9], 0, s[22:23]
	global_load_dword v213, v[34:35], off nt
.Lcv16_1_2251:
	s_and_b64 vcc, exec, s[10:11]
	s_cbranch_vccnz .Lcv16_1_2253
	v_lshl_add_u64 v[34:35], v[6:7], 0, s[22:23]
	global_load_dword v214, v[34:35], off nt
.Lcv16_1_2253:
	s_and_b64 vcc, exec, s[10:11]
	s_cbranch_vccnz .Lcv16_1_end
	v_lshl_add_u64 v[34:35], v[4:5], 0, s[22:23]
	global_load_dword v215, v[34:35], off nt
.Lcv16_1_end:
	s_add_u32 s22, s22, 0x58000
	s_addc_u32 s23, s23, 0
	s_and_b64 vcc, exec, s[10:11]
	s_cbranch_vccnz .Lcv16_2_2241
	v_lshl_add_u64 v[34:35], v[18:19], 0, s[22:23]
	global_load_dword v216, v[34:35], off nt
.Lcv16_2_2241:
	s_and_b64 vcc, exec, s[10:11]
	s_cbranch_vccnz .Lcv16_2_2243
	v_lshl_add_u64 v[34:35], v[16:17], 0, s[22:23]
	global_load_dword v217, v[34:35], off nt
.Lcv16_2_2243:
	s_and_b64 vcc, exec, s[10:11]
	s_cbranch_vccnz .Lcv16_2_2245
	v_lshl_add_u64 v[34:35], v[14:15], 0, s[22:23]
	global_load_dword v218, v[34:35], off nt
.Lcv16_2_2245:
	s_and_b64 vcc, exec, s[10:11]
	s_cbranch_vccnz .Lcv16_2_2247
	v_lshl_add_u64 v[34:35], v[12:13], 0, s[22:23]
	global_load_dword v219, v[34:35], off nt
.Lcv16_2_2247:
	s_and_b64 vcc, exec, s[10:11]
	s_cbranch_vccnz .Lcv16_2_2249
	v_lshl_add_u64 v[34:35], v[10:11], 0, s[22:23]
	global_load_dword v220, v[34:35], off nt
.Lcv16_2_2249:
	s_and_b64 vcc, exec, s[10:11]
	s_cbranch_vccnz .Lcv16_2_2251
	v_lshl_add_u64 v[34:35], v[8:9], 0, s[22:23]
	global_load_dword v221, v[34:35], off nt
.Lcv16_2_2251:
	s_and_b64 vcc, exec, s[10:11]
	s_cbranch_vccnz .Lcv16_2_2253
	v_lshl_add_u64 v[34:35], v[6:7], 0, s[22:23]
	global_load_dword v222, v[34:35], off nt
.Lcv16_2_2253:
	s_and_b64 vcc, exec, s[10:11]
	s_cbranch_vccnz .Lcv16_2_end
	v_lshl_add_u64 v[34:35], v[4:5], 0, s[22:23]
	global_load_dword v223, v[34:35], off nt
.Lcv16_2_end:
	s_add_u32 s22, s22, 0x58000
	s_addc_u32 s23, s23, 0
	s_and_b64 vcc, exec, s[10:11]
	s_cbranch_vccnz .Lcv16_3_2241
	v_lshl_add_u64 v[34:35], v[18:19], 0, s[22:23]
	global_load_dword v224, v[34:35], off nt
.Lcv16_3_2241:
	s_and_b64 vcc, exec, s[10:11]
	s_cbranch_vccnz .Lcv16_3_2243
	v_lshl_add_u64 v[34:35], v[16:17], 0, s[22:23]
	global_load_dword v225, v[34:35], off nt
.Lcv16_3_2243:
	s_and_b64 vcc, exec, s[10:11]
	s_cbranch_vccnz .Lcv16_3_2245
	v_lshl_add_u64 v[34:35], v[14:15], 0, s[22:23]
	global_load_dword v226, v[34:35], off nt
.Lcv16_3_2245:
	s_and_b64 vcc, exec, s[10:11]
	s_cbranch_vccnz .Lcv16_3_2247
	v_lshl_add_u64 v[34:35], v[12:13], 0, s[22:23]
	global_load_dword v227, v[34:35], off nt
.Lcv16_3_2247:
	s_and_b64 vcc, exec, s[10:11]
	s_cbranch_vccnz .Lcv16_3_2249
	v_lshl_add_u64 v[34:35], v[10:11], 0, s[22:23]
	global_load_dword v228, v[34:35], off nt
.Lcv16_3_2249:
	s_and_b64 vcc, exec, s[10:11]
	s_cbranch_vccnz .Lcv16_3_2251
	v_lshl_add_u64 v[34:35], v[8:9], 0, s[22:23]
	global_load_dword v229, v[34:35], off nt
.Lcv16_3_2251:
	s_and_b64 vcc, exec, s[10:11]
	s_cbranch_vccnz .Lcv16_3_2253
	v_lshl_add_u64 v[34:35], v[6:7], 0, s[22:23]
	global_load_dword v230, v[34:35], off nt
.Lcv16_3_2253:
	s_and_b64 vcc, exec, s[10:11]
	s_cbranch_vccnz .Lcv16_3_end
	v_lshl_add_u64 v[34:35], v[4:5], 0, s[22:23]
	global_load_dword v231, v[34:35], off nt
.Lcv16_3_end:
	s_add_u32 s22, s22, 0x58000
	s_addc_u32 s23, s23, 0
	s_waitcnt vmcnt(0)
	ds_write_b32 v0, v200
	ds_write_b32 v0, v201 offset:264
	ds_write_b32 v0, v202 offset:528
	ds_write_b32 v0, v203 offset:792
	ds_write_b32 v0, v204 offset:1056
	ds_write_b32 v0, v205 offset:1320
	ds_write_b32 v0, v206 offset:1584
	ds_write_b32 v0, v207 offset:1848
	ds_write_b32 v0, v208 offset:2112
	ds_write_b32 v0, v209 offset:2376
	ds_write_b32 v0, v210 offset:2640
	ds_write_b32 v0, v211 offset:2904
	ds_write_b32 v0, v212 offset:3168
	ds_write_b32 v0, v213 offset:3432
	ds_write_b32 v0, v214 offset:3696
	ds_write_b32 v0, v215 offset:3960
	ds_write_b32 v0, v216 offset:4224
	ds_write_b32 v0, v217 offset:4488
	ds_write_b32 v0, v218 offset:4752
	ds_write_b32 v0, v219 offset:5016
	ds_write_b32 v0, v220 offset:5280
	ds_write_b32 v0, v221 offset:5544
	ds_write_b32 v0, v222 offset:5808
	ds_write_b32 v0, v223 offset:6072
	ds_write_b32 v0, v224 offset:6336
	ds_write_b32 v0, v225 offset:6600
	ds_write_b32 v0, v226 offset:6864
	ds_write_b32 v0, v227 offset:7128
	ds_write_b32 v0, v228 offset:7392
	ds_write_b32 v0, v229 offset:7656
	ds_write_b32 v0, v230 offset:7920
	ds_write_b32 v0, v231 offset:8184
	s_branch .LBB0_2236

.LBB0_2260:
	v_mov_b32_e32 v200, 0
	v_mov_b32_e32 v201, 0
	v_mov_b32_e32 v202, 0
	v_mov_b32_e32 v203, 0
	v_mov_b32_e32 v204, 0
	v_mov_b32_e32 v205, 0
	v_mov_b32_e32 v206, 0
	v_mov_b32_e32 v207, 0
	v_mov_b32_e32 v208, 0
	v_mov_b32_e32 v209, 0
	v_mov_b32_e32 v210, 0
	v_mov_b32_e32 v211, 0
	v_mov_b32_e32 v212, 0
	v_mov_b32_e32 v213, 0
	v_mov_b32_e32 v214, 0
	v_mov_b32_e32 v215, 0
	v_mov_b32_e32 v216, 0
	v_mov_b32_e32 v217, 0
	v_mov_b32_e32 v218, 0
	v_mov_b32_e32 v219, 0
	v_mov_b32_e32 v220, 0
	v_mov_b32_e32 v221, 0
	v_mov_b32_e32 v222, 0
	v_mov_b32_e32 v223, 0
	v_mov_b32_e32 v224, 0
	v_mov_b32_e32 v225, 0
	v_mov_b32_e32 v226, 0
	v_mov_b32_e32 v227, 0
	v_mov_b32_e32 v228, 0
	v_mov_b32_e32 v229, 0
	v_mov_b32_e32 v230, 0
	v_mov_b32_e32 v231, 0
	s_and_saveexec_b64 s[16:17], vcc
	s_cbranch_execz .Lcv17_0_2262
	v_add_u32_e32 v10, s4, v0
	v_ashrrev_i32_e32 v11, 31, v10
	v_lshlrev_b64 v[10:11], 12, v[10:11]
	v_lshl_add_u64 v[10:11], v[4:5], 0, v[10:11]
	global_load_dword v200, v[10:11], off nt

.Lcv17_0_end:
	s_or_b64 exec, exec, s[16:17]
	s_add_i32 s4, s4, 16
	s_and_saveexec_b64 s[16:17], vcc
	s_cbranch_execz .Lcv17_1_2262
	v_add_u32_e32 v10, s4, v0
	v_ashrrev_i32_e32 v11, 31, v10
	v_lshlrev_b64 v[10:11], 12, v[10:11]
	v_lshl_add_u64 v[10:11], v[4:5], 0, v[10:11]
	global_load_dword v208, v[10:11], off nt
.Lcv17_1_2262:
	s_or_b64 exec, exec, s[16:17]
	s_and_saveexec_b64 s[16:17], vcc
	s_cbranch_execz .Lcv17_1_2264
	v_add3_u32 v10, v0, s4, 2
	v_ashrrev_i32_e32 v11, 31, v10
	v_lshlrev_b64 v[10:11], 12, v[10:11]
	v_lshl_add_u64 v[10:11], v[4:5], 0, v[10:11]
	global_load_dword v209, v[10:11], off nt
.Lcv17_1_2264:
	s_or_b64 exec, exec, s[16:17]
	s_and_saveexec_b64 s[16:17], vcc
	s_cbranch_execz .Lcv17_1_2266
	v_add3_u32 v10, v0, s4, 4
	v_ashrrev_i32_e32 v11, 31, v10
	v_lshlrev_b64 v[10:11], 12, v[10:11]
	v_lshl_add_u64 v[10:11], v[4:5], 0, v[10:11]
	global_load_dword v210, v[10:11], off nt
.Lcv17_1_2266:
	s_or_b64 exec, exec, s[16:17]
	s_and_saveexec_b64 s[16:17], vcc
	s_cbranch_execz .Lcv17_1_2268
	v_add3_u32 v10, v0, s4, 6
	v_ashrrev_i32_e32 v11, 31, v10
	v_lshlrev_b64 v[10:11], 12, v[10:11]
	v_lshl_add_u64 v[10:11], v[4:5], 0, v[10:11]
	global_load_dword v211, v[10:11], off nt
.Lcv17_1_2268:
	s_or_b64 exec, exec, s[16:17]
	s_and_saveexec_b64 s[16:17], vcc
	s_cbranch_execz .Lcv17_1_2270
	v_add3_u32 v10, v0, s4, 8
	v_ashrrev_i32_e32 v11, 31, v10
	v_lshlrev_b64 v[10:11], 12, v[10:11]
	v_lshl_add_u64 v[10:11], v[4:5], 0, v[10:11]
	global_load_dword v212, v[10:11], off nt
.Lcv17_1_2270:
	s_or_b64 exec, exec, s[16:17]
	s_and_saveexec_b64 s[16:17], vcc
	s_cbranch_execz .Lcv17_1_2272
	v_add3_u32 v10, v0, s4, 10
	v_ashrrev_i32_e32 v11, 31, v10
	v_lshlrev_b64 v[10:11], 12, v[10:11]
	v_lshl_add_u64 v[10:11], v[4:5], 0, v[10:11]
	global_load_dword v213, v[10:11], off nt
.Lcv17_1_2272:
	s_or_b64 exec, exec, s[16:17]
	s_and_saveexec_b64 s[16:17], vcc
	s_cbranch_execz .Lcv17_1_2274
	v_add3_u32 v10, v0, s4, 12
	v_ashrrev_i32_e32 v11, 31, v10
	v_lshlrev_b64 v[10:11], 12, v[10:11]
	v_lshl_add_u64 v[10:11], v[4:5], 0, v[10:11]
	global_load_dword v214, v[10:11], off nt
.Lcv17_1_2274:
	s_or_b64 exec, exec, s[16:17]
	s_and_saveexec_b64 s[16:17], vcc
	s_cbranch_execz .Lcv17_1_end
	v_add3_u32 v10, v0, s4, 14
	v_ashrrev_i32_e32 v11, 31, v10
	v_lshlrev_b64 v[10:11], 12, v[10:11]
	v_lshl_add_u64 v[10:11], v[4:5], 0, v[10:11]
	global_load_dword v215, v[10:11], off nt
.Lcv17_1_end:
	s_or_b64 exec, exec, s[16:17]
	s_add_i32 s4, s4, 16
	s_and_saveexec_b64 s[16:17], vcc
	s_cbranch_execz .Lcv17_2_2262
	v_add_u32_e32 v10, s4, v0
	v_ashrrev_i32_e32 v11, 31, v10
	v_lshlrev_b64 v[10:11], 12, v[10:11]
	v_lshl_add_u64 v[10:11], v[4:5], 0, v[10:11]
	global_load_dword v216, v[10:11], off nt
.Lcv17_2_2262:
	s_or_b64 exec, exec, s[16:17]
	s_and_saveexec_b64 s[16:17], vcc
	s_cbranch_execz .Lcv17_2_2264
	v_add3_u32 v10, v0, s4, 2
	v_ashrrev_i32_e32 v11, 31, v10
	v_lshlrev_b64 v[10:11], 12, v[10:11]
	v_lshl_add_u64 v[10:11], v[4:5], 0, v[10:11]
	global_load_dword v217, v[10:11], off nt
.Lcv17_2_2264:
	s_or_b64 exec, exec, s[16:17]
	s_and_saveexec_b64 s[16:17], vcc
	s_cbranch_execz .Lcv17_2_2266
	v_add3_u32 v10, v0, s4, 4
	v_ashrrev_i32_e32 v11, 31, v10
	v_lshlrev_b64 v[10:11], 12, v[10:11]
	v_lshl_add_u64 v[10:11], v[4:5], 0, v[10:11]
	global_load_dword v218, v[10:11], off nt
.Lcv17_2_2266:
	s_or_b64 exec, exec, s[16:17]
	s_and_saveexec_b64 s[16:17], vcc
	s_cbranch_execz .Lcv17_2_2268
	v_add3_u32 v10, v0, s4, 6
	v_ashrrev_i32_e32 v11, 31, v10
	v_lshlrev_b64 v[10:11], 12, v[10:11]
	v_lshl_add_u64 v[10:11], v[4:5], 0, v[10:11]
	global_load_dword v219, v[10:11], off nt
.Lcv17_2_2268:
	s_or_b64 exec, exec, s[16:17]
	s_and_saveexec_b64 s[16:17], vcc
	s_cbranch_execz .Lcv17_2_2270
	v_add3_u32 v10, v0, s4, 8
	v_ashrrev_i32_e32 v11, 31, v10
	v_lshlrev_b64 v[10:11], 12, v[10:11]
	v_lshl_add_u64 v[10:11], v[4:5], 0, v[10:11]
	global_load_dword v220, v[10:11], off nt
.Lcv17_2_2270:
	s_or_b64 exec, exec, s[16:17]
	s_and_saveexec_b64 s[16:17], vcc
	s_cbranch_execz .Lcv17_2_2272
	v_add3_u32 v10, v0, s4, 10
	v_ashrrev_i32_e32 v11, 31, v10
	v_lshlrev_b64 v[10:11], 12, v[10:11]
	v_lshl_add_u64 v[10:11], v[4:5], 0, v[10:11]
	global_load_dword v221, v[10:11], off nt
.Lcv17_2_2272:
	s_or_b64 exec, exec, s[16:17]
	s_and_saveexec_b64 s[16:17], vcc
	s_cbranch_execz .Lcv17_2_2274
	v_add3_u32 v10, v0, s4, 12
	v_ashrrev_i32_e32 v11, 31, v10
	v_lshlrev_b64 v[10:11], 12, v[10:11]
	v_lshl_add_u64 v[10:11], v[4:5], 0, v[10:11]
	global_load_dword v222, v[10:11], off nt
.Lcv17_2_2274:
	s_or_b64 exec, exec, s[16:17]
	s_and_saveexec_b64 s[16:17], vcc
	s_cbranch_execz .Lcv17_2_end
	v_add3_u32 v10, v0, s4, 14
	v_ashrrev_i32_e32 v11, 31, v10
	v_lshlrev_b64 v[10:11], 12, v[10:11]
	v_lshl_add_u64 v[10:11], v[4:5], 0, v[10:11]
	global_load_dword v223, v[10:11], off nt
.Lcv17_2_end:
	s_or_b64 exec, exec, s[16:17]
	s_add_i32 s4, s4, 16
	s_and_saveexec_b64 s[16:17], vcc
	s_cbranch_execz .Lcv17_3_2262
	v_add_u32_e32 v10, s4, v0
	v_ashrrev_i32_e32 v11, 31, v10
	v_lshlrev_b64 v[10:11], 12, v[10:11]
	v_lshl_add_u64 v[10:11], v[4:5], 0, v[10:11]
	global_load_dword v224, v[10:11], off nt
.Lcv17_3_2262:
	s_or_b64 exec, exec, s[16:17]
	s_and_saveexec_b64 s[16:17], vcc
	s_cbranch_execz .Lcv17_3_2264
	v_add3_u32 v10, v0, s4, 2
	v_ashrrev_i32_e32 v11, 31, v10
	v_lshlrev_b64 v[10:11], 12, v[10:11]
	v_lshl_add_u64 v[10:11], v[4:5], 0, v[10:11]
	global_load_dword v225, v[10:11], off nt
.Lcv17_3_2264:
	s_or_b64 exec, exec, s[16:17]
	s_and_saveexec_b64 s[16:17], vcc
	s_cbranch_execz .Lcv17_3_2266
	v_add3_u32 v10, v0, s4, 4
	v_ashrrev_i32_e32 v11, 31, v10
	v_lshlrev_b64 v[10:11], 12, v[10:11]
	v_lshl_add_u64 v[10:11], v[4:5], 0, v[10:11]
	global_load_dword v226, v[10:11], off nt
.Lcv17_3_2266:
	s_or_b64 exec, exec, s[16:17]
	s_and_saveexec_b64 s[16:17], vcc
	s_cbranch_execz .Lcv17_3_2268
	v_add3_u32 v10, v0, s4, 6
	v_ashrrev_i32_e32 v11, 31, v10
	v_lshlrev_b64 v[10:11], 12, v[10:11]
	v_lshl_add_u64 v[10:11], v[4:5], 0, v[10:11]
	global_load_dword v227, v[10:11], off nt
.Lcv17_3_2268:
	s_or_b64 exec, exec, s[16:17]
	s_and_saveexec_b64 s[16:17], vcc
	s_cbranch_execz .Lcv17_3_2270
	v_add3_u32 v10, v0, s4, 8
	v_ashrrev_i32_e32 v11, 31, v10
	v_lshlrev_b64 v[10:11], 12, v[10:11]
	v_lshl_add_u64 v[10:11], v[4:5], 0, v[10:11]
	global_load_dword v228, v[10:11], off nt
.Lcv17_3_2270:
	s_or_b64 exec, exec, s[16:17]
	s_and_saveexec_b64 s[16:17], vcc
	s_cbranch_execz .Lcv17_3_2272
	v_add3_u32 v10, v0, s4, 10
	v_ashrrev_i32_e32 v11, 31, v10
	v_lshlrev_b64 v[10:11], 12, v[10:11]
	v_lshl_add_u64 v[10:11], v[4:5], 0, v[10:11]
	global_load_dword v229, v[10:11], off nt
.Lcv17_3_2272:
	s_or_b64 exec, exec, s[16:17]
	s_and_saveexec_b64 s[16:17], vcc
	s_cbranch_execz .Lcv17_3_2274
	v_add3_u32 v10, v0, s4, 12
	v_ashrrev_i32_e32 v11, 31, v10
	v_lshlrev_b64 v[10:11], 12, v[10:11]
	v_lshl_add_u64 v[10:11], v[4:5], 0, v[10:11]
	global_load_dword v230, v[10:11], off nt
.Lcv17_3_2274:
	s_or_b64 exec, exec, s[16:17]
	s_and_saveexec_b64 s[16:17], vcc
	s_cbranch_execz .Lcv17_3_end
	v_add3_u32 v10, v0, s4, 14
	v_ashrrev_i32_e32 v11, 31, v10
	v_lshlrev_b64 v[10:11], 12, v[10:11]
	v_lshl_add_u64 v[10:11], v[4:5], 0, v[10:11]
	global_load_dword v231, v[10:11], off nt
.Lcv17_3_end:
	s_or_b64 exec, exec, s[16:17]
	s_add_i32 s4, s4, 16
	s_waitcnt vmcnt(0)
	ds_write_b32 v8, v200
	ds_write_b32 v8, v201 offset:264
	ds_write_b32 v8, v202 offset:528
	ds_write_b32 v8, v203 offset:792
	ds_write_b32 v8, v204 offset:1056
	ds_write_b32 v8, v205 offset:1320
	ds_write_b32 v8, v206 offset:1584
	ds_write_b32 v8, v207 offset:1848
	ds_write_b32 v8, v208 offset:2112
	ds_write_b32 v8, v209 offset:2376
	ds_write_b32 v8, v210 offset:2640
	ds_write_b32 v8, v211 offset:2904
	ds_write_b32 v8, v212 offset:3168
	ds_write_b32 v8, v213 offset:3432
	ds_write_b32 v8, v214 offset:3696
	ds_write_b32 v8, v215 offset:3960
	ds_write_b32 v8, v216 offset:4224
	ds_write_b32 v8, v217 offset:4488
	ds_write_b32 v8, v218 offset:4752
	ds_write_b32 v8, v219 offset:5016
	ds_write_b32 v8, v220 offset:5280
	ds_write_b32 v8, v221 offset:5544
	ds_write_b32 v8, v222 offset:5808
	ds_write_b32 v8, v223 offset:6072
	ds_write_b32 v8, v224 offset:6336
	ds_write_b32 v8, v225 offset:6600
	ds_write_b32 v8, v226 offset:6864
	ds_write_b32 v8, v227 offset:7128
	ds_write_b32 v8, v228 offset:7392
	ds_write_b32 v8, v229 offset:7656
	ds_write_b32 v8, v230 offset:7920
	ds_write_b32 v8, v231 offset:8184
	s_branch .LBB0_2257

.LBB0_3543:
	v_mov_b32_e32 v200, 0
	v_mov_b32_e32 v201, 0
	v_mov_b32_e32 v202, 0
	v_mov_b32_e32 v203, 0
	v_mov_b32_e32 v204, 0
	v_mov_b32_e32 v205, 0
	v_mov_b32_e32 v206, 0
	v_mov_b32_e32 v207, 0
	v_mov_b32_e32 v208, 0
	v_mov_b32_e32 v209, 0
	v_mov_b32_e32 v210, 0
	v_mov_b32_e32 v211, 0
	v_mov_b32_e32 v212, 0
	v_mov_b32_e32 v213, 0
	v_mov_b32_e32 v214, 0
	v_mov_b32_e32 v215, 0
	v_mov_b32_e32 v216, 0
	v_mov_b32_e32 v217, 0
	v_mov_b32_e32 v218, 0
	v_mov_b32_e32 v219, 0
	v_mov_b32_e32 v220, 0
	v_mov_b32_e32 v221, 0
	v_mov_b32_e32 v222, 0
	v_mov_b32_e32 v223, 0
	v_mov_b32_e32 v224, 0
	v_mov_b32_e32 v225, 0
	v_mov_b32_e32 v226, 0
	v_mov_b32_e32 v227, 0
	v_mov_b32_e32 v228, 0
	v_mov_b32_e32 v229, 0
	v_mov_b32_e32 v230, 0
	v_mov_b32_e32 v231, 0
	s_and_saveexec_b64 s[20:21], vcc
	s_cbranch_execz .Lcv18_0_3545
	v_add_u32_e32 v10, s7, v0
	v_mad_i64_i32 v[10:11], s[8:9], v10, s4, v[4:5]
	global_load_dword v200, v[10:11], off nt

.Lcv18_0_end:
	s_or_b64 exec, exec, s[20:21]
	s_add_i32 s7, s7, 16
	s_and_saveexec_b64 s[20:21], vcc
	s_cbranch_execz .Lcv18_1_3545
	v_add_u32_e32 v10, s7, v0
	v_mad_i64_i32 v[10:11], s[8:9], v10, s4, v[4:5]
	global_load_dword v208, v[10:11], off nt
.Lcv18_1_3545:
	s_or_b64 exec, exec, s[20:21]
	s_and_saveexec_b64 s[20:21], vcc
	s_cbranch_execz .Lcv18_1_3547
	v_add3_u32 v9, v0, s7, 2
	v_mad_i64_i32 v[10:11], s[8:9], v9, s4, v[4:5]
	global_load_dword v209, v[10:11], off nt
.Lcv18_1_3547:
	s_or_b64 exec, exec, s[20:21]
	s_and_saveexec_b64 s[20:21], vcc
	s_cbranch_execz .Lcv18_1_3549
	v_add3_u32 v10, v0, s7, 4
	v_mad_i64_i32 v[10:11], s[8:9], v10, s4, v[4:5]
	global_load_dword v210, v[10:11], off nt
.Lcv18_1_3549:
	s_or_b64 exec, exec, s[20:21]
	s_and_saveexec_b64 s[20:21], vcc
	s_cbranch_execz .Lcv18_1_3551
	v_add3_u32 v9, v0, s7, 6
	v_mad_i64_i32 v[10:11], s[8:9], v9, s4, v[4:5]
	global_load_dword v211, v[10:11], off nt
.Lcv18_1_3551:
	s_or_b64 exec, exec, s[20:21]
	s_and_saveexec_b64 s[20:21], vcc
	s_cbranch_execz .Lcv18_1_3553
	v_add3_u32 v10, v0, s7, 8
	v_mad_i64_i32 v[10:11], s[8:9], v10, s4, v[4:5]
	global_load_dword v212, v[10:11], off nt
.Lcv18_1_3553:
	s_or_b64 exec, exec, s[20:21]
	s_and_saveexec_b64 s[20:21], vcc
	s_cbranch_execz .Lcv18_1_3555
	v_add3_u32 v9, v0, s7, 10
	v_mad_i64_i32 v[10:11], s[8:9], v9, s4, v[4:5]
	global_load_dword v213, v[10:11], off nt
.Lcv18_1_3555:
	s_or_b64 exec, exec, s[20:21]
	s_and_saveexec_b64 s[20:21], vcc
	s_cbranch_execz .Lcv18_1_3557
	v_add3_u32 v10, v0, s7, 12
	v_mad_i64_i32 v[10:11], s[8:9], v10, s4, v[4:5]
	global_load_dword v214, v[10:11], off nt
.Lcv18_1_3557:
	s_or_b64 exec, exec, s[20:21]
	s_and_saveexec_b64 s[20:21], vcc
	s_cbranch_execz .Lcv18_1_end
	v_add3_u32 v9, v0, s7, 14
	v_mad_i64_i32 v[10:11], s[8:9], v9, s4, v[4:5]
	global_load_dword v215, v[10:11], off nt
.Lcv18_1_end:
	s_or_b64 exec, exec, s[20:21]
	s_add_i32 s7, s7, 16
	s_and_saveexec_b64 s[20:21], vcc
	s_cbranch_execz .Lcv18_2_3545
	v_add_u32_e32 v10, s7, v0
	v_mad_i64_i32 v[10:11], s[8:9], v10, s4, v[4:5]
	global_load_dword v216, v[10:11], off nt
.Lcv18_2_3545:
	s_or_b64 exec, exec, s[20:21]
	s_and_saveexec_b64 s[20:21], vcc
	s_cbranch_execz .Lcv18_2_3547
	v_add3_u32 v9, v0, s7, 2
	v_mad_i64_i32 v[10:11], s[8:9], v9, s4, v[4:5]
	global_load_dword v217, v[10:11], off nt
.Lcv18_2_3547:
	s_or_b64 exec, exec, s[20:21]
	s_and_saveexec_b64 s[20:21], vcc
	s_cbranch_execz .Lcv18_2_3549
	v_add3_u32 v10, v0, s7, 4
	v_mad_i64_i32 v[10:11], s[8:9], v10, s4, v[4:5]
	global_load_dword v218, v[10:11], off nt
.Lcv18_2_3549:
	s_or_b64 exec, exec, s[20:21]
	s_and_saveexec_b64 s[20:21], vcc
	s_cbranch_execz .Lcv18_2_3551
	v_add3_u32 v9, v0, s7, 6
	v_mad_i64_i32 v[10:11], s[8:9], v9, s4, v[4:5]
	global_load_dword v219, v[10:11], off nt
.Lcv18_2_3551:
	s_or_b64 exec, exec, s[20:21]
	s_and_saveexec_b64 s[20:21], vcc
	s_cbranch_execz .Lcv18_2_3553
	v_add3_u32 v10, v0, s7, 8
	v_mad_i64_i32 v[10:11], s[8:9], v10, s4, v[4:5]
	global_load_dword v220, v[10:11], off nt
.Lcv18_2_3553:
	s_or_b64 exec, exec, s[20:21]
	s_and_saveexec_b64 s[20:21], vcc
	s_cbranch_execz .Lcv18_2_3555
	v_add3_u32 v9, v0, s7, 10
	v_mad_i64_i32 v[10:11], s[8:9], v9, s4, v[4:5]
	global_load_dword v221, v[10:11], off nt
.Lcv18_2_3555:
	s_or_b64 exec, exec, s[20:21]
	s_and_saveexec_b64 s[20:21], vcc
	s_cbranch_execz .Lcv18_2_3557
	v_add3_u32 v10, v0, s7, 12
	v_mad_i64_i32 v[10:11], s[8:9], v10, s4, v[4:5]
	global_load_dword v222, v[10:11], off nt
.Lcv18_2_3557:
	s_or_b64 exec, exec, s[20:21]
	s_and_saveexec_b64 s[20:21], vcc
	s_cbranch_execz .Lcv18_2_end
	v_add3_u32 v9, v0, s7, 14
	v_mad_i64_i32 v[10:11], s[8:9], v9, s4, v[4:5]
	global_load_dword v223, v[10:11], off nt
.Lcv18_2_end:
	s_or_b64 exec, exec, s[20:21]
	s_add_i32 s7, s7, 16
	s_and_saveexec_b64 s[20:21], vcc
	s_cbranch_execz .Lcv18_3_3545
	v_add_u32_e32 v10, s7, v0
	v_mad_i64_i32 v[10:11], s[8:9], v10, s4, v[4:5]
	global_load_dword v224, v[10:11], off nt
.Lcv18_3_3545:
	s_or_b64 exec, exec, s[20:21]
	s_and_saveexec_b64 s[20:21], vcc
	s_cbranch_execz .Lcv18_3_3547
	v_add3_u32 v9, v0, s7, 2
	v_mad_i64_i32 v[10:11], s[8:9], v9, s4, v[4:5]
	global_load_dword v225, v[10:11], off nt
.Lcv18_3_3547:
	s_or_b64 exec, exec, s[20:21]
	s_and_saveexec_b64 s[20:21], vcc
	s_cbranch_execz .Lcv18_3_3549
	v_add3_u32 v10, v0, s7, 4
	v_mad_i64_i32 v[10:11], s[8:9], v10, s4, v[4:5]
	global_load_dword v226, v[10:11], off nt
.Lcv18_3_3549:
	s_or_b64 exec, exec, s[20:21]
	s_and_saveexec_b64 s[20:21], vcc
	s_cbranch_execz .Lcv18_3_3551
	v_add3_u32 v9, v0, s7, 6
	v_mad_i64_i32 v[10:11], s[8:9], v9, s4, v[4:5]
	global_load_dword v227, v[10:11], off nt
.Lcv18_3_3551:
	s_or_b64 exec, exec, s[20:21]
	s_and_saveexec_b64 s[20:21], vcc
	s_cbranch_execz .Lcv18_3_3553
	v_add3_u32 v10, v0, s7, 8
	v_mad_i64_i32 v[10:11], s[8:9], v10, s4, v[4:5]
	global_load_dword v228, v[10:11], off nt
.Lcv18_3_3553:
	s_or_b64 exec, exec, s[20:21]
	s_and_saveexec_b64 s[20:21], vcc
	s_cbranch_execz .Lcv18_3_3555
	v_add3_u32 v9, v0, s7, 10
	v_mad_i64_i32 v[10:11], s[8:9], v9, s4, v[4:5]
	global_load_dword v229, v[10:11], off nt
.Lcv18_3_3555:
	s_or_b64 exec, exec, s[20:21]
	s_and_saveexec_b64 s[20:21], vcc
	s_cbranch_execz .Lcv18_3_3557
	v_add3_u32 v10, v0, s7, 12
	v_mad_i64_i32 v[10:11], s[8:9], v10, s4, v[4:5]
	global_load_dword v230, v[10:11], off nt
.Lcv18_3_3557:
	s_or_b64 exec, exec, s[20:21]
	s_and_saveexec_b64 s[20:21], vcc
	s_cbranch_execz .Lcv18_3_end
	v_add3_u32 v9, v0, s7, 14
	v_mad_i64_i32 v[10:11], s[8:9], v9, s4, v[4:5]
	global_load_dword v231, v[10:11], off nt
.Lcv18_3_end:
	s_or_b64 exec, exec, s[20:21]
	s_add_i32 s7, s7, 16
	s_waitcnt vmcnt(0)
	ds_write_b32 v8, v200
	ds_write_b32 v8, v201 offset:264
	ds_write_b32 v8, v202 offset:528
	ds_write_b32 v8, v203 offset:792
	ds_write_b32 v8, v204 offset:1056
	ds_write_b32 v8, v205 offset:1320
	ds_write_b32 v8, v206 offset:1584
	ds_write_b32 v8, v207 offset:1848
	ds_write_b32 v8, v208 offset:2112
	ds_write_b32 v8, v209 offset:2376
	ds_write_b32 v8, v210 offset:2640
	ds_write_b32 v8, v211 offset:2904
	ds_write_b32 v8, v212 offset:3168
	ds_write_b32 v8, v213 offset:3432
	ds_write_b32 v8, v214 offset:3696
	ds_write_b32 v8, v215 offset:3960
	ds_write_b32 v8, v216 offset:4224
	ds_write_b32 v8, v217 offset:4488
	ds_write_b32 v8, v218 offset:4752
	ds_write_b32 v8, v219 offset:5016
	ds_write_b32 v8, v220 offset:5280
	ds_write_b32 v8, v221 offset:5544
	ds_write_b32 v8, v222 offset:5808
	ds_write_b32 v8, v223 offset:6072
	ds_write_b32 v8, v224 offset:6336
	ds_write_b32 v8, v225 offset:6600
	ds_write_b32 v8, v226 offset:6864
	ds_write_b32 v8, v227 offset:7128
	ds_write_b32 v8, v228 offset:7392
	ds_write_b32 v8, v229 offset:7656
	ds_write_b32 v8, v230 offset:7920
	ds_write_b32 v8, v231 offset:8184
	s_branch .LBB0_3538
